# weight-conversion (f32->bf16 transpose) stores issued without the nt hint; rest identical to the best version
# speedup vs baseline: 1.0021x; 1.0021x over previous
.LBB0_458:
	s_or_b64 exec, exec, s[4:5]
	s_waitcnt vmcnt(0)
	v_cvt_pk_bf16_f32 v156, v102, v98
	v_cvt_pk_bf16_f32 v157, v110, v106
	v_cvt_pk_bf16_f32 v158, v118, v114
	v_cvt_pk_bf16_f32 v159, v126, v122
	ds_write_b128 v136, v[156:159]
	v_cvt_pk_bf16_f32 v156, v103, v99
	v_cvt_pk_bf16_f32 v157, v111, v107
	v_cvt_pk_bf16_f32 v158, v119, v115
	v_cvt_pk_bf16_f32 v159, v127, v123
	ds_write_b128 v136, v[156:159] offset:4096
	v_cvt_pk_bf16_f32 v156, v104, v100
	v_cvt_pk_bf16_f32 v98, v105, v101
	v_cvt_pk_bf16_f32 v99, v113, v109
	v_cvt_pk_bf16_f32 v100, v121, v117
	v_cvt_pk_bf16_f32 v101, v129, v125
	ds_write_b128 v136, v[98:101] offset:12288
	v_cvt_pk_bf16_f32 v98, v70, v66
	v_cvt_pk_bf16_f32 v99, v78, v74
	v_cvt_pk_bf16_f32 v100, v86, v82
	v_cvt_pk_bf16_f32 v101, v94, v90
	ds_write_b128 v137, v[98:101]
	v_cvt_pk_bf16_f32 v98, v71, v67
	v_cvt_pk_bf16_f32 v99, v79, v75
	v_cvt_pk_bf16_f32 v100, v87, v83
	v_cvt_pk_bf16_f32 v101, v95, v91
	ds_write_b128 v137, v[98:101] offset:4096
	v_cvt_pk_bf16_f32 v98, v72, v68
	v_cvt_pk_bf16_f32 v66, v73, v69
	v_cvt_pk_bf16_f32 v67, v81, v77
	v_cvt_pk_bf16_f32 v68, v89, v85
	v_cvt_pk_bf16_f32 v69, v97, v93
	ds_write_b128 v137, v[66:69] offset:12288
	v_cvt_pk_bf16_f32 v66, v38, v34
	v_cvt_pk_bf16_f32 v67, v46, v42
	v_cvt_pk_bf16_f32 v68, v54, v50
	v_cvt_pk_bf16_f32 v69, v62, v58
	ds_write_b128 v138, v[66:69]
	v_cvt_pk_bf16_f32 v66, v39, v35
	v_cvt_pk_bf16_f32 v67, v47, v43
	v_cvt_pk_bf16_f32 v68, v55, v51
	v_cvt_pk_bf16_f32 v69, v63, v59
	ds_write_b128 v138, v[66:69] offset:4096
	v_cvt_pk_bf16_f32 v66, v40, v36
	v_cvt_pk_bf16_f32 v34, v41, v37
	v_cvt_pk_bf16_f32 v35, v49, v45
	v_cvt_pk_bf16_f32 v36, v57, v53
	v_cvt_pk_bf16_f32 v37, v65, v61
	ds_write_b128 v138, v[34:37] offset:12288
	v_cvt_pk_bf16_f32 v34, v6, v2
	v_cvt_pk_bf16_f32 v35, v14, v10
	v_cvt_pk_bf16_f32 v36, v22, v18
	v_cvt_pk_bf16_f32 v37, v30, v26
	ds_write_b128 v139, v[34:37]
	v_cvt_pk_bf16_f32 v34, v7, v3
	v_cvt_pk_bf16_f32 v35, v15, v11
	v_cvt_pk_bf16_f32 v36, v23, v19
	v_cvt_pk_bf16_f32 v37, v31, v27
	v_cvt_pk_bf16_f32 v157, v112, v108
	v_cvt_pk_bf16_f32 v158, v120, v116
	v_cvt_pk_bf16_f32 v159, v128, v124
	v_cvt_pk_bf16_f32 v99, v80, v76
	v_cvt_pk_bf16_f32 v100, v88, v84
	v_cvt_pk_bf16_f32 v101, v96, v92
	v_cvt_pk_bf16_f32 v67, v48, v44
	v_cvt_pk_bf16_f32 v68, v56, v52
	v_cvt_pk_bf16_f32 v69, v64, v60
	ds_write_b128 v139, v[34:37] offset:4096
	v_cvt_pk_bf16_f32 v34, v8, v4
	v_cvt_pk_bf16_f32 v35, v16, v12
	v_cvt_pk_bf16_f32 v36, v24, v20
	v_cvt_pk_bf16_f32 v37, v32, v28
	v_cvt_pk_bf16_f32 v2, v9, v5
	v_cvt_pk_bf16_f32 v3, v17, v13
	v_cvt_pk_bf16_f32 v4, v25, v21
	v_cvt_pk_bf16_f32 v5, v33, v29
	s_sub_i32 s4, 0, s15
	ds_write_b128 v136, v[156:159] offset:8192
	ds_write_b128 v137, v[98:101] offset:8192
	ds_write_b128 v138, v[66:69] offset:8192
	ds_write_b128 v139, v[34:37] offset:8192
	ds_write_b128 v139, v[2:5] offset:12288
	ds_read_b128 v[2:5], v140
	s_add_i32 s4, s4, s28
	v_add_u32_e32 v12, s4, v135
	s_ashr_i32 s15, s14, 31
	v_ashrrev_i32_e32 v13, 31, v12
	v_lshl_add_u64 v[10:11], s[14:15], 1, v[132:133]
	v_lshlrev_b64 v[6:7], 12, v[12:13]
	v_lshl_add_u64 v[14:15], v[10:11], 0, v[6:7]
	ds_read_b128 v[6:9], v141
	s_waitcnt lgkmcnt(0)
	global_store_dwordx4 v[14:15], v[2:5], off
	s_add_i32 s25, s25, s18
	s_add_i32 s28, s28, s29
	v_add_u32_e32 v2, 8, v12
	v_ashrrev_i32_e32 v3, 31, v2
	v_lshlrev_b64 v[2:3], 12, v[2:3]
	v_lshl_add_u64 v[2:3], v[10:11], 0, v[2:3]
	global_store_dwordx4 v[2:3], v[6:9], off
	ds_read_b128 v[2:5], v142
	s_cmpk_lt_i32 s25, 0x200
	v_add_u32_e32 v6, 16, v12
	v_ashrrev_i32_e32 v7, 31, v6
	v_lshlrev_b64 v[6:7], 12, v[6:7]
	v_lshl_add_u64 v[14:15], v[10:11], 0, v[6:7]
	ds_read_b128 v[6:9], v143
	s_waitcnt lgkmcnt(1)
	global_store_dwordx4 v[14:15], v[2:5], off
	s_nop 1
	v_add_u32_e32 v2, 24, v12
	v_ashrrev_i32_e32 v3, 31, v2
	v_lshlrev_b64 v[2:3], 12, v[2:3]
	v_lshl_add_u64 v[2:3], v[10:11], 0, v[2:3]
	s_waitcnt lgkmcnt(0)
	global_store_dwordx4 v[2:3], v[6:9], off
	ds_read_b128 v[2:5], v144
	s_nop 0
	v_add_u32_e32 v6, 32, v12
	v_ashrrev_i32_e32 v7, 31, v6
	v_lshlrev_b64 v[6:7], 12, v[6:7]
	v_lshl_add_u64 v[14:15], v[10:11], 0, v[6:7]
	ds_read_b128 v[6:9], v145
	s_waitcnt lgkmcnt(1)
	global_store_dwordx4 v[14:15], v[2:5], off
	s_nop 1
	v_add_u32_e32 v2, 40, v12
	v_ashrrev_i32_e32 v3, 31, v2
	v_lshlrev_b64 v[2:3], 12, v[2:3]
	v_lshl_add_u64 v[2:3], v[10:11], 0, v[2:3]
	s_waitcnt lgkmcnt(0)
	global_store_dwordx4 v[2:3], v[6:9], off
	ds_read_b128 v[2:5], v146
	s_nop 0
	v_add_u32_e32 v6, 48, v12
	v_ashrrev_i32_e32 v7, 31, v6
	v_lshlrev_b64 v[6:7], 12, v[6:7]
	v_lshl_add_u64 v[14:15], v[10:11], 0, v[6:7]
	ds_read_b128 v[6:9], v147
	s_waitcnt lgkmcnt(1)
	global_store_dwordx4 v[14:15], v[2:5], off
	s_nop 1
	v_add_u32_e32 v2, 56, v12
	v_ashrrev_i32_e32 v3, 31, v2
	v_lshlrev_b64 v[2:3], 12, v[2:3]
	v_lshl_add_u64 v[2:3], v[10:11], 0, v[2:3]
	s_waitcnt lgkmcnt(0)
	global_store_dwordx4 v[2:3], v[6:9], off
	ds_read_b128 v[2:5], v148
	s_nop 0
	v_add_u32_e32 v6, 64, v12
	v_ashrrev_i32_e32 v7, 31, v6
	v_lshlrev_b64 v[6:7], 12, v[6:7]
	v_lshl_add_u64 v[14:15], v[10:11], 0, v[6:7]
	ds_read_b128 v[6:9], v149
	s_waitcnt lgkmcnt(1)
	global_store_dwordx4 v[14:15], v[2:5], off
	s_nop 1
	v_add_u32_e32 v2, 0x48, v12
	v_ashrrev_i32_e32 v3, 31, v2
	v_lshlrev_b64 v[2:3], 12, v[2:3]
	v_lshl_add_u64 v[2:3], v[10:11], 0, v[2:3]
	s_waitcnt lgkmcnt(0)
	global_store_dwordx4 v[2:3], v[6:9], off
	ds_read_b128 v[2:5], v150
	s_nop 0
	v_add_u32_e32 v6, 0x50, v12
	v_ashrrev_i32_e32 v7, 31, v6
	v_lshlrev_b64 v[6:7], 12, v[6:7]
	v_lshl_add_u64 v[14:15], v[10:11], 0, v[6:7]
	ds_read_b128 v[6:9], v151
	s_waitcnt lgkmcnt(1)
	global_store_dwordx4 v[14:15], v[2:5], off
	s_nop 1
	v_add_u32_e32 v2, 0x58, v12
	v_ashrrev_i32_e32 v3, 31, v2
	v_lshlrev_b64 v[2:3], 12, v[2:3]
	v_lshl_add_u64 v[2:3], v[10:11], 0, v[2:3]
	s_waitcnt lgkmcnt(0)
	global_store_dwordx4 v[2:3], v[6:9], off
	ds_read_b128 v[2:5], v152
	s_nop 0
	v_add_u32_e32 v6, 0x60, v12
	v_ashrrev_i32_e32 v7, 31, v6
	v_lshlrev_b64 v[6:7], 12, v[6:7]
	v_lshl_add_u64 v[14:15], v[10:11], 0, v[6:7]
	ds_read_b128 v[6:9], v153
	s_waitcnt lgkmcnt(1)
	global_store_dwordx4 v[14:15], v[2:5], off
	s_nop 1
	v_add_u32_e32 v2, 0x68, v12
	v_ashrrev_i32_e32 v3, 31, v2
	v_lshlrev_b64 v[2:3], 12, v[2:3]
	v_lshl_add_u64 v[2:3], v[10:11], 0, v[2:3]
	s_waitcnt lgkmcnt(0)
	global_store_dwordx4 v[2:3], v[6:9], off
	ds_read_b128 v[2:5], v154
	s_nop 0
	v_add_u32_e32 v6, 0x70, v12
	v_ashrrev_i32_e32 v7, 31, v6
	v_lshlrev_b64 v[6:7], 12, v[6:7]
	v_lshl_add_u64 v[14:15], v[10:11], 0, v[6:7]
	ds_read_b128 v[6:9], v155
	s_waitcnt lgkmcnt(1)
	global_store_dwordx4 v[14:15], v[2:5], off
	s_nop 1
	v_add_u32_e32 v2, 0x78, v12
	v_ashrrev_i32_e32 v3, 31, v2
	v_lshlrev_b64 v[2:3], 12, v[2:3]
	v_lshl_add_u64 v[2:3], v[10:11], 0, v[2:3]
	s_waitcnt lgkmcnt(0)
	global_store_dwordx4 v[2:3], v[6:9], off
	s_cbranch_scc0 .LBB0_454

.LBB0_466:
	s_or_b64 exec, exec, s[4:5]
	v_cvt_pk_bf16_f32 v64, v174, v172
	v_cvt_pk_bf16_f32 v65, v170, v168
	v_cvt_pk_bf16_f32 v66, v166, v164
	v_cvt_pk_bf16_f32 v67, v162, v160
	ds_write_b128 v178, v[64:67]
	v_cvt_pk_bf16_f32 v64, v175, v173
	v_cvt_pk_bf16_f32 v65, v171, v169
	v_cvt_pk_bf16_f32 v66, v167, v165
	v_cvt_pk_bf16_f32 v67, v163, v161
	ds_write_b128 v178, v[64:67] offset:4096
	v_cvt_pk_bf16_f32 v64, v158, v156
	v_cvt_pk_bf16_f32 v65, v154, v152
	v_cvt_pk_bf16_f32 v66, v150, v148
	v_cvt_pk_bf16_f32 v67, v146, v144
	ds_write_b128 v178, v[64:67] offset:8192
	v_cvt_pk_bf16_f32 v64, v159, v157
	v_cvt_pk_bf16_f32 v65, v155, v153
	v_cvt_pk_bf16_f32 v66, v151, v149
	v_cvt_pk_bf16_f32 v67, v147, v145
	ds_write_b128 v178, v[64:67] offset:12288
	v_cvt_pk_bf16_f32 v64, v142, v140
	v_cvt_pk_bf16_f32 v65, v138, v136
	v_cvt_pk_bf16_f32 v66, v116, v114
	v_cvt_pk_bf16_f32 v67, v112, v110
	ds_write_b128 v179, v[64:67]
	v_cvt_pk_bf16_f32 v64, v143, v141
	v_cvt_pk_bf16_f32 v65, v139, v137
	v_cvt_pk_bf16_f32 v66, v117, v115
	v_cvt_pk_bf16_f32 v67, v113, v111
	ds_write_b128 v179, v[64:67] offset:4096
	v_cvt_pk_bf16_f32 v64, v134, v132
	v_cvt_pk_bf16_f32 v65, v108, v106
	v_cvt_pk_bf16_f32 v66, v104, v102
	v_cvt_pk_bf16_f32 v67, v100, v98
	ds_write_b128 v179, v[64:67] offset:8192
	v_cvt_pk_bf16_f32 v64, v135, v133
	v_cvt_pk_bf16_f32 v65, v109, v107
	v_cvt_pk_bf16_f32 v66, v105, v103
	v_cvt_pk_bf16_f32 v67, v101, v99
	ds_write_b128 v179, v[64:67] offset:12288
	v_cvt_pk_bf16_f32 v64, v118, v62
	v_cvt_pk_bf16_f32 v65, v58, v54
	v_cvt_pk_bf16_f32 v66, v50, v46
	v_cvt_pk_bf16_f32 v67, v38, v34
	ds_write_b128 v185, v[64:67]
	v_cvt_pk_bf16_f32 v62, v119, v63
	v_cvt_pk_bf16_f32 v63, v59, v55
	v_cvt_pk_bf16_f32 v64, v51, v47
	v_cvt_pk_bf16_f32 v65, v39, v35
	ds_write_b128 v185, v[62:65] offset:4096
	v_cvt_pk_bf16_f32 v65, v40, v36
	v_cvt_pk_bf16_f32 v34, v45, v43
	v_cvt_pk_bf16_f32 v35, v61, v57
	v_cvt_pk_bf16_f32 v36, v53, v49
	v_cvt_pk_bf16_f32 v37, v41, v37
	ds_write_b128 v185, v[34:37] offset:12288
	v_cvt_pk_bf16_f32 v34, v30, v26
	v_cvt_pk_bf16_f32 v35, v22, v18
	v_cvt_pk_bf16_f32 v36, v14, v10
	v_cvt_pk_bf16_f32 v37, v6, v2
	ds_write_b128 v190, v[34:37]
	v_cvt_pk_bf16_f32 v34, v31, v27
	v_cvt_pk_bf16_f32 v35, v23, v19
	v_cvt_pk_bf16_f32 v36, v15, v11
	v_cvt_pk_bf16_f32 v37, v7, v3
	v_cvt_pk_bf16_f32 v62, v44, v42
	v_cvt_pk_bf16_f32 v63, v60, v56
	v_cvt_pk_bf16_f32 v64, v52, v48
	ds_write_b128 v190, v[34:37] offset:4096
	v_cvt_pk_bf16_f32 v34, v32, v28
	v_cvt_pk_bf16_f32 v35, v24, v20
	v_cvt_pk_bf16_f32 v36, v16, v12
	v_cvt_pk_bf16_f32 v37, v8, v4
	v_cvt_pk_bf16_f32 v2, v33, v29
	v_cvt_pk_bf16_f32 v3, v25, v21
	v_cvt_pk_bf16_f32 v4, v17, v13
	v_cvt_pk_bf16_f32 v5, v9, v5
	s_sub_i32 s2, 0, s2
	ds_write_b128 v185, v[62:65] offset:8192
	ds_write_b128 v190, v[34:37] offset:8192
	ds_write_b128 v190, v[2:5] offset:12288
	ds_read_b128 v[2:5], v191
	s_add_i32 s2, s2, s28
	v_add_u32_e32 v12, s2, v177
	v_ashrrev_i32_e32 v13, 31, v12
	v_lshl_add_u64 v[10:11], s[14:15], 1, v[130:131]
	v_lshlrev_b64 v[6:7], 12, v[12:13]
	v_lshl_add_u64 v[14:15], v[10:11], 0, v[6:7]
	ds_read_b128 v[6:9], v192
	s_waitcnt lgkmcnt(0)
	global_store_dwordx4 v[14:15], v[2:5], off
	s_add_i32 s45, s45, s18
	s_add_i32 s28, s28, s29
	v_add_u32_e32 v2, 8, v12
	v_ashrrev_i32_e32 v3, 31, v2
	v_lshlrev_b64 v[2:3], 12, v[2:3]
	v_lshl_add_u64 v[2:3], v[10:11], 0, v[2:3]
	global_store_dwordx4 v[2:3], v[6:9], off
	ds_read_b128 v[2:5], v193
	s_cmpk_lt_i32 s45, 0x800
	v_add_u32_e32 v6, 16, v12
	v_ashrrev_i32_e32 v7, 31, v6
	v_lshlrev_b64 v[6:7], 12, v[6:7]
	v_lshl_add_u64 v[14:15], v[10:11], 0, v[6:7]
	ds_read_b128 v[6:9], v194
	s_waitcnt lgkmcnt(1)
	global_store_dwordx4 v[14:15], v[2:5], off
	s_nop 1
	v_add_u32_e32 v2, 24, v12
	v_ashrrev_i32_e32 v3, 31, v2
	v_lshlrev_b64 v[2:3], 12, v[2:3]
	v_lshl_add_u64 v[2:3], v[10:11], 0, v[2:3]
	s_waitcnt lgkmcnt(0)
	global_store_dwordx4 v[2:3], v[6:9], off
	ds_read_b128 v[2:5], v195
	s_nop 0
	v_add_u32_e32 v6, 32, v12
	v_ashrrev_i32_e32 v7, 31, v6
	v_lshlrev_b64 v[6:7], 12, v[6:7]
	v_lshl_add_u64 v[14:15], v[10:11], 0, v[6:7]
	ds_read_b128 v[6:9], v196
	s_waitcnt lgkmcnt(1)
	global_store_dwordx4 v[14:15], v[2:5], off
	s_nop 1
	v_add_u32_e32 v2, 40, v12
	v_ashrrev_i32_e32 v3, 31, v2
	v_lshlrev_b64 v[2:3], 12, v[2:3]
	v_lshl_add_u64 v[2:3], v[10:11], 0, v[2:3]
	s_waitcnt lgkmcnt(0)
	global_store_dwordx4 v[2:3], v[6:9], off
	ds_read_b128 v[2:5], v197
	s_nop 0
	v_add_u32_e32 v6, 48, v12
	v_ashrrev_i32_e32 v7, 31, v6
	v_lshlrev_b64 v[6:7], 12, v[6:7]
	v_lshl_add_u64 v[14:15], v[10:11], 0, v[6:7]
	ds_read_b128 v[6:9], v198
	s_waitcnt lgkmcnt(1)
	global_store_dwordx4 v[14:15], v[2:5], off
	s_nop 1
	v_add_u32_e32 v2, 56, v12
	v_ashrrev_i32_e32 v3, 31, v2
	v_lshlrev_b64 v[2:3], 12, v[2:3]
	v_lshl_add_u64 v[2:3], v[10:11], 0, v[2:3]
	s_waitcnt lgkmcnt(0)
	global_store_dwordx4 v[2:3], v[6:9], off
	ds_read_b128 v[2:5], v199
	s_nop 0
	v_add_u32_e32 v6, 64, v12
	v_ashrrev_i32_e32 v7, 31, v6
	v_lshlrev_b64 v[6:7], 12, v[6:7]
	v_lshl_add_u64 v[14:15], v[10:11], 0, v[6:7]
	ds_read_b128 v[6:9], v200
	s_waitcnt lgkmcnt(1)
	global_store_dwordx4 v[14:15], v[2:5], off
	s_nop 1
	v_add_u32_e32 v2, 0x48, v12
	v_ashrrev_i32_e32 v3, 31, v2
	v_lshlrev_b64 v[2:3], 12, v[2:3]
	v_lshl_add_u64 v[2:3], v[10:11], 0, v[2:3]
	s_waitcnt lgkmcnt(0)
	global_store_dwordx4 v[2:3], v[6:9], off
	ds_read_b128 v[2:5], v201
	s_nop 0
	v_add_u32_e32 v6, 0x50, v12
	v_ashrrev_i32_e32 v7, 31, v6
	v_lshlrev_b64 v[6:7], 12, v[6:7]
	v_lshl_add_u64 v[14:15], v[10:11], 0, v[6:7]
	ds_read_b128 v[6:9], v202
	s_waitcnt lgkmcnt(1)
	global_store_dwordx4 v[14:15], v[2:5], off
	s_nop 1
	v_add_u32_e32 v2, 0x58, v12
	v_ashrrev_i32_e32 v3, 31, v2
	v_lshlrev_b64 v[2:3], 12, v[2:3]
	v_lshl_add_u64 v[2:3], v[10:11], 0, v[2:3]
	s_waitcnt lgkmcnt(0)
	global_store_dwordx4 v[2:3], v[6:9], off
	ds_read_b128 v[2:5], v203
	s_nop 0
	v_add_u32_e32 v6, 0x60, v12
	v_ashrrev_i32_e32 v7, 31, v6
	v_lshlrev_b64 v[6:7], 12, v[6:7]
	v_lshl_add_u64 v[14:15], v[10:11], 0, v[6:7]
	ds_read_b128 v[6:9], v204
	s_waitcnt lgkmcnt(1)
	global_store_dwordx4 v[14:15], v[2:5], off
	s_nop 1
	v_add_u32_e32 v2, 0x68, v12
	v_ashrrev_i32_e32 v3, 31, v2
	v_lshlrev_b64 v[2:3], 12, v[2:3]
	v_lshl_add_u64 v[2:3], v[10:11], 0, v[2:3]
	s_waitcnt lgkmcnt(0)
	global_store_dwordx4 v[2:3], v[6:9], off
	ds_read_b128 v[2:5], v205
	s_nop 0
	v_add_u32_e32 v6, 0x70, v12
	v_ashrrev_i32_e32 v7, 31, v6
	v_lshlrev_b64 v[6:7], 12, v[6:7]
	v_lshl_add_u64 v[14:15], v[10:11], 0, v[6:7]
	ds_read_b128 v[6:9], v206
	s_waitcnt lgkmcnt(1)
	global_store_dwordx4 v[14:15], v[2:5], off
	s_nop 1
	v_add_u32_e32 v2, 0x78, v12
	v_ashrrev_i32_e32 v3, 31, v2
	v_lshlrev_b64 v[2:3], 12, v[2:3]
	v_lshl_add_u64 v[2:3], v[10:11], 0, v[2:3]
	s_waitcnt lgkmcnt(0)
	global_store_dwordx4 v[2:3], v[6:9], off
	s_cbranch_scc0 .LBB0_469

.LBB0_471:
	s_or_b64 exec, exec, s[4:5]
	s_waitcnt vmcnt(0)
	v_cvt_pk_bf16_f32 v154, v102, v98
	v_cvt_pk_bf16_f32 v155, v110, v106
	v_cvt_pk_bf16_f32 v156, v118, v114
	v_cvt_pk_bf16_f32 v157, v126, v122
	ds_write_b128 v134, v[154:157]
	v_cvt_pk_bf16_f32 v154, v103, v99
	v_cvt_pk_bf16_f32 v155, v111, v107
	v_cvt_pk_bf16_f32 v156, v119, v115
	v_cvt_pk_bf16_f32 v157, v127, v123
	ds_write_b128 v134, v[154:157] offset:4096
	v_cvt_pk_bf16_f32 v154, v104, v100
	v_cvt_pk_bf16_f32 v98, v105, v101
	v_cvt_pk_bf16_f32 v99, v113, v109
	v_cvt_pk_bf16_f32 v100, v121, v117
	v_cvt_pk_bf16_f32 v101, v129, v125
	ds_write_b128 v134, v[98:101] offset:12288
	v_cvt_pk_bf16_f32 v98, v70, v66
	v_cvt_pk_bf16_f32 v99, v78, v74
	v_cvt_pk_bf16_f32 v100, v86, v82
	v_cvt_pk_bf16_f32 v101, v94, v90
	ds_write_b128 v135, v[98:101]
	v_cvt_pk_bf16_f32 v98, v71, v67
	v_cvt_pk_bf16_f32 v99, v79, v75
	v_cvt_pk_bf16_f32 v100, v87, v83
	v_cvt_pk_bf16_f32 v101, v95, v91
	ds_write_b128 v135, v[98:101] offset:4096
	v_cvt_pk_bf16_f32 v98, v72, v68
	v_cvt_pk_bf16_f32 v66, v73, v69
	v_cvt_pk_bf16_f32 v67, v81, v77
	v_cvt_pk_bf16_f32 v68, v89, v85
	v_cvt_pk_bf16_f32 v69, v97, v93
	ds_write_b128 v135, v[66:69] offset:12288
	v_cvt_pk_bf16_f32 v66, v38, v34
	v_cvt_pk_bf16_f32 v67, v46, v42
	v_cvt_pk_bf16_f32 v68, v54, v50
	v_cvt_pk_bf16_f32 v69, v62, v58
	ds_write_b128 v136, v[66:69]
	v_cvt_pk_bf16_f32 v66, v39, v35
	v_cvt_pk_bf16_f32 v67, v47, v43
	v_cvt_pk_bf16_f32 v68, v55, v51
	v_cvt_pk_bf16_f32 v69, v63, v59
	ds_write_b128 v136, v[66:69] offset:4096
	v_cvt_pk_bf16_f32 v66, v40, v36
	v_cvt_pk_bf16_f32 v34, v41, v37
	v_cvt_pk_bf16_f32 v35, v49, v45
	v_cvt_pk_bf16_f32 v36, v57, v53
	v_cvt_pk_bf16_f32 v37, v65, v61
	ds_write_b128 v136, v[34:37] offset:12288
	v_cvt_pk_bf16_f32 v34, v6, v2
	v_cvt_pk_bf16_f32 v35, v14, v10
	v_cvt_pk_bf16_f32 v36, v22, v18
	v_cvt_pk_bf16_f32 v37, v30, v26
	ds_write_b128 v137, v[34:37]
	v_cvt_pk_bf16_f32 v34, v7, v3
	v_cvt_pk_bf16_f32 v35, v15, v11
	v_cvt_pk_bf16_f32 v36, v23, v19
	v_cvt_pk_bf16_f32 v37, v31, v27
	v_cvt_pk_bf16_f32 v155, v112, v108
	v_cvt_pk_bf16_f32 v156, v120, v116
	v_cvt_pk_bf16_f32 v157, v128, v124
	v_cvt_pk_bf16_f32 v99, v80, v76
	v_cvt_pk_bf16_f32 v100, v88, v84
	v_cvt_pk_bf16_f32 v101, v96, v92
	v_cvt_pk_bf16_f32 v67, v48, v44
	v_cvt_pk_bf16_f32 v68, v56, v52
	v_cvt_pk_bf16_f32 v69, v64, v60
	ds_write_b128 v137, v[34:37] offset:4096
	v_cvt_pk_bf16_f32 v34, v8, v4
	v_cvt_pk_bf16_f32 v35, v16, v12
	v_cvt_pk_bf16_f32 v36, v24, v20
	v_cvt_pk_bf16_f32 v37, v32, v28
	v_cvt_pk_bf16_f32 v2, v9, v5
	v_cvt_pk_bf16_f32 v3, v17, v13
	v_cvt_pk_bf16_f32 v4, v25, v21
	v_cvt_pk_bf16_f32 v5, v33, v29
	s_sub_i32 s4, 0, s13
	ds_write_b128 v134, v[154:157] offset:8192
	ds_write_b128 v135, v[98:101] offset:8192
	ds_write_b128 v136, v[66:69] offset:8192
	ds_write_b128 v137, v[34:37] offset:8192
	ds_write_b128 v137, v[2:5] offset:12288
	ds_read_b128 v[2:5], v138
	s_add_i32 s4, s4, s3
	v_add_u32_e32 v12, s4, v133
	s_ashr_i32 s13, s12, 31
	v_ashrrev_i32_e32 v13, 31, v12
	v_lshl_add_u64 v[10:11], s[12:13], 1, v[130:131]
	v_lshlrev_b64 v[6:7], 14, v[12:13]
	v_lshl_add_u64 v[14:15], v[10:11], 0, v[6:7]
	ds_read_b128 v[6:9], v139
	s_waitcnt lgkmcnt(0)
	global_store_dwordx4 v[14:15], v[2:5], off
	s_add_i32 s2, s2, s18
	s_add_i32 s3, s3, s14
	v_add_u32_e32 v2, 8, v12
	v_ashrrev_i32_e32 v3, 31, v2
	v_lshlrev_b64 v[2:3], 14, v[2:3]
	v_lshl_add_u64 v[2:3], v[10:11], 0, v[2:3]
	global_store_dwordx4 v[2:3], v[6:9], off
	ds_read_b128 v[2:5], v140
	s_cmpk_gt_i32 s2, 0x7ff
	v_add_u32_e32 v6, 16, v12
	v_ashrrev_i32_e32 v7, 31, v6
	v_lshlrev_b64 v[6:7], 14, v[6:7]
	v_lshl_add_u64 v[14:15], v[10:11], 0, v[6:7]
	ds_read_b128 v[6:9], v141
	s_waitcnt lgkmcnt(1)
	global_store_dwordx4 v[14:15], v[2:5], off
	s_nop 1
	v_add_u32_e32 v2, 24, v12
	v_ashrrev_i32_e32 v3, 31, v2
	v_lshlrev_b64 v[2:3], 14, v[2:3]
	v_lshl_add_u64 v[2:3], v[10:11], 0, v[2:3]
	s_waitcnt lgkmcnt(0)
	global_store_dwordx4 v[2:3], v[6:9], off
	ds_read_b128 v[2:5], v142
	s_nop 0
	v_add_u32_e32 v6, 32, v12
	v_ashrrev_i32_e32 v7, 31, v6
	v_lshlrev_b64 v[6:7], 14, v[6:7]
	v_lshl_add_u64 v[14:15], v[10:11], 0, v[6:7]
	ds_read_b128 v[6:9], v143
	s_waitcnt lgkmcnt(1)
	global_store_dwordx4 v[14:15], v[2:5], off
	s_nop 1
	v_add_u32_e32 v2, 40, v12
	v_ashrrev_i32_e32 v3, 31, v2
	v_lshlrev_b64 v[2:3], 14, v[2:3]
	v_lshl_add_u64 v[2:3], v[10:11], 0, v[2:3]
	s_waitcnt lgkmcnt(0)
	global_store_dwordx4 v[2:3], v[6:9], off
	ds_read_b128 v[2:5], v144
	s_nop 0
	v_add_u32_e32 v6, 48, v12
	v_ashrrev_i32_e32 v7, 31, v6
	v_lshlrev_b64 v[6:7], 14, v[6:7]
	v_lshl_add_u64 v[14:15], v[10:11], 0, v[6:7]
	ds_read_b128 v[6:9], v145
	s_waitcnt lgkmcnt(1)
	global_store_dwordx4 v[14:15], v[2:5], off
	s_nop 1
	v_add_u32_e32 v2, 56, v12
	v_ashrrev_i32_e32 v3, 31, v2
	v_lshlrev_b64 v[2:3], 14, v[2:3]
	v_lshl_add_u64 v[2:3], v[10:11], 0, v[2:3]
	s_waitcnt lgkmcnt(0)
	global_store_dwordx4 v[2:3], v[6:9], off
	ds_read_b128 v[2:5], v146
	s_nop 0
	v_add_u32_e32 v6, 64, v12
	v_ashrrev_i32_e32 v7, 31, v6
	v_lshlrev_b64 v[6:7], 14, v[6:7]
	v_lshl_add_u64 v[14:15], v[10:11], 0, v[6:7]
	ds_read_b128 v[6:9], v147
	s_waitcnt lgkmcnt(1)
	global_store_dwordx4 v[14:15], v[2:5], off
	s_nop 1
	v_add_u32_e32 v2, 0x48, v12
	v_ashrrev_i32_e32 v3, 31, v2
	v_lshlrev_b64 v[2:3], 14, v[2:3]
	v_lshl_add_u64 v[2:3], v[10:11], 0, v[2:3]
	s_waitcnt lgkmcnt(0)
	global_store_dwordx4 v[2:3], v[6:9], off
	ds_read_b128 v[2:5], v148
	s_nop 0
	v_add_u32_e32 v6, 0x50, v12
	v_ashrrev_i32_e32 v7, 31, v6
	v_lshlrev_b64 v[6:7], 14, v[6:7]
	v_lshl_add_u64 v[14:15], v[10:11], 0, v[6:7]
	ds_read_b128 v[6:9], v149
	s_waitcnt lgkmcnt(1)
	global_store_dwordx4 v[14:15], v[2:5], off
	s_nop 1
	v_add_u32_e32 v2, 0x58, v12
	v_ashrrev_i32_e32 v3, 31, v2
	v_lshlrev_b64 v[2:3], 14, v[2:3]
	v_lshl_add_u64 v[2:3], v[10:11], 0, v[2:3]
	s_waitcnt lgkmcnt(0)
	global_store_dwordx4 v[2:3], v[6:9], off
	ds_read_b128 v[2:5], v150
	s_nop 0
	v_add_u32_e32 v6, 0x60, v12
	v_ashrrev_i32_e32 v7, 31, v6
	v_lshlrev_b64 v[6:7], 14, v[6:7]
	v_lshl_add_u64 v[14:15], v[10:11], 0, v[6:7]
	ds_read_b128 v[6:9], v151
	s_waitcnt lgkmcnt(1)
	global_store_dwordx4 v[14:15], v[2:5], off
	s_nop 1
	v_add_u32_e32 v2, 0x68, v12
	v_ashrrev_i32_e32 v3, 31, v2
	v_lshlrev_b64 v[2:3], 14, v[2:3]
	v_lshl_add_u64 v[2:3], v[10:11], 0, v[2:3]
	s_waitcnt lgkmcnt(0)
	global_store_dwordx4 v[2:3], v[6:9], off
	ds_read_b128 v[2:5], v152
	s_nop 0
	v_add_u32_e32 v6, 0x70, v12
	v_ashrrev_i32_e32 v7, 31, v6
	v_lshlrev_b64 v[6:7], 14, v[6:7]
	v_lshl_add_u64 v[14:15], v[10:11], 0, v[6:7]
	ds_read_b128 v[6:9], v153
	s_waitcnt lgkmcnt(1)
	global_store_dwordx4 v[14:15], v[2:5], off
	s_nop 1
	v_add_u32_e32 v2, 0x78, v12
	v_ashrrev_i32_e32 v3, 31, v2
	v_lshlrev_b64 v[2:3], 14, v[2:3]
	v_lshl_add_u64 v[2:3], v[10:11], 0, v[2:3]
	s_waitcnt lgkmcnt(0)
	global_store_dwordx4 v[2:3], v[6:9], off
	s_cbranch_scc1 .LBB0_474

.LBB0_478:
	s_or_b64 exec, exec, s[4:5]
	s_waitcnt vmcnt(0)
	v_cvt_pk_bf16_f32 v132, v8, v20
	v_cvt_pk_bf16_f32 v133, v32, v40
	v_cvt_pk_bf16_f32 v134, v64, v72
	v_cvt_pk_bf16_f32 v135, v88, v100
	ds_write_b128 v165, v[132:135]
	v_cvt_pk_bf16_f32 v132, v9, v21
	v_cvt_pk_bf16_f32 v133, v33, v41
	v_cvt_pk_bf16_f32 v134, v65, v73
	v_cvt_pk_bf16_f32 v135, v89, v101
	ds_write_b128 v165, v[132:135] offset:4096
	v_cvt_pk_bf16_f32 v132, v10, v22
	v_cvt_pk_bf16_f32 v8, v11, v23
	v_cvt_pk_bf16_f32 v9, v35, v43
	v_cvt_pk_bf16_f32 v10, v67, v75
	v_cvt_pk_bf16_f32 v11, v91, v103
	ds_write_b128 v165, v[8:11] offset:12288
	v_cvt_pk_bf16_f32 v8, v4, v16
	v_cvt_pk_bf16_f32 v2, v5, v17
	v_cvt_pk_bf16_f32 v3, v29, v37
	v_cvt_pk_bf16_f32 v4, v61, v69
	v_cvt_pk_bf16_f32 v5, v85, v97
	ds_write_b128 v166, v[2:5] offset:4096
	v_cvt_pk_bf16_f32 v2, v6, v18
	v_cvt_pk_bf16_f32 v3, v30, v38
	v_cvt_pk_bf16_f32 v4, v62, v70
	v_cvt_pk_bf16_f32 v5, v86, v98
	ds_write_b128 v166, v[2:5] offset:8192
	v_cvt_pk_bf16_f32 v2, v7, v19
	v_cvt_pk_bf16_f32 v3, v31, v39
	v_cvt_pk_bf16_f32 v4, v63, v71
	v_cvt_pk_bf16_f32 v5, v87, v99
	ds_write_b128 v166, v[2:5] offset:12288
	v_cvt_pk_bf16_f32 v2, v12, v24
	v_cvt_pk_bf16_f32 v3, v44, v48
	v_cvt_pk_bf16_f32 v4, v76, v80
	v_cvt_pk_bf16_f32 v5, v108, v112
	ds_write_b128 v167, v[2:5]
	v_cvt_pk_bf16_f32 v2, v13, v25
	v_cvt_pk_bf16_f32 v3, v45, v49
	v_cvt_pk_bf16_f32 v4, v77, v81
	v_cvt_pk_bf16_f32 v5, v109, v113
	ds_write_b128 v167, v[2:5] offset:4096
	v_cvt_pk_bf16_f32 v2, v14, v26
	v_cvt_pk_bf16_f32 v3, v46, v50
	v_cvt_pk_bf16_f32 v4, v78, v82
	v_cvt_pk_bf16_f32 v5, v110, v114
	ds_write_b128 v167, v[2:5] offset:8192
	v_cvt_pk_bf16_f32 v2, v15, v27
	v_cvt_pk_bf16_f32 v3, v47, v51
	v_cvt_pk_bf16_f32 v4, v79, v83
	v_cvt_pk_bf16_f32 v5, v111, v115
	ds_write_b128 v167, v[2:5] offset:12288
	v_cvt_pk_bf16_f32 v2, v52, v56
	v_cvt_pk_bf16_f32 v3, v92, v104
	v_cvt_pk_bf16_f32 v4, v116, v120
	v_cvt_pk_bf16_f32 v5, v124, v128
	ds_write_b128 v168, v[2:5]
	v_cvt_pk_bf16_f32 v2, v53, v57
	v_cvt_pk_bf16_f32 v3, v93, v105
	v_cvt_pk_bf16_f32 v4, v117, v121
	v_cvt_pk_bf16_f32 v5, v125, v129
	ds_write_b128 v168, v[2:5] offset:4096
	v_cvt_pk_bf16_f32 v2, v54, v58
	v_cvt_pk_bf16_f32 v3, v94, v106
	v_cvt_pk_bf16_f32 v4, v118, v122
	v_cvt_pk_bf16_f32 v5, v126, v130
	v_cvt_pk_bf16_f32 v133, v34, v42
	v_cvt_pk_bf16_f32 v134, v66, v74
	v_cvt_pk_bf16_f32 v135, v90, v102
	v_cvt_pk_bf16_f32 v9, v28, v36
	v_cvt_pk_bf16_f32 v10, v60, v68
	v_cvt_pk_bf16_f32 v11, v84, v96
	ds_write_b128 v168, v[2:5] offset:8192
	v_cvt_pk_bf16_f32 v2, v55, v59
	v_cvt_pk_bf16_f32 v3, v95, v107
	v_cvt_pk_bf16_f32 v4, v119, v123
	v_cvt_pk_bf16_f32 v5, v127, v131
	s_sub_i32 s4, 0, s15
	ds_write_b128 v165, v[132:135] offset:8192
	ds_write_b128 v166, v[8:11]
	ds_write_b128 v168, v[2:5] offset:12288
	ds_read_b128 v[2:5], v169
	s_add_i32 s4, s4, s13
	v_add_u32_e32 v12, s4, v164
	s_ashr_i32 s1, s0, 31
	v_ashrrev_i32_e32 v13, 31, v12
	v_lshl_add_u64 v[10:11], s[0:1], 1, v[160:161]
	v_lshlrev_b64 v[6:7], 12, v[12:13]
	v_lshl_add_u64 v[14:15], v[10:11], 0, v[6:7]
	ds_read_b128 v[6:9], v170
	s_waitcnt lgkmcnt(0)
	global_store_dwordx4 v[14:15], v[2:5], off
	s_add_i32 s3, s3, s18
	s_add_i32 s13, s13, s14
	v_add_u32_e32 v2, 8, v12
	v_ashrrev_i32_e32 v3, 31, v2
	v_lshlrev_b64 v[2:3], 12, v[2:3]
	v_lshl_add_u64 v[2:3], v[10:11], 0, v[2:3]
	global_store_dwordx4 v[2:3], v[6:9], off
	ds_read_b128 v[2:5], v171
	s_cmpk_lt_i32 s3, 0x200
	v_add_u32_e32 v6, 16, v12
	v_ashrrev_i32_e32 v7, 31, v6
	v_lshlrev_b64 v[6:7], 12, v[6:7]
	v_lshl_add_u64 v[14:15], v[10:11], 0, v[6:7]
	ds_read_b128 v[6:9], v172
	s_waitcnt lgkmcnt(1)
	global_store_dwordx4 v[14:15], v[2:5], off
	s_nop 1
	v_add_u32_e32 v2, 24, v12
	v_ashrrev_i32_e32 v3, 31, v2
	v_lshlrev_b64 v[2:3], 12, v[2:3]
	v_lshl_add_u64 v[2:3], v[10:11], 0, v[2:3]
	s_waitcnt lgkmcnt(0)
	global_store_dwordx4 v[2:3], v[6:9], off
	ds_read_b128 v[2:5], v173
	s_nop 0
	v_add_u32_e32 v6, 32, v12
	v_ashrrev_i32_e32 v7, 31, v6
	v_lshlrev_b64 v[6:7], 12, v[6:7]
	v_lshl_add_u64 v[14:15], v[10:11], 0, v[6:7]
	ds_read_b128 v[6:9], v174
	s_waitcnt lgkmcnt(1)
	global_store_dwordx4 v[14:15], v[2:5], off
	s_nop 1
	v_add_u32_e32 v2, 40, v12
	v_ashrrev_i32_e32 v3, 31, v2
	v_lshlrev_b64 v[2:3], 12, v[2:3]
	v_lshl_add_u64 v[2:3], v[10:11], 0, v[2:3]
	s_waitcnt lgkmcnt(0)
	global_store_dwordx4 v[2:3], v[6:9], off
	ds_read_b128 v[2:5], v175
	s_nop 0
	v_add_u32_e32 v6, 48, v12
	v_ashrrev_i32_e32 v7, 31, v6
	v_lshlrev_b64 v[6:7], 12, v[6:7]
	v_lshl_add_u64 v[14:15], v[10:11], 0, v[6:7]
	ds_read_b128 v[6:9], v176
	s_waitcnt lgkmcnt(1)
	global_store_dwordx4 v[14:15], v[2:5], off
	s_nop 1
	v_add_u32_e32 v2, 56, v12
	v_ashrrev_i32_e32 v3, 31, v2
	v_lshlrev_b64 v[2:3], 12, v[2:3]
	v_lshl_add_u64 v[2:3], v[10:11], 0, v[2:3]
	s_waitcnt lgkmcnt(0)
	global_store_dwordx4 v[2:3], v[6:9], off
	ds_read_b128 v[2:5], v177
	s_nop 0
	v_add_u32_e32 v6, 64, v12
	v_ashrrev_i32_e32 v7, 31, v6
	v_lshlrev_b64 v[6:7], 12, v[6:7]
	v_lshl_add_u64 v[14:15], v[10:11], 0, v[6:7]
	ds_read_b128 v[6:9], v178
	s_waitcnt lgkmcnt(1)
	global_store_dwordx4 v[14:15], v[2:5], off
	s_nop 1
	v_add_u32_e32 v2, 0x48, v12
	v_ashrrev_i32_e32 v3, 31, v2
	v_lshlrev_b64 v[2:3], 12, v[2:3]
	v_lshl_add_u64 v[2:3], v[10:11], 0, v[2:3]
	s_waitcnt lgkmcnt(0)
	global_store_dwordx4 v[2:3], v[6:9], off
	ds_read_b128 v[2:5], v179
	s_nop 0
	v_add_u32_e32 v6, 0x50, v12
	v_ashrrev_i32_e32 v7, 31, v6
	v_lshlrev_b64 v[6:7], 12, v[6:7]
	v_lshl_add_u64 v[14:15], v[10:11], 0, v[6:7]
	ds_read_b128 v[6:9], v185
	s_waitcnt lgkmcnt(1)
	global_store_dwordx4 v[14:15], v[2:5], off
	s_nop 1
	v_add_u32_e32 v2, 0x58, v12
	v_ashrrev_i32_e32 v3, 31, v2
	v_lshlrev_b64 v[2:3], 12, v[2:3]
	v_lshl_add_u64 v[2:3], v[10:11], 0, v[2:3]
	s_waitcnt lgkmcnt(0)
	global_store_dwordx4 v[2:3], v[6:9], off
	ds_read_b128 v[2:5], v190
	s_nop 0
	v_add_u32_e32 v6, 0x60, v12
	v_ashrrev_i32_e32 v7, 31, v6
	v_lshlrev_b64 v[6:7], 12, v[6:7]
	v_lshl_add_u64 v[14:15], v[10:11], 0, v[6:7]
	ds_read_b128 v[6:9], v191
	s_waitcnt lgkmcnt(1)
	global_store_dwordx4 v[14:15], v[2:5], off
	s_nop 1
	v_add_u32_e32 v2, 0x68, v12
	v_ashrrev_i32_e32 v3, 31, v2
	v_lshlrev_b64 v[2:3], 12, v[2:3]
	v_lshl_add_u64 v[2:3], v[10:11], 0, v[2:3]
	s_waitcnt lgkmcnt(0)
	global_store_dwordx4 v[2:3], v[6:9], off
	ds_read_b128 v[2:5], v192
	s_nop 0
	v_add_u32_e32 v6, 0x70, v12
	v_ashrrev_i32_e32 v7, 31, v6
	v_lshlrev_b64 v[6:7], 12, v[6:7]
	v_lshl_add_u64 v[14:15], v[10:11], 0, v[6:7]
	ds_read_b128 v[6:9], v193
	s_waitcnt lgkmcnt(1)
	global_store_dwordx4 v[14:15], v[2:5], off
	s_nop 1
	v_add_u32_e32 v2, 0x78, v12
	v_ashrrev_i32_e32 v3, 31, v2
	v_lshlrev_b64 v[2:3], 12, v[2:3]
	v_lshl_add_u64 v[2:3], v[10:11], 0, v[2:3]
	s_waitcnt lgkmcnt(0)
	global_store_dwordx4 v[2:3], v[6:9], off
	s_cbranch_scc0 .LBB0_483

.LBB0_485:
	s_or_b64 exec, exec, s[4:5]
	s_waitcnt vmcnt(0)
	v_cvt_pk_bf16_f32 v132, v8, v20
	v_cvt_pk_bf16_f32 v133, v32, v40
	v_cvt_pk_bf16_f32 v134, v64, v72
	v_cvt_pk_bf16_f32 v135, v88, v100
	ds_write_b128 v165, v[132:135]
	v_cvt_pk_bf16_f32 v132, v9, v21
	v_cvt_pk_bf16_f32 v133, v33, v41
	v_cvt_pk_bf16_f32 v134, v65, v73
	v_cvt_pk_bf16_f32 v135, v89, v101
	ds_write_b128 v165, v[132:135] offset:4096
	v_cvt_pk_bf16_f32 v132, v10, v22
	v_cvt_pk_bf16_f32 v8, v11, v23
	v_cvt_pk_bf16_f32 v9, v35, v43
	v_cvt_pk_bf16_f32 v10, v67, v75
	v_cvt_pk_bf16_f32 v11, v91, v103
	ds_write_b128 v165, v[8:11] offset:12288
	v_cvt_pk_bf16_f32 v8, v4, v16
	v_cvt_pk_bf16_f32 v2, v5, v17
	v_cvt_pk_bf16_f32 v3, v29, v37
	v_cvt_pk_bf16_f32 v4, v61, v69
	v_cvt_pk_bf16_f32 v5, v85, v97
	ds_write_b128 v166, v[2:5] offset:4096
	v_cvt_pk_bf16_f32 v2, v6, v18
	v_cvt_pk_bf16_f32 v3, v30, v38
	v_cvt_pk_bf16_f32 v4, v62, v70
	v_cvt_pk_bf16_f32 v5, v86, v98
	ds_write_b128 v166, v[2:5] offset:8192
	v_cvt_pk_bf16_f32 v2, v7, v19
	v_cvt_pk_bf16_f32 v3, v31, v39
	v_cvt_pk_bf16_f32 v4, v63, v71
	v_cvt_pk_bf16_f32 v5, v87, v99
	ds_write_b128 v166, v[2:5] offset:12288
	v_cvt_pk_bf16_f32 v2, v12, v24
	v_cvt_pk_bf16_f32 v3, v44, v48
	v_cvt_pk_bf16_f32 v4, v76, v80
	v_cvt_pk_bf16_f32 v5, v108, v112
	ds_write_b128 v167, v[2:5]
	v_cvt_pk_bf16_f32 v2, v13, v25
	v_cvt_pk_bf16_f32 v3, v45, v49
	v_cvt_pk_bf16_f32 v4, v77, v81
	v_cvt_pk_bf16_f32 v5, v109, v113
	ds_write_b128 v167, v[2:5] offset:4096
	v_cvt_pk_bf16_f32 v2, v14, v26
	v_cvt_pk_bf16_f32 v3, v46, v50
	v_cvt_pk_bf16_f32 v4, v78, v82
	v_cvt_pk_bf16_f32 v5, v110, v114
	ds_write_b128 v167, v[2:5] offset:8192
	v_cvt_pk_bf16_f32 v2, v15, v27
	v_cvt_pk_bf16_f32 v3, v47, v51
	v_cvt_pk_bf16_f32 v4, v79, v83
	v_cvt_pk_bf16_f32 v5, v111, v115
	ds_write_b128 v167, v[2:5] offset:12288
	v_cvt_pk_bf16_f32 v2, v52, v56
	v_cvt_pk_bf16_f32 v3, v92, v104
	v_cvt_pk_bf16_f32 v4, v116, v120
	v_cvt_pk_bf16_f32 v5, v124, v128
	ds_write_b128 v168, v[2:5]
	v_cvt_pk_bf16_f32 v2, v53, v57
	v_cvt_pk_bf16_f32 v3, v93, v105
	v_cvt_pk_bf16_f32 v4, v117, v121
	v_cvt_pk_bf16_f32 v5, v125, v129
	ds_write_b128 v168, v[2:5] offset:4096
	v_cvt_pk_bf16_f32 v2, v54, v58
	v_cvt_pk_bf16_f32 v3, v94, v106
	v_cvt_pk_bf16_f32 v4, v118, v122
	v_cvt_pk_bf16_f32 v5, v126, v130
	v_cvt_pk_bf16_f32 v133, v34, v42
	v_cvt_pk_bf16_f32 v134, v66, v74
	v_cvt_pk_bf16_f32 v135, v90, v102
	v_cvt_pk_bf16_f32 v9, v28, v36
	v_cvt_pk_bf16_f32 v10, v60, v68
	v_cvt_pk_bf16_f32 v11, v84, v96
	ds_write_b128 v168, v[2:5] offset:8192
	v_cvt_pk_bf16_f32 v2, v55, v59
	v_cvt_pk_bf16_f32 v3, v95, v107
	v_cvt_pk_bf16_f32 v4, v119, v123
	v_cvt_pk_bf16_f32 v5, v127, v131
	s_sub_i32 s4, 0, s13
	ds_write_b128 v165, v[132:135] offset:8192
	ds_write_b128 v166, v[8:11]
	ds_write_b128 v168, v[2:5] offset:12288
	ds_read_b128 v[2:5], v169
	s_add_i32 s4, s4, s3
	v_add_u32_e32 v12, s4, v164
	s_ashr_i32 s1, s0, 31
	v_ashrrev_i32_e32 v13, 31, v12
	v_lshl_add_u64 v[10:11], s[0:1], 1, v[160:161]
	v_lshlrev_b64 v[6:7], 12, v[12:13]
	v_lshl_add_u64 v[14:15], v[10:11], 0, v[6:7]
	ds_read_b128 v[6:9], v170
	s_waitcnt lgkmcnt(0)
	global_store_dwordx4 v[14:15], v[2:5], off
	s_add_i32 s2, s2, s18
	s_add_i32 s3, s3, s12
	v_add_u32_e32 v2, 8, v12
	v_ashrrev_i32_e32 v3, 31, v2
	v_lshlrev_b64 v[2:3], 12, v[2:3]
	v_lshl_add_u64 v[2:3], v[10:11], 0, v[2:3]
	global_store_dwordx4 v[2:3], v[6:9], off
	ds_read_b128 v[2:5], v171
	s_cmpk_gt_i32 s2, 0x1ff
	v_add_u32_e32 v6, 16, v12
	v_ashrrev_i32_e32 v7, 31, v6
	v_lshlrev_b64 v[6:7], 12, v[6:7]
	v_lshl_add_u64 v[14:15], v[10:11], 0, v[6:7]
	ds_read_b128 v[6:9], v172
	s_waitcnt lgkmcnt(1)
	global_store_dwordx4 v[14:15], v[2:5], off
	s_nop 1
	v_add_u32_e32 v2, 24, v12
	v_ashrrev_i32_e32 v3, 31, v2
	v_lshlrev_b64 v[2:3], 12, v[2:3]
	v_lshl_add_u64 v[2:3], v[10:11], 0, v[2:3]
	s_waitcnt lgkmcnt(0)
	global_store_dwordx4 v[2:3], v[6:9], off
	ds_read_b128 v[2:5], v173
	s_nop 0
	v_add_u32_e32 v6, 32, v12
	v_ashrrev_i32_e32 v7, 31, v6
	v_lshlrev_b64 v[6:7], 12, v[6:7]
	v_lshl_add_u64 v[14:15], v[10:11], 0, v[6:7]
	ds_read_b128 v[6:9], v174
	s_waitcnt lgkmcnt(1)
	global_store_dwordx4 v[14:15], v[2:5], off
	s_nop 1
	v_add_u32_e32 v2, 40, v12
	v_ashrrev_i32_e32 v3, 31, v2
	v_lshlrev_b64 v[2:3], 12, v[2:3]
	v_lshl_add_u64 v[2:3], v[10:11], 0, v[2:3]
	s_waitcnt lgkmcnt(0)
	global_store_dwordx4 v[2:3], v[6:9], off
	ds_read_b128 v[2:5], v175
	s_nop 0
	v_add_u32_e32 v6, 48, v12
	v_ashrrev_i32_e32 v7, 31, v6
	v_lshlrev_b64 v[6:7], 12, v[6:7]
	v_lshl_add_u64 v[14:15], v[10:11], 0, v[6:7]
	ds_read_b128 v[6:9], v176
	s_waitcnt lgkmcnt(1)
	global_store_dwordx4 v[14:15], v[2:5], off
	s_nop 1
	v_add_u32_e32 v2, 56, v12
	v_ashrrev_i32_e32 v3, 31, v2
	v_lshlrev_b64 v[2:3], 12, v[2:3]
	v_lshl_add_u64 v[2:3], v[10:11], 0, v[2:3]
	s_waitcnt lgkmcnt(0)
	global_store_dwordx4 v[2:3], v[6:9], off
	ds_read_b128 v[2:5], v177
	s_nop 0
	v_add_u32_e32 v6, 64, v12
	v_ashrrev_i32_e32 v7, 31, v6
	v_lshlrev_b64 v[6:7], 12, v[6:7]
	v_lshl_add_u64 v[14:15], v[10:11], 0, v[6:7]
	ds_read_b128 v[6:9], v178
	s_waitcnt lgkmcnt(1)
	global_store_dwordx4 v[14:15], v[2:5], off
	s_nop 1
	v_add_u32_e32 v2, 0x48, v12
	v_ashrrev_i32_e32 v3, 31, v2
	v_lshlrev_b64 v[2:3], 12, v[2:3]
	v_lshl_add_u64 v[2:3], v[10:11], 0, v[2:3]
	s_waitcnt lgkmcnt(0)
	global_store_dwordx4 v[2:3], v[6:9], off
	ds_read_b128 v[2:5], v179
	s_nop 0
	v_add_u32_e32 v6, 0x50, v12
	v_ashrrev_i32_e32 v7, 31, v6
	v_lshlrev_b64 v[6:7], 12, v[6:7]
	v_lshl_add_u64 v[14:15], v[10:11], 0, v[6:7]
	ds_read_b128 v[6:9], v185
	s_waitcnt lgkmcnt(1)
	global_store_dwordx4 v[14:15], v[2:5], off
	s_nop 1
	v_add_u32_e32 v2, 0x58, v12
	v_ashrrev_i32_e32 v3, 31, v2
	v_lshlrev_b64 v[2:3], 12, v[2:3]
	v_lshl_add_u64 v[2:3], v[10:11], 0, v[2:3]
	s_waitcnt lgkmcnt(0)
	global_store_dwordx4 v[2:3], v[6:9], off
	ds_read_b128 v[2:5], v190
	s_nop 0
	v_add_u32_e32 v6, 0x60, v12
	v_ashrrev_i32_e32 v7, 31, v6
	v_lshlrev_b64 v[6:7], 12, v[6:7]
	v_lshl_add_u64 v[14:15], v[10:11], 0, v[6:7]
	ds_read_b128 v[6:9], v191
	s_waitcnt lgkmcnt(1)
	global_store_dwordx4 v[14:15], v[2:5], off
	s_nop 1
	v_add_u32_e32 v2, 0x68, v12
	v_ashrrev_i32_e32 v3, 31, v2
	v_lshlrev_b64 v[2:3], 12, v[2:3]
	v_lshl_add_u64 v[2:3], v[10:11], 0, v[2:3]
	s_waitcnt lgkmcnt(0)
	global_store_dwordx4 v[2:3], v[6:9], off
	ds_read_b128 v[2:5], v192
	s_nop 0
	v_add_u32_e32 v6, 0x70, v12
	v_ashrrev_i32_e32 v7, 31, v6
	v_lshlrev_b64 v[6:7], 12, v[6:7]
	v_lshl_add_u64 v[14:15], v[10:11], 0, v[6:7]
	ds_read_b128 v[6:9], v193
	s_waitcnt lgkmcnt(1)
	global_store_dwordx4 v[14:15], v[2:5], off
	s_nop 1
	v_add_u32_e32 v2, 0x78, v12
	v_ashrrev_i32_e32 v3, 31, v2
	v_lshlrev_b64 v[2:3], 12, v[2:3]
	v_lshl_add_u64 v[2:3], v[10:11], 0, v[2:3]
	s_waitcnt lgkmcnt(0)
	global_store_dwordx4 v[2:3], v[6:9], off
	s_cbranch_scc1 .LBB0_490

.LBB0_496:
	s_or_b64 exec, exec, s[4:5]
	s_waitcnt vmcnt(0)
	v_cvt_pk_bf16_f32 v130, v2, v14
	v_cvt_pk_bf16_f32 v131, v34, v46
	v_cvt_pk_bf16_f32 v132, v66, v82
	v_cvt_pk_bf16_f32 v133, v94, v110
	v_add_u32_e32 v1, v167, v166
	ds_write_b128 v1, v[130:133]
	v_cvt_pk_bf16_f32 v130, v3, v15
	v_cvt_pk_bf16_f32 v131, v35, v47
	v_cvt_pk_bf16_f32 v132, v67, v83
	v_cvt_pk_bf16_f32 v133, v95, v111
	ds_write_b128 v1, v[130:133] offset:4096
	v_cvt_pk_bf16_f32 v130, v4, v16
	v_cvt_pk_bf16_f32 v131, v36, v48
	v_cvt_pk_bf16_f32 v132, v68, v84
	v_cvt_pk_bf16_f32 v133, v96, v112
	v_cvt_pk_bf16_f32 v2, v5, v17
	v_cvt_pk_bf16_f32 v3, v37, v49
	v_cvt_pk_bf16_f32 v4, v69, v85
	v_cvt_pk_bf16_f32 v5, v97, v113
	ds_write_b128 v1, v[130:133] offset:8192
	ds_write_b128 v1, v[2:5] offset:12288
	v_cvt_pk_bf16_f32 v2, v10, v22
	v_cvt_pk_bf16_f32 v3, v38, v50
	v_cvt_pk_bf16_f32 v4, v62, v78
	v_cvt_pk_bf16_f32 v5, v90, v98
	v_add_u32_e32 v1, v167, v168
	ds_write_b128 v1, v[2:5]
	v_cvt_pk_bf16_f32 v2, v11, v23
	v_cvt_pk_bf16_f32 v3, v39, v51
	v_cvt_pk_bf16_f32 v4, v63, v79
	v_cvt_pk_bf16_f32 v5, v91, v99
	ds_write_b128 v1, v[2:5] offset:4096
	v_cvt_pk_bf16_f32 v2, v12, v24
	v_cvt_pk_bf16_f32 v3, v40, v52
	v_cvt_pk_bf16_f32 v4, v64, v80
	v_cvt_pk_bf16_f32 v5, v92, v100
	ds_write_b128 v1, v[2:5] offset:8192
	v_cvt_pk_bf16_f32 v2, v13, v25
	v_cvt_pk_bf16_f32 v3, v41, v53
	v_cvt_pk_bf16_f32 v4, v65, v81
	v_cvt_pk_bf16_f32 v5, v93, v101
	ds_write_b128 v1, v[2:5] offset:12288
	v_cvt_pk_bf16_f32 v2, v6, v18
	v_cvt_pk_bf16_f32 v3, v42, v54
	v_cvt_pk_bf16_f32 v4, v74, v86
	v_cvt_pk_bf16_f32 v5, v106, v118
	v_add_u32_e32 v1, v167, v169
	ds_write_b128 v1, v[2:5]
	v_cvt_pk_bf16_f32 v2, v7, v19
	v_cvt_pk_bf16_f32 v3, v43, v55
	v_cvt_pk_bf16_f32 v4, v75, v87
	v_cvt_pk_bf16_f32 v5, v107, v119
	ds_write_b128 v1, v[2:5] offset:4096
	v_cvt_pk_bf16_f32 v2, v8, v20
	v_cvt_pk_bf16_f32 v3, v44, v56
	v_cvt_pk_bf16_f32 v4, v76, v88
	v_cvt_pk_bf16_f32 v5, v108, v120
	ds_write_b128 v1, v[2:5] offset:8192
	v_cvt_pk_bf16_f32 v2, v9, v21
	v_cvt_pk_bf16_f32 v3, v45, v57
	v_cvt_pk_bf16_f32 v4, v77, v89
	v_cvt_pk_bf16_f32 v5, v109, v121
	ds_write_b128 v1, v[2:5] offset:12288
	v_cvt_pk_bf16_f32 v2, v26, v30
	v_cvt_pk_bf16_f32 v3, v58, v70
	v_cvt_pk_bf16_f32 v4, v102, v114
	v_cvt_pk_bf16_f32 v5, v122, v126
	v_add_u32_e32 v1, v167, v170
	ds_write_b128 v1, v[2:5]
	v_cvt_pk_bf16_f32 v2, v27, v31
	v_cvt_pk_bf16_f32 v3, v59, v71
	v_cvt_pk_bf16_f32 v4, v103, v115
	v_cvt_pk_bf16_f32 v5, v123, v127
	ds_write_b128 v1, v[2:5] offset:4096
	v_cvt_pk_bf16_f32 v2, v28, v32
	v_cvt_pk_bf16_f32 v3, v60, v72
	v_cvt_pk_bf16_f32 v4, v104, v116
	v_cvt_pk_bf16_f32 v5, v124, v128
	ds_write_b128 v1, v[2:5] offset:8192
	v_cvt_pk_bf16_f32 v2, v29, v33
	v_cvt_pk_bf16_f32 v3, v61, v73
	v_cvt_pk_bf16_f32 v4, v105, v117
	v_cvt_pk_bf16_f32 v5, v125, v129
	s_sub_i32 s4, 0, s45
	ds_write_b128 v1, v[2:5] offset:12288
	v_add_u32_e32 v1, v172, v171
	ds_read_b128 v[2:5], v1
	s_add_i32 s4, s4, s30
	v_add_u32_e32 v12, s4, v210
	s_ashr_i32 s15, s14, 31
	v_ashrrev_i32_e32 v13, 31, v12
	v_lshl_add_u64 v[10:11], s[14:15], 1, v[162:163]
	v_lshlrev_b64 v[6:7], 12, v[12:13]
	v_add_u32_e32 v1, v174, v173
	v_lshl_add_u64 v[14:15], v[10:11], 0, v[6:7]
	ds_read_b128 v[6:9], v1
	s_waitcnt lgkmcnt(0)
	global_store_dwordx4 v[14:15], v[2:5], off
	v_add_u32_e32 v1, v176, v175
	s_add_i32 s25, s25, s18
	v_add_u32_e32 v2, 8, v12
	v_ashrrev_i32_e32 v3, 31, v2
	v_lshlrev_b64 v[2:3], 12, v[2:3]
	v_lshl_add_u64 v[2:3], v[10:11], 0, v[2:3]
	global_store_dwordx4 v[2:3], v[6:9], off
	ds_read_b128 v[2:5], v1
	v_add_u32_e32 v1, v178, v177
	v_add_u32_e32 v6, 16, v12
	v_ashrrev_i32_e32 v7, 31, v6
	v_lshlrev_b64 v[6:7], 12, v[6:7]
	v_lshl_add_u64 v[14:15], v[10:11], 0, v[6:7]
	ds_read_b128 v[6:9], v1
	s_waitcnt lgkmcnt(1)
	global_store_dwordx4 v[14:15], v[2:5], off
	v_add_u32_e32 v1, v179, v171
	v_add_u32_e32 v210, s31, v210
	v_add_u32_e32 v2, 24, v12
	v_ashrrev_i32_e32 v3, 31, v2
	v_lshlrev_b64 v[2:3], 12, v[2:3]
	v_lshl_add_u64 v[2:3], v[10:11], 0, v[2:3]
	s_waitcnt lgkmcnt(0)
	global_store_dwordx4 v[2:3], v[6:9], off
	ds_read_b128 v[2:5], v1
	v_add_u32_e32 v1, v190, v185
	v_add_u32_e32 v6, 32, v12
	v_ashrrev_i32_e32 v7, 31, v6
	v_lshlrev_b64 v[6:7], 12, v[6:7]
	v_lshl_add_u64 v[14:15], v[10:11], 0, v[6:7]
	ds_read_b128 v[6:9], v1
	s_waitcnt lgkmcnt(1)
	global_store_dwordx4 v[14:15], v[2:5], off
	v_add_u32_e32 v1, v192, v191
	s_cmpk_lt_i32 s25, 0x200
	v_add_u32_e32 v2, 40, v12
	v_ashrrev_i32_e32 v3, 31, v2
	v_lshlrev_b64 v[2:3], 12, v[2:3]
	v_lshl_add_u64 v[2:3], v[10:11], 0, v[2:3]
	s_waitcnt lgkmcnt(0)
	global_store_dwordx4 v[2:3], v[6:9], off
	ds_read_b128 v[2:5], v1
	v_add_u32_e32 v1, v194, v193
	v_add_u32_e32 v6, 48, v12
	v_ashrrev_i32_e32 v7, 31, v6
	v_lshlrev_b64 v[6:7], 12, v[6:7]
	v_lshl_add_u64 v[14:15], v[10:11], 0, v[6:7]
	ds_read_b128 v[6:9], v1
	s_waitcnt lgkmcnt(1)
	global_store_dwordx4 v[14:15], v[2:5], off
	v_add_u32_e32 v1, v195, v171
	v_add_u32_e32 v209, s31, v209
	v_add_u32_e32 v2, 56, v12
	v_ashrrev_i32_e32 v3, 31, v2
	v_lshlrev_b64 v[2:3], 12, v[2:3]
	v_lshl_add_u64 v[2:3], v[10:11], 0, v[2:3]
	s_waitcnt lgkmcnt(0)
	global_store_dwordx4 v[2:3], v[6:9], off
	ds_read_b128 v[2:5], v1
	v_add_u32_e32 v1, v197, v196
	v_add_u32_e32 v6, 64, v12
	v_ashrrev_i32_e32 v7, 31, v6
	v_lshlrev_b64 v[6:7], 12, v[6:7]
	v_lshl_add_u64 v[14:15], v[10:11], 0, v[6:7]
	ds_read_b128 v[6:9], v1
	s_waitcnt lgkmcnt(1)
	global_store_dwordx4 v[14:15], v[2:5], off
	v_add_u32_e32 v1, v199, v198
	s_nop 0
	v_add_u32_e32 v2, 0x48, v12
	v_ashrrev_i32_e32 v3, 31, v2
	v_lshlrev_b64 v[2:3], 12, v[2:3]
	v_lshl_add_u64 v[2:3], v[10:11], 0, v[2:3]
	s_waitcnt lgkmcnt(0)
	global_store_dwordx4 v[2:3], v[6:9], off
	ds_read_b128 v[2:5], v1
	v_add_u32_e32 v1, v201, v200
	v_add_u32_e32 v6, 0x50, v12
	v_ashrrev_i32_e32 v7, 31, v6
	v_lshlrev_b64 v[6:7], 12, v[6:7]
	v_lshl_add_u64 v[14:15], v[10:11], 0, v[6:7]
	ds_read_b128 v[6:9], v1
	s_waitcnt lgkmcnt(1)
	global_store_dwordx4 v[14:15], v[2:5], off
	v_add_u32_e32 v1, v202, v171
	s_nop 0
	v_add_u32_e32 v2, 0x58, v12
	v_ashrrev_i32_e32 v3, 31, v2
	v_lshlrev_b64 v[2:3], 12, v[2:3]
	v_lshl_add_u64 v[2:3], v[10:11], 0, v[2:3]
	s_waitcnt lgkmcnt(0)
	global_store_dwordx4 v[2:3], v[6:9], off
	ds_read_b128 v[2:5], v1
	v_add_u32_e32 v1, v204, v203
	v_add_u32_e32 v6, 0x60, v12
	v_ashrrev_i32_e32 v7, 31, v6
	v_lshlrev_b64 v[6:7], 12, v[6:7]
	v_lshl_add_u64 v[14:15], v[10:11], 0, v[6:7]
	ds_read_b128 v[6:9], v1
	s_waitcnt lgkmcnt(1)
	global_store_dwordx4 v[14:15], v[2:5], off
	v_add_u32_e32 v1, v206, v205
	s_nop 0
	v_add_u32_e32 v2, 0x68, v12
	v_ashrrev_i32_e32 v3, 31, v2
	v_lshlrev_b64 v[2:3], 12, v[2:3]
	v_lshl_add_u64 v[2:3], v[10:11], 0, v[2:3]
	s_waitcnt lgkmcnt(0)
	global_store_dwordx4 v[2:3], v[6:9], off
	ds_read_b128 v[2:5], v1
	v_add_u32_e32 v1, v208, v207
	v_add_u32_e32 v6, 0x70, v12
	v_ashrrev_i32_e32 v7, 31, v6
	v_lshlrev_b64 v[6:7], 12, v[6:7]
	v_lshl_add_u64 v[14:15], v[10:11], 0, v[6:7]
	ds_read_b128 v[6:9], v1
	s_waitcnt lgkmcnt(1)
	global_store_dwordx4 v[14:15], v[2:5], off
	s_nop 1
	v_add_u32_e32 v2, 0x78, v12
	v_ashrrev_i32_e32 v3, 31, v2
	v_lshlrev_b64 v[2:3], 12, v[2:3]
	v_lshl_add_u64 v[2:3], v[10:11], 0, v[2:3]
	s_waitcnt lgkmcnt(0)
	global_store_dwordx4 v[2:3], v[6:9], off
	s_cbranch_scc0 .LBB0_492

.LBB0_503:
	s_or_b64 exec, exec, s[4:5]
	s_waitcnt vmcnt(0)
	v_cvt_pk_bf16_f32 v132, v102, v98
	v_cvt_pk_bf16_f32 v133, v110, v106
	v_cvt_pk_bf16_f32 v134, v118, v114
	v_cvt_pk_bf16_f32 v135, v126, v122
	v_add_u32_e32 v1, v167, v166
	ds_write_b128 v1, v[132:135]
	v_cvt_pk_bf16_f32 v132, v103, v99
	v_cvt_pk_bf16_f32 v133, v111, v107
	v_cvt_pk_bf16_f32 v134, v119, v115
	v_cvt_pk_bf16_f32 v135, v127, v123
	ds_write_b128 v1, v[132:135] offset:4096
	v_cvt_pk_bf16_f32 v132, v104, v100
	v_cvt_pk_bf16_f32 v133, v112, v108
	v_cvt_pk_bf16_f32 v134, v120, v116
	v_cvt_pk_bf16_f32 v135, v128, v124
	v_cvt_pk_bf16_f32 v98, v105, v101
	v_cvt_pk_bf16_f32 v99, v113, v109
	v_cvt_pk_bf16_f32 v100, v121, v117
	v_cvt_pk_bf16_f32 v101, v129, v125
	ds_write_b128 v1, v[132:135] offset:8192
	ds_write_b128 v1, v[98:101] offset:12288
	v_cvt_pk_bf16_f32 v98, v70, v66
	v_cvt_pk_bf16_f32 v99, v78, v74
	v_cvt_pk_bf16_f32 v100, v86, v82
	v_cvt_pk_bf16_f32 v101, v94, v90
	v_add_u32_e32 v1, v167, v168
	ds_write_b128 v1, v[98:101]
	v_cvt_pk_bf16_f32 v98, v71, v67
	v_cvt_pk_bf16_f32 v99, v79, v75
	v_cvt_pk_bf16_f32 v100, v87, v83
	v_cvt_pk_bf16_f32 v101, v95, v91
	ds_write_b128 v1, v[98:101] offset:4096
	v_cvt_pk_bf16_f32 v98, v72, v68
	v_cvt_pk_bf16_f32 v99, v80, v76
	v_cvt_pk_bf16_f32 v100, v88, v84
	v_cvt_pk_bf16_f32 v101, v96, v92
	v_cvt_pk_bf16_f32 v66, v73, v69
	v_cvt_pk_bf16_f32 v67, v81, v77
	v_cvt_pk_bf16_f32 v68, v89, v85
	v_cvt_pk_bf16_f32 v69, v97, v93
	ds_write_b128 v1, v[98:101] offset:8192
	ds_write_b128 v1, v[66:69] offset:12288
	v_cvt_pk_bf16_f32 v66, v38, v34
	v_cvt_pk_bf16_f32 v67, v46, v42
	v_cvt_pk_bf16_f32 v68, v54, v50
	v_cvt_pk_bf16_f32 v69, v62, v58
	v_add_u32_e32 v1, v167, v169
	ds_write_b128 v1, v[66:69]
	v_cvt_pk_bf16_f32 v66, v39, v35
	v_cvt_pk_bf16_f32 v67, v47, v43
	v_cvt_pk_bf16_f32 v68, v55, v51
	v_cvt_pk_bf16_f32 v69, v63, v59
	ds_write_b128 v1, v[66:69] offset:4096
	v_cvt_pk_bf16_f32 v66, v40, v36
	v_cvt_pk_bf16_f32 v67, v48, v44
	v_cvt_pk_bf16_f32 v68, v56, v52
	v_cvt_pk_bf16_f32 v69, v64, v60
	v_cvt_pk_bf16_f32 v34, v41, v37
	v_cvt_pk_bf16_f32 v35, v49, v45
	v_cvt_pk_bf16_f32 v36, v57, v53
	v_cvt_pk_bf16_f32 v37, v65, v61
	ds_write_b128 v1, v[66:69] offset:8192
	ds_write_b128 v1, v[34:37] offset:12288
	v_cvt_pk_bf16_f32 v34, v6, v2
	v_cvt_pk_bf16_f32 v35, v14, v10
	v_cvt_pk_bf16_f32 v36, v22, v18
	v_cvt_pk_bf16_f32 v37, v30, v26
	v_add_u32_e32 v1, v167, v170
	ds_write_b128 v1, v[34:37]
	v_cvt_pk_bf16_f32 v34, v7, v3
	v_cvt_pk_bf16_f32 v35, v15, v11
	v_cvt_pk_bf16_f32 v36, v23, v19
	v_cvt_pk_bf16_f32 v37, v31, v27
	ds_write_b128 v1, v[34:37] offset:4096
	v_cvt_pk_bf16_f32 v34, v8, v4
	v_cvt_pk_bf16_f32 v35, v16, v12
	v_cvt_pk_bf16_f32 v36, v24, v20
	v_cvt_pk_bf16_f32 v37, v32, v28
	v_cvt_pk_bf16_f32 v2, v9, v5
	v_cvt_pk_bf16_f32 v3, v17, v13
	v_cvt_pk_bf16_f32 v4, v25, v21
	v_cvt_pk_bf16_f32 v5, v33, v29
	s_sub_i32 s4, 0, s1
	ds_write_b128 v1, v[34:37] offset:8192
	ds_write_b128 v1, v[2:5] offset:12288
	v_add_u32_e32 v1, v172, v171
	ds_read_b128 v[2:5], v1
	s_add_i32 s4, s4, s3
	v_add_u32_e32 v12, s4, v165
	s_ashr_i32 s1, s0, 31
	v_ashrrev_i32_e32 v13, 31, v12
	v_lshl_add_u64 v[10:11], s[0:1], 1, v[130:131]
	v_lshlrev_b64 v[6:7], 14, v[12:13]
	v_add_u32_e32 v1, v174, v173
	v_lshl_add_u64 v[14:15], v[10:11], 0, v[6:7]
	ds_read_b128 v[6:9], v1
	s_waitcnt lgkmcnt(0)
	global_store_dwordx4 v[14:15], v[2:5], off
	v_add_u32_e32 v1, v176, v175
	s_add_i32 s2, s2, s18
	v_add_u32_e32 v2, 8, v12
	v_ashrrev_i32_e32 v3, 31, v2
	v_lshlrev_b64 v[2:3], 14, v[2:3]
	v_lshl_add_u64 v[2:3], v[10:11], 0, v[2:3]
	global_store_dwordx4 v[2:3], v[6:9], off
	ds_read_b128 v[2:5], v1
	v_add_u32_e32 v1, v178, v177
	v_add_u32_e32 v6, 16, v12
	v_ashrrev_i32_e32 v7, 31, v6
	v_lshlrev_b64 v[6:7], 14, v[6:7]
	v_lshl_add_u64 v[14:15], v[10:11], 0, v[6:7]
	ds_read_b128 v[6:9], v1
	s_waitcnt lgkmcnt(1)
	global_store_dwordx4 v[14:15], v[2:5], off
	v_add_u32_e32 v1, v179, v171
	v_add_u32_e32 v165, s10, v165
	v_add_u32_e32 v2, 24, v12
	v_ashrrev_i32_e32 v3, 31, v2
	v_lshlrev_b64 v[2:3], 14, v[2:3]
	v_lshl_add_u64 v[2:3], v[10:11], 0, v[2:3]
	s_waitcnt lgkmcnt(0)
	global_store_dwordx4 v[2:3], v[6:9], off
	ds_read_b128 v[2:5], v1
	v_add_u32_e32 v1, v190, v185
	v_add_u32_e32 v6, 32, v12
	v_ashrrev_i32_e32 v7, 31, v6
	v_lshlrev_b64 v[6:7], 14, v[6:7]
	v_lshl_add_u64 v[14:15], v[10:11], 0, v[6:7]
	ds_read_b128 v[6:9], v1
	s_waitcnt lgkmcnt(1)
	global_store_dwordx4 v[14:15], v[2:5], off
	v_add_u32_e32 v1, v192, v191
	s_cmpk_gt_i32 s2, 0x7ff
	v_add_u32_e32 v2, 40, v12
	v_ashrrev_i32_e32 v3, 31, v2
	v_lshlrev_b64 v[2:3], 14, v[2:3]
	v_lshl_add_u64 v[2:3], v[10:11], 0, v[2:3]
	s_waitcnt lgkmcnt(0)
	global_store_dwordx4 v[2:3], v[6:9], off
	ds_read_b128 v[2:5], v1
	v_add_u32_e32 v1, v194, v193
	v_add_u32_e32 v6, 48, v12
	v_ashrrev_i32_e32 v7, 31, v6
	v_lshlrev_b64 v[6:7], 14, v[6:7]
	v_lshl_add_u64 v[14:15], v[10:11], 0, v[6:7]
	ds_read_b128 v[6:9], v1
	s_waitcnt lgkmcnt(1)
	global_store_dwordx4 v[14:15], v[2:5], off
	v_add_u32_e32 v1, v195, v171
	v_add_u32_e32 v159, s10, v159
	v_add_u32_e32 v2, 56, v12
	v_ashrrev_i32_e32 v3, 31, v2
	v_lshlrev_b64 v[2:3], 14, v[2:3]
	v_lshl_add_u64 v[2:3], v[10:11], 0, v[2:3]
	s_waitcnt lgkmcnt(0)
	global_store_dwordx4 v[2:3], v[6:9], off
	ds_read_b128 v[2:5], v1
	v_add_u32_e32 v1, v197, v196
	v_add_u32_e32 v6, 64, v12
	v_ashrrev_i32_e32 v7, 31, v6
	v_lshlrev_b64 v[6:7], 14, v[6:7]
	v_lshl_add_u64 v[14:15], v[10:11], 0, v[6:7]
	ds_read_b128 v[6:9], v1
	s_waitcnt lgkmcnt(1)
	global_store_dwordx4 v[14:15], v[2:5], off
	v_add_u32_e32 v1, v199, v198
	s_nop 0
	v_add_u32_e32 v2, 0x48, v12
	v_ashrrev_i32_e32 v3, 31, v2
	v_lshlrev_b64 v[2:3], 14, v[2:3]
	v_lshl_add_u64 v[2:3], v[10:11], 0, v[2:3]
	s_waitcnt lgkmcnt(0)
	global_store_dwordx4 v[2:3], v[6:9], off
	ds_read_b128 v[2:5], v1
	v_add_u32_e32 v1, v201, v200
	v_add_u32_e32 v6, 0x50, v12
	v_ashrrev_i32_e32 v7, 31, v6
	v_lshlrev_b64 v[6:7], 14, v[6:7]
	v_lshl_add_u64 v[14:15], v[10:11], 0, v[6:7]
	ds_read_b128 v[6:9], v1
	s_waitcnt lgkmcnt(1)
	global_store_dwordx4 v[14:15], v[2:5], off
	v_add_u32_e32 v1, v202, v171
	s_nop 0
	v_add_u32_e32 v2, 0x58, v12
	v_ashrrev_i32_e32 v3, 31, v2
	v_lshlrev_b64 v[2:3], 14, v[2:3]
	v_lshl_add_u64 v[2:3], v[10:11], 0, v[2:3]
	s_waitcnt lgkmcnt(0)
	global_store_dwordx4 v[2:3], v[6:9], off
	ds_read_b128 v[2:5], v1
	v_add_u32_e32 v1, v204, v203
	v_add_u32_e32 v6, 0x60, v12
	v_ashrrev_i32_e32 v7, 31, v6
	v_lshlrev_b64 v[6:7], 14, v[6:7]
	v_lshl_add_u64 v[14:15], v[10:11], 0, v[6:7]
	ds_read_b128 v[6:9], v1
	s_waitcnt lgkmcnt(1)
	global_store_dwordx4 v[14:15], v[2:5], off
	v_add_u32_e32 v1, v206, v205
	s_nop 0
	v_add_u32_e32 v2, 0x68, v12
	v_ashrrev_i32_e32 v3, 31, v2
	v_lshlrev_b64 v[2:3], 14, v[2:3]
	v_lshl_add_u64 v[2:3], v[10:11], 0, v[2:3]
	s_waitcnt lgkmcnt(0)
	global_store_dwordx4 v[2:3], v[6:9], off
	ds_read_b128 v[2:5], v1
	v_add_u32_e32 v1, v208, v207
	v_add_u32_e32 v6, 0x70, v12
	v_ashrrev_i32_e32 v7, 31, v6
	v_lshlrev_b64 v[6:7], 14, v[6:7]
	v_lshl_add_u64 v[14:15], v[10:11], 0, v[6:7]
	ds_read_b128 v[6:9], v1
	s_waitcnt lgkmcnt(1)
	global_store_dwordx4 v[14:15], v[2:5], off
	s_nop 1
	v_add_u32_e32 v2, 0x78, v12
	v_ashrrev_i32_e32 v3, 31, v2
	v_lshlrev_b64 v[2:3], 14, v[2:3]
	v_lshl_add_u64 v[2:3], v[10:11], 0, v[2:3]
	s_waitcnt lgkmcnt(0)
	global_store_dwordx4 v[2:3], v[6:9], off
	s_cbranch_scc1 .LBB0_506

.LBB0_574:
	s_or_b64 exec, exec, s[4:5]
	v_cvt_pk_bf16_f32 v64, v174, v172
	v_cvt_pk_bf16_f32 v65, v170, v168
	v_cvt_pk_bf16_f32 v66, v166, v164
	v_cvt_pk_bf16_f32 v67, v162, v160
	ds_write_b128 v178, v[64:67]
	v_cvt_pk_bf16_f32 v64, v175, v173
	v_cvt_pk_bf16_f32 v65, v171, v169
	v_cvt_pk_bf16_f32 v66, v167, v165
	v_cvt_pk_bf16_f32 v67, v163, v161
	ds_write_b128 v178, v[64:67] offset:4096
	v_cvt_pk_bf16_f32 v64, v158, v156
	v_cvt_pk_bf16_f32 v65, v154, v152
	v_cvt_pk_bf16_f32 v66, v150, v148
	v_cvt_pk_bf16_f32 v67, v146, v144
	ds_write_b128 v178, v[64:67] offset:8192
	v_cvt_pk_bf16_f32 v64, v159, v157
	v_cvt_pk_bf16_f32 v65, v155, v153
	v_cvt_pk_bf16_f32 v66, v151, v149
	v_cvt_pk_bf16_f32 v67, v147, v145
	ds_write_b128 v178, v[64:67] offset:12288
	v_cvt_pk_bf16_f32 v64, v142, v140
	v_cvt_pk_bf16_f32 v65, v138, v136
	v_cvt_pk_bf16_f32 v66, v116, v114
	v_cvt_pk_bf16_f32 v67, v112, v110
	ds_write_b128 v179, v[64:67]
	v_cvt_pk_bf16_f32 v64, v143, v141
	v_cvt_pk_bf16_f32 v65, v139, v137
	v_cvt_pk_bf16_f32 v66, v117, v115
	v_cvt_pk_bf16_f32 v67, v113, v111
	ds_write_b128 v179, v[64:67] offset:4096
	v_cvt_pk_bf16_f32 v64, v134, v132
	v_cvt_pk_bf16_f32 v65, v108, v106
	v_cvt_pk_bf16_f32 v66, v104, v102
	v_cvt_pk_bf16_f32 v67, v100, v98
	ds_write_b128 v179, v[64:67] offset:8192
	v_cvt_pk_bf16_f32 v64, v135, v133
	v_cvt_pk_bf16_f32 v65, v109, v107
	v_cvt_pk_bf16_f32 v66, v105, v103
	v_cvt_pk_bf16_f32 v67, v101, v99
	ds_write_b128 v179, v[64:67] offset:12288
	v_cvt_pk_bf16_f32 v64, v118, v62
	v_cvt_pk_bf16_f32 v65, v58, v54
	v_cvt_pk_bf16_f32 v66, v50, v46
	v_cvt_pk_bf16_f32 v67, v38, v34
	ds_write_b128 v185, v[64:67]
	v_cvt_pk_bf16_f32 v62, v119, v63
	v_cvt_pk_bf16_f32 v63, v59, v55
	v_cvt_pk_bf16_f32 v64, v51, v47
	v_cvt_pk_bf16_f32 v65, v39, v35
	ds_write_b128 v185, v[62:65] offset:4096
	v_cvt_pk_bf16_f32 v65, v40, v36
	v_cvt_pk_bf16_f32 v34, v45, v43
	v_cvt_pk_bf16_f32 v35, v61, v57
	v_cvt_pk_bf16_f32 v36, v53, v49
	v_cvt_pk_bf16_f32 v37, v41, v37
	ds_write_b128 v185, v[34:37] offset:12288
	v_cvt_pk_bf16_f32 v34, v30, v26
	v_cvt_pk_bf16_f32 v35, v22, v18
	v_cvt_pk_bf16_f32 v36, v14, v10
	v_cvt_pk_bf16_f32 v37, v6, v2
	ds_write_b128 v190, v[34:37]
	v_cvt_pk_bf16_f32 v34, v31, v27
	v_cvt_pk_bf16_f32 v35, v23, v19
	v_cvt_pk_bf16_f32 v36, v15, v11
	v_cvt_pk_bf16_f32 v37, v7, v3
	v_cvt_pk_bf16_f32 v62, v44, v42
	v_cvt_pk_bf16_f32 v63, v60, v56
	v_cvt_pk_bf16_f32 v64, v52, v48
	ds_write_b128 v190, v[34:37] offset:4096
	v_cvt_pk_bf16_f32 v34, v32, v28
	v_cvt_pk_bf16_f32 v35, v24, v20
	v_cvt_pk_bf16_f32 v36, v16, v12
	v_cvt_pk_bf16_f32 v37, v8, v4
	v_cvt_pk_bf16_f32 v2, v33, v29
	v_cvt_pk_bf16_f32 v3, v25, v21
	v_cvt_pk_bf16_f32 v4, v17, v13
	v_cvt_pk_bf16_f32 v5, v9, v5
	s_sub_i32 s2, 0, s2
	ds_write_b128 v185, v[62:65] offset:8192
	ds_write_b128 v190, v[34:37] offset:8192
	ds_write_b128 v190, v[2:5] offset:12288
	ds_read_b128 v[2:5], v191
	s_add_i32 s2, s2, s24
	v_add_u32_e32 v12, s2, v177
	v_ashrrev_i32_e32 v13, 31, v12
	v_lshl_add_u64 v[10:11], s[0:1], 1, v[130:131]
	v_lshlrev_b64 v[6:7], 12, v[12:13]
	v_lshl_add_u64 v[14:15], v[10:11], 0, v[6:7]
	ds_read_b128 v[6:9], v192
	s_waitcnt lgkmcnt(0)
	global_store_dwordx4 v[14:15], v[2:5], off
	s_add_i32 s15, s15, s18
	s_add_i32 s24, s24, s25
	v_add_u32_e32 v2, 8, v12
	v_ashrrev_i32_e32 v3, 31, v2
	v_lshlrev_b64 v[2:3], 12, v[2:3]
	v_lshl_add_u64 v[2:3], v[10:11], 0, v[2:3]
	global_store_dwordx4 v[2:3], v[6:9], off
	ds_read_b128 v[2:5], v193
	s_cmpk_lt_i32 s15, 0x800
	v_add_u32_e32 v6, 16, v12
	v_ashrrev_i32_e32 v7, 31, v6
	v_lshlrev_b64 v[6:7], 12, v[6:7]
	v_lshl_add_u64 v[14:15], v[10:11], 0, v[6:7]
	ds_read_b128 v[6:9], v194
	s_waitcnt lgkmcnt(1)
	global_store_dwordx4 v[14:15], v[2:5], off
	s_nop 1
	v_add_u32_e32 v2, 24, v12
	v_ashrrev_i32_e32 v3, 31, v2
	v_lshlrev_b64 v[2:3], 12, v[2:3]
	v_lshl_add_u64 v[2:3], v[10:11], 0, v[2:3]
	s_waitcnt lgkmcnt(0)
	global_store_dwordx4 v[2:3], v[6:9], off
	ds_read_b128 v[2:5], v195
	s_nop 0
	v_add_u32_e32 v6, 32, v12
	v_ashrrev_i32_e32 v7, 31, v6
	v_lshlrev_b64 v[6:7], 12, v[6:7]
	v_lshl_add_u64 v[14:15], v[10:11], 0, v[6:7]
	ds_read_b128 v[6:9], v196
	s_waitcnt lgkmcnt(1)
	global_store_dwordx4 v[14:15], v[2:5], off
	s_nop 1
	v_add_u32_e32 v2, 40, v12
	v_ashrrev_i32_e32 v3, 31, v2
	v_lshlrev_b64 v[2:3], 12, v[2:3]
	v_lshl_add_u64 v[2:3], v[10:11], 0, v[2:3]
	s_waitcnt lgkmcnt(0)
	global_store_dwordx4 v[2:3], v[6:9], off
	ds_read_b128 v[2:5], v197
	s_nop 0
	v_add_u32_e32 v6, 48, v12
	v_ashrrev_i32_e32 v7, 31, v6
	v_lshlrev_b64 v[6:7], 12, v[6:7]
	v_lshl_add_u64 v[14:15], v[10:11], 0, v[6:7]
	ds_read_b128 v[6:9], v198
	s_waitcnt lgkmcnt(1)
	global_store_dwordx4 v[14:15], v[2:5], off
	s_nop 1
	v_add_u32_e32 v2, 56, v12
	v_ashrrev_i32_e32 v3, 31, v2
	v_lshlrev_b64 v[2:3], 12, v[2:3]
	v_lshl_add_u64 v[2:3], v[10:11], 0, v[2:3]
	s_waitcnt lgkmcnt(0)
	global_store_dwordx4 v[2:3], v[6:9], off
	ds_read_b128 v[2:5], v199
	s_nop 0
	v_add_u32_e32 v6, 64, v12
	v_ashrrev_i32_e32 v7, 31, v6
	v_lshlrev_b64 v[6:7], 12, v[6:7]
	v_lshl_add_u64 v[14:15], v[10:11], 0, v[6:7]
	ds_read_b128 v[6:9], v200
	s_waitcnt lgkmcnt(1)
	global_store_dwordx4 v[14:15], v[2:5], off
	s_nop 1
	v_add_u32_e32 v2, 0x48, v12
	v_ashrrev_i32_e32 v3, 31, v2
	v_lshlrev_b64 v[2:3], 12, v[2:3]
	v_lshl_add_u64 v[2:3], v[10:11], 0, v[2:3]
	s_waitcnt lgkmcnt(0)
	global_store_dwordx4 v[2:3], v[6:9], off
	ds_read_b128 v[2:5], v201
	s_nop 0
	v_add_u32_e32 v6, 0x50, v12
	v_ashrrev_i32_e32 v7, 31, v6
	v_lshlrev_b64 v[6:7], 12, v[6:7]
	v_lshl_add_u64 v[14:15], v[10:11], 0, v[6:7]
	ds_read_b128 v[6:9], v202
	s_waitcnt lgkmcnt(1)
	global_store_dwordx4 v[14:15], v[2:5], off
	s_nop 1
	v_add_u32_e32 v2, 0x58, v12
	v_ashrrev_i32_e32 v3, 31, v2
	v_lshlrev_b64 v[2:3], 12, v[2:3]
	v_lshl_add_u64 v[2:3], v[10:11], 0, v[2:3]
	s_waitcnt lgkmcnt(0)
	global_store_dwordx4 v[2:3], v[6:9], off
	ds_read_b128 v[2:5], v203
	s_nop 0
	v_add_u32_e32 v6, 0x60, v12
	v_ashrrev_i32_e32 v7, 31, v6
	v_lshlrev_b64 v[6:7], 12, v[6:7]
	v_lshl_add_u64 v[14:15], v[10:11], 0, v[6:7]
	ds_read_b128 v[6:9], v204
	s_waitcnt lgkmcnt(1)
	global_store_dwordx4 v[14:15], v[2:5], off
	s_nop 1
	v_add_u32_e32 v2, 0x68, v12
	v_ashrrev_i32_e32 v3, 31, v2
	v_lshlrev_b64 v[2:3], 12, v[2:3]
	v_lshl_add_u64 v[2:3], v[10:11], 0, v[2:3]
	s_waitcnt lgkmcnt(0)
	global_store_dwordx4 v[2:3], v[6:9], off
	ds_read_b128 v[2:5], v205
	s_nop 0
	v_add_u32_e32 v6, 0x70, v12
	v_ashrrev_i32_e32 v7, 31, v6
	v_lshlrev_b64 v[6:7], 12, v[6:7]
	v_lshl_add_u64 v[14:15], v[10:11], 0, v[6:7]
	ds_read_b128 v[6:9], v206
	s_waitcnt lgkmcnt(1)
	global_store_dwordx4 v[14:15], v[2:5], off
	s_nop 1
	v_add_u32_e32 v2, 0x78, v12
	v_ashrrev_i32_e32 v3, 31, v2
	v_lshlrev_b64 v[2:3], 12, v[2:3]
	v_lshl_add_u64 v[2:3], v[10:11], 0, v[2:3]
	s_waitcnt lgkmcnt(0)
	global_store_dwordx4 v[2:3], v[6:9], off
	s_cbranch_scc0 .LBB0_577

.LBB0_579:
	s_or_b64 exec, exec, s[4:5]
	s_waitcnt vmcnt(0)
	v_cvt_pk_bf16_f32 v154, v102, v98
	v_cvt_pk_bf16_f32 v155, v110, v106
	v_cvt_pk_bf16_f32 v156, v118, v114
	v_cvt_pk_bf16_f32 v157, v126, v122
	ds_write_b128 v134, v[154:157]
	v_cvt_pk_bf16_f32 v154, v103, v99
	v_cvt_pk_bf16_f32 v155, v111, v107
	v_cvt_pk_bf16_f32 v156, v119, v115
	v_cvt_pk_bf16_f32 v157, v127, v123
	ds_write_b128 v134, v[154:157] offset:4096
	v_cvt_pk_bf16_f32 v154, v104, v100
	v_cvt_pk_bf16_f32 v98, v105, v101
	v_cvt_pk_bf16_f32 v99, v113, v109
	v_cvt_pk_bf16_f32 v100, v121, v117
	v_cvt_pk_bf16_f32 v101, v129, v125
	ds_write_b128 v134, v[98:101] offset:12288
	v_cvt_pk_bf16_f32 v98, v70, v66
	v_cvt_pk_bf16_f32 v99, v78, v74
	v_cvt_pk_bf16_f32 v100, v86, v82
	v_cvt_pk_bf16_f32 v101, v94, v90
	ds_write_b128 v135, v[98:101]
	v_cvt_pk_bf16_f32 v98, v71, v67
	v_cvt_pk_bf16_f32 v99, v79, v75
	v_cvt_pk_bf16_f32 v100, v87, v83
	v_cvt_pk_bf16_f32 v101, v95, v91
	ds_write_b128 v135, v[98:101] offset:4096
	v_cvt_pk_bf16_f32 v98, v72, v68
	v_cvt_pk_bf16_f32 v66, v73, v69
	v_cvt_pk_bf16_f32 v67, v81, v77
	v_cvt_pk_bf16_f32 v68, v89, v85
	v_cvt_pk_bf16_f32 v69, v97, v93
	ds_write_b128 v135, v[66:69] offset:12288
	v_cvt_pk_bf16_f32 v66, v38, v34
	v_cvt_pk_bf16_f32 v67, v46, v42
	v_cvt_pk_bf16_f32 v68, v54, v50
	v_cvt_pk_bf16_f32 v69, v62, v58
	ds_write_b128 v136, v[66:69]
	v_cvt_pk_bf16_f32 v66, v39, v35
	v_cvt_pk_bf16_f32 v67, v47, v43
	v_cvt_pk_bf16_f32 v68, v55, v51
	v_cvt_pk_bf16_f32 v69, v63, v59
	ds_write_b128 v136, v[66:69] offset:4096
	v_cvt_pk_bf16_f32 v66, v40, v36
	v_cvt_pk_bf16_f32 v34, v41, v37
	v_cvt_pk_bf16_f32 v35, v49, v45
	v_cvt_pk_bf16_f32 v36, v57, v53
	v_cvt_pk_bf16_f32 v37, v65, v61
	ds_write_b128 v136, v[34:37] offset:12288
	v_cvt_pk_bf16_f32 v34, v6, v2
	v_cvt_pk_bf16_f32 v35, v14, v10
	v_cvt_pk_bf16_f32 v36, v22, v18
	v_cvt_pk_bf16_f32 v37, v30, v26
	ds_write_b128 v137, v[34:37]
	v_cvt_pk_bf16_f32 v34, v7, v3
	v_cvt_pk_bf16_f32 v35, v15, v11
	v_cvt_pk_bf16_f32 v36, v23, v19
	v_cvt_pk_bf16_f32 v37, v31, v27
	v_cvt_pk_bf16_f32 v155, v112, v108
	v_cvt_pk_bf16_f32 v156, v120, v116
	v_cvt_pk_bf16_f32 v157, v128, v124
	v_cvt_pk_bf16_f32 v99, v80, v76
	v_cvt_pk_bf16_f32 v100, v88, v84
	v_cvt_pk_bf16_f32 v101, v96, v92
	v_cvt_pk_bf16_f32 v67, v48, v44
	v_cvt_pk_bf16_f32 v68, v56, v52
	v_cvt_pk_bf16_f32 v69, v64, v60
	ds_write_b128 v137, v[34:37] offset:4096
	v_cvt_pk_bf16_f32 v34, v8, v4
	v_cvt_pk_bf16_f32 v35, v16, v12
	v_cvt_pk_bf16_f32 v36, v24, v20
	v_cvt_pk_bf16_f32 v37, v32, v28
	v_cvt_pk_bf16_f32 v2, v9, v5
	v_cvt_pk_bf16_f32 v3, v17, v13
	v_cvt_pk_bf16_f32 v4, v25, v21
	v_cvt_pk_bf16_f32 v5, v33, v29
	s_sub_i32 s4, 0, s1
	ds_write_b128 v134, v[154:157] offset:8192
	ds_write_b128 v135, v[98:101] offset:8192
	ds_write_b128 v136, v[66:69] offset:8192
	ds_write_b128 v137, v[34:37] offset:8192
	ds_write_b128 v137, v[2:5] offset:12288
	ds_read_b128 v[2:5], v138
	s_add_i32 s4, s4, s3
	v_add_u32_e32 v12, s4, v133
	s_ashr_i32 s1, s0, 31
	v_ashrrev_i32_e32 v13, 31, v12
	v_lshl_add_u64 v[10:11], s[0:1], 1, v[130:131]
	v_lshlrev_b64 v[6:7], 14, v[12:13]
	v_lshl_add_u64 v[14:15], v[10:11], 0, v[6:7]
	ds_read_b128 v[6:9], v139
	s_waitcnt lgkmcnt(0)
	global_store_dwordx4 v[14:15], v[2:5], off
	s_add_i32 s2, s2, s18
	s_add_i32 s3, s3, s10
	v_add_u32_e32 v2, 8, v12
	v_ashrrev_i32_e32 v3, 31, v2
	v_lshlrev_b64 v[2:3], 14, v[2:3]
	v_lshl_add_u64 v[2:3], v[10:11], 0, v[2:3]
	global_store_dwordx4 v[2:3], v[6:9], off
	ds_read_b128 v[2:5], v140
	s_cmpk_gt_i32 s2, 0x7ff
	v_add_u32_e32 v6, 16, v12
	v_ashrrev_i32_e32 v7, 31, v6
	v_lshlrev_b64 v[6:7], 14, v[6:7]
	v_lshl_add_u64 v[14:15], v[10:11], 0, v[6:7]
	ds_read_b128 v[6:9], v141
	s_waitcnt lgkmcnt(1)
	global_store_dwordx4 v[14:15], v[2:5], off
	s_nop 1
	v_add_u32_e32 v2, 24, v12
	v_ashrrev_i32_e32 v3, 31, v2
	v_lshlrev_b64 v[2:3], 14, v[2:3]
	v_lshl_add_u64 v[2:3], v[10:11], 0, v[2:3]
	s_waitcnt lgkmcnt(0)
	global_store_dwordx4 v[2:3], v[6:9], off
	ds_read_b128 v[2:5], v142
	s_nop 0
	v_add_u32_e32 v6, 32, v12
	v_ashrrev_i32_e32 v7, 31, v6
	v_lshlrev_b64 v[6:7], 14, v[6:7]
	v_lshl_add_u64 v[14:15], v[10:11], 0, v[6:7]
	ds_read_b128 v[6:9], v143
	s_waitcnt lgkmcnt(1)
	global_store_dwordx4 v[14:15], v[2:5], off
	s_nop 1
	v_add_u32_e32 v2, 40, v12
	v_ashrrev_i32_e32 v3, 31, v2
	v_lshlrev_b64 v[2:3], 14, v[2:3]
	v_lshl_add_u64 v[2:3], v[10:11], 0, v[2:3]
	s_waitcnt lgkmcnt(0)
	global_store_dwordx4 v[2:3], v[6:9], off
	ds_read_b128 v[2:5], v144
	s_nop 0
	v_add_u32_e32 v6, 48, v12
	v_ashrrev_i32_e32 v7, 31, v6
	v_lshlrev_b64 v[6:7], 14, v[6:7]
	v_lshl_add_u64 v[14:15], v[10:11], 0, v[6:7]
	ds_read_b128 v[6:9], v145
	s_waitcnt lgkmcnt(1)
	global_store_dwordx4 v[14:15], v[2:5], off
	s_nop 1
	v_add_u32_e32 v2, 56, v12
	v_ashrrev_i32_e32 v3, 31, v2
	v_lshlrev_b64 v[2:3], 14, v[2:3]
	v_lshl_add_u64 v[2:3], v[10:11], 0, v[2:3]
	s_waitcnt lgkmcnt(0)
	global_store_dwordx4 v[2:3], v[6:9], off
	ds_read_b128 v[2:5], v146
	s_nop 0
	v_add_u32_e32 v6, 64, v12
	v_ashrrev_i32_e32 v7, 31, v6
	v_lshlrev_b64 v[6:7], 14, v[6:7]
	v_lshl_add_u64 v[14:15], v[10:11], 0, v[6:7]
	ds_read_b128 v[6:9], v147
	s_waitcnt lgkmcnt(1)
	global_store_dwordx4 v[14:15], v[2:5], off
	s_nop 1
	v_add_u32_e32 v2, 0x48, v12
	v_ashrrev_i32_e32 v3, 31, v2
	v_lshlrev_b64 v[2:3], 14, v[2:3]
	v_lshl_add_u64 v[2:3], v[10:11], 0, v[2:3]
	s_waitcnt lgkmcnt(0)
	global_store_dwordx4 v[2:3], v[6:9], off
	ds_read_b128 v[2:5], v148
	s_nop 0
	v_add_u32_e32 v6, 0x50, v12
	v_ashrrev_i32_e32 v7, 31, v6
	v_lshlrev_b64 v[6:7], 14, v[6:7]
	v_lshl_add_u64 v[14:15], v[10:11], 0, v[6:7]
	ds_read_b128 v[6:9], v149
	s_waitcnt lgkmcnt(1)
	global_store_dwordx4 v[14:15], v[2:5], off
	s_nop 1
	v_add_u32_e32 v2, 0x58, v12
	v_ashrrev_i32_e32 v3, 31, v2
	v_lshlrev_b64 v[2:3], 14, v[2:3]
	v_lshl_add_u64 v[2:3], v[10:11], 0, v[2:3]
	s_waitcnt lgkmcnt(0)
	global_store_dwordx4 v[2:3], v[6:9], off
	ds_read_b128 v[2:5], v150
	s_nop 0
	v_add_u32_e32 v6, 0x60, v12
	v_ashrrev_i32_e32 v7, 31, v6
	v_lshlrev_b64 v[6:7], 14, v[6:7]
	v_lshl_add_u64 v[14:15], v[10:11], 0, v[6:7]
	ds_read_b128 v[6:9], v151
	s_waitcnt lgkmcnt(1)
	global_store_dwordx4 v[14:15], v[2:5], off
	s_nop 1
	v_add_u32_e32 v2, 0x68, v12
	v_ashrrev_i32_e32 v3, 31, v2
	v_lshlrev_b64 v[2:3], 14, v[2:3]
	v_lshl_add_u64 v[2:3], v[10:11], 0, v[2:3]
	s_waitcnt lgkmcnt(0)
	global_store_dwordx4 v[2:3], v[6:9], off
	ds_read_b128 v[2:5], v152
	s_nop 0
	v_add_u32_e32 v6, 0x70, v12
	v_ashrrev_i32_e32 v7, 31, v6
	v_lshlrev_b64 v[6:7], 14, v[6:7]
	v_lshl_add_u64 v[14:15], v[10:11], 0, v[6:7]
	ds_read_b128 v[6:9], v153
	s_waitcnt lgkmcnt(1)
	global_store_dwordx4 v[14:15], v[2:5], off
	s_nop 1
	v_add_u32_e32 v2, 0x78, v12
	v_ashrrev_i32_e32 v3, 31, v2
	v_lshlrev_b64 v[2:3], 14, v[2:3]
	v_lshl_add_u64 v[2:3], v[10:11], 0, v[2:3]
	s_waitcnt lgkmcnt(0)
	global_store_dwordx4 v[2:3], v[6:9], off
	s_cbranch_scc1 .LBB0_582

.LBB0_587:
	s_or_b64 exec, exec, s[4:5]
	s_waitcnt vmcnt(0)
	v_cvt_pk_bf16_f32 v132, v8, v20
	v_cvt_pk_bf16_f32 v133, v32, v40
	v_cvt_pk_bf16_f32 v134, v64, v72
	v_cvt_pk_bf16_f32 v135, v88, v100
	ds_write_b128 v165, v[132:135]
	v_cvt_pk_bf16_f32 v132, v9, v21
	v_cvt_pk_bf16_f32 v133, v33, v41
	v_cvt_pk_bf16_f32 v134, v65, v73
	v_cvt_pk_bf16_f32 v135, v89, v101
	ds_write_b128 v165, v[132:135] offset:4096
	v_cvt_pk_bf16_f32 v132, v10, v22
	v_cvt_pk_bf16_f32 v8, v11, v23
	v_cvt_pk_bf16_f32 v9, v35, v43
	v_cvt_pk_bf16_f32 v10, v67, v75
	v_cvt_pk_bf16_f32 v11, v91, v103
	ds_write_b128 v165, v[8:11] offset:12288
	v_cvt_pk_bf16_f32 v8, v4, v16
	v_cvt_pk_bf16_f32 v2, v5, v17
	v_cvt_pk_bf16_f32 v3, v29, v37
	v_cvt_pk_bf16_f32 v4, v61, v69
	v_cvt_pk_bf16_f32 v5, v85, v97
	ds_write_b128 v166, v[2:5] offset:4096
	v_cvt_pk_bf16_f32 v2, v6, v18
	v_cvt_pk_bf16_f32 v3, v30, v38
	v_cvt_pk_bf16_f32 v4, v62, v70
	v_cvt_pk_bf16_f32 v5, v86, v98
	ds_write_b128 v166, v[2:5] offset:8192
	v_cvt_pk_bf16_f32 v2, v7, v19
	v_cvt_pk_bf16_f32 v3, v31, v39
	v_cvt_pk_bf16_f32 v4, v63, v71
	v_cvt_pk_bf16_f32 v5, v87, v99
	ds_write_b128 v166, v[2:5] offset:12288
	v_cvt_pk_bf16_f32 v2, v12, v24
	v_cvt_pk_bf16_f32 v3, v44, v48
	v_cvt_pk_bf16_f32 v4, v76, v80
	v_cvt_pk_bf16_f32 v5, v108, v112
	ds_write_b128 v167, v[2:5]
	v_cvt_pk_bf16_f32 v2, v13, v25
	v_cvt_pk_bf16_f32 v3, v45, v49
	v_cvt_pk_bf16_f32 v4, v77, v81
	v_cvt_pk_bf16_f32 v5, v109, v113
	ds_write_b128 v167, v[2:5] offset:4096
	v_cvt_pk_bf16_f32 v2, v14, v26
	v_cvt_pk_bf16_f32 v3, v46, v50
	v_cvt_pk_bf16_f32 v4, v78, v82
	v_cvt_pk_bf16_f32 v5, v110, v114
	ds_write_b128 v167, v[2:5] offset:8192
	v_cvt_pk_bf16_f32 v2, v15, v27
	v_cvt_pk_bf16_f32 v3, v47, v51
	v_cvt_pk_bf16_f32 v4, v79, v83
	v_cvt_pk_bf16_f32 v5, v111, v115
	ds_write_b128 v167, v[2:5] offset:12288
	v_cvt_pk_bf16_f32 v2, v52, v56
	v_cvt_pk_bf16_f32 v3, v92, v104
	v_cvt_pk_bf16_f32 v4, v116, v120
	v_cvt_pk_bf16_f32 v5, v124, v128
	ds_write_b128 v168, v[2:5]
	v_cvt_pk_bf16_f32 v2, v53, v57
	v_cvt_pk_bf16_f32 v3, v93, v105
	v_cvt_pk_bf16_f32 v4, v117, v121
	v_cvt_pk_bf16_f32 v5, v125, v129
	ds_write_b128 v168, v[2:5] offset:4096
	v_cvt_pk_bf16_f32 v2, v54, v58
	v_cvt_pk_bf16_f32 v3, v94, v106
	v_cvt_pk_bf16_f32 v4, v118, v122
	v_cvt_pk_bf16_f32 v5, v126, v130
	v_cvt_pk_bf16_f32 v133, v34, v42
	v_cvt_pk_bf16_f32 v134, v66, v74
	v_cvt_pk_bf16_f32 v135, v90, v102
	v_cvt_pk_bf16_f32 v9, v28, v36
	v_cvt_pk_bf16_f32 v10, v60, v68
	v_cvt_pk_bf16_f32 v11, v84, v96
	ds_write_b128 v168, v[2:5] offset:8192
	v_cvt_pk_bf16_f32 v2, v55, v59
	v_cvt_pk_bf16_f32 v3, v95, v107
	v_cvt_pk_bf16_f32 v4, v119, v123
	v_cvt_pk_bf16_f32 v5, v127, v131
	s_sub_i32 s4, 0, s24
	ds_write_b128 v165, v[132:135] offset:8192
	ds_write_b128 v166, v[8:11]
	ds_write_b128 v168, v[2:5] offset:12288
	ds_read_b128 v[2:5], v169
	s_add_i32 s4, s4, s14
	v_add_u32_e32 v12, s4, v164
	s_ashr_i32 s1, s0, 31
	v_ashrrev_i32_e32 v13, 31, v12
	v_lshl_add_u64 v[10:11], s[0:1], 1, v[160:161]
	v_lshlrev_b64 v[6:7], 12, v[12:13]
	v_lshl_add_u64 v[14:15], v[10:11], 0, v[6:7]
	ds_read_b128 v[6:9], v170
	s_waitcnt lgkmcnt(0)
	global_store_dwordx4 v[14:15], v[2:5], off
	s_add_i32 s3, s3, s18
	s_add_i32 s14, s14, s15
	v_add_u32_e32 v2, 8, v12
	v_ashrrev_i32_e32 v3, 31, v2
	v_lshlrev_b64 v[2:3], 12, v[2:3]
	v_lshl_add_u64 v[2:3], v[10:11], 0, v[2:3]
	global_store_dwordx4 v[2:3], v[6:9], off
	ds_read_b128 v[2:5], v171
	s_cmpk_lt_i32 s3, 0x200
	v_add_u32_e32 v6, 16, v12
	v_ashrrev_i32_e32 v7, 31, v6
	v_lshlrev_b64 v[6:7], 12, v[6:7]
	v_lshl_add_u64 v[14:15], v[10:11], 0, v[6:7]
	ds_read_b128 v[6:9], v172
	s_waitcnt lgkmcnt(1)
	global_store_dwordx4 v[14:15], v[2:5], off
	s_nop 1
	v_add_u32_e32 v2, 24, v12
	v_ashrrev_i32_e32 v3, 31, v2
	v_lshlrev_b64 v[2:3], 12, v[2:3]
	v_lshl_add_u64 v[2:3], v[10:11], 0, v[2:3]
	s_waitcnt lgkmcnt(0)
	global_store_dwordx4 v[2:3], v[6:9], off
	ds_read_b128 v[2:5], v173
	s_nop 0
	v_add_u32_e32 v6, 32, v12
	v_ashrrev_i32_e32 v7, 31, v6
	v_lshlrev_b64 v[6:7], 12, v[6:7]
	v_lshl_add_u64 v[14:15], v[10:11], 0, v[6:7]
	ds_read_b128 v[6:9], v174
	s_waitcnt lgkmcnt(1)
	global_store_dwordx4 v[14:15], v[2:5], off
	s_nop 1
	v_add_u32_e32 v2, 40, v12
	v_ashrrev_i32_e32 v3, 31, v2
	v_lshlrev_b64 v[2:3], 12, v[2:3]
	v_lshl_add_u64 v[2:3], v[10:11], 0, v[2:3]
	s_waitcnt lgkmcnt(0)
	global_store_dwordx4 v[2:3], v[6:9], off
	ds_read_b128 v[2:5], v175
	s_nop 0
	v_add_u32_e32 v6, 48, v12
	v_ashrrev_i32_e32 v7, 31, v6
	v_lshlrev_b64 v[6:7], 12, v[6:7]
	v_lshl_add_u64 v[14:15], v[10:11], 0, v[6:7]
	ds_read_b128 v[6:9], v176
	s_waitcnt lgkmcnt(1)
	global_store_dwordx4 v[14:15], v[2:5], off
	s_nop 1
	v_add_u32_e32 v2, 56, v12
	v_ashrrev_i32_e32 v3, 31, v2
	v_lshlrev_b64 v[2:3], 12, v[2:3]
	v_lshl_add_u64 v[2:3], v[10:11], 0, v[2:3]
	s_waitcnt lgkmcnt(0)
	global_store_dwordx4 v[2:3], v[6:9], off
	ds_read_b128 v[2:5], v177
	s_nop 0
	v_add_u32_e32 v6, 64, v12
	v_ashrrev_i32_e32 v7, 31, v6
	v_lshlrev_b64 v[6:7], 12, v[6:7]
	v_lshl_add_u64 v[14:15], v[10:11], 0, v[6:7]
	ds_read_b128 v[6:9], v178
	s_waitcnt lgkmcnt(1)
	global_store_dwordx4 v[14:15], v[2:5], off
	s_nop 1
	v_add_u32_e32 v2, 0x48, v12
	v_ashrrev_i32_e32 v3, 31, v2
	v_lshlrev_b64 v[2:3], 12, v[2:3]
	v_lshl_add_u64 v[2:3], v[10:11], 0, v[2:3]
	s_waitcnt lgkmcnt(0)
	global_store_dwordx4 v[2:3], v[6:9], off
	ds_read_b128 v[2:5], v179
	s_nop 0
	v_add_u32_e32 v6, 0x50, v12
	v_ashrrev_i32_e32 v7, 31, v6
	v_lshlrev_b64 v[6:7], 12, v[6:7]
	v_lshl_add_u64 v[14:15], v[10:11], 0, v[6:7]
	ds_read_b128 v[6:9], v185
	s_waitcnt lgkmcnt(1)
	global_store_dwordx4 v[14:15], v[2:5], off
	s_nop 1
	v_add_u32_e32 v2, 0x58, v12
	v_ashrrev_i32_e32 v3, 31, v2
	v_lshlrev_b64 v[2:3], 12, v[2:3]
	v_lshl_add_u64 v[2:3], v[10:11], 0, v[2:3]
	s_waitcnt lgkmcnt(0)
	global_store_dwordx4 v[2:3], v[6:9], off
	ds_read_b128 v[2:5], v190
	s_nop 0
	v_add_u32_e32 v6, 0x60, v12
	v_ashrrev_i32_e32 v7, 31, v6
	v_lshlrev_b64 v[6:7], 12, v[6:7]
	v_lshl_add_u64 v[14:15], v[10:11], 0, v[6:7]
	ds_read_b128 v[6:9], v191
	s_waitcnt lgkmcnt(1)
	global_store_dwordx4 v[14:15], v[2:5], off
	s_nop 1
	v_add_u32_e32 v2, 0x68, v12
	v_ashrrev_i32_e32 v3, 31, v2
	v_lshlrev_b64 v[2:3], 12, v[2:3]
	v_lshl_add_u64 v[2:3], v[10:11], 0, v[2:3]
	s_waitcnt lgkmcnt(0)
	global_store_dwordx4 v[2:3], v[6:9], off
	ds_read_b128 v[2:5], v192
	s_nop 0
	v_add_u32_e32 v6, 0x70, v12
	v_ashrrev_i32_e32 v7, 31, v6
	v_lshlrev_b64 v[6:7], 12, v[6:7]
	v_lshl_add_u64 v[14:15], v[10:11], 0, v[6:7]
	ds_read_b128 v[6:9], v193
	s_waitcnt lgkmcnt(1)
	global_store_dwordx4 v[14:15], v[2:5], off
	s_nop 1
	v_add_u32_e32 v2, 0x78, v12
	v_ashrrev_i32_e32 v3, 31, v2
	v_lshlrev_b64 v[2:3], 12, v[2:3]
	v_lshl_add_u64 v[2:3], v[10:11], 0, v[2:3]
	s_waitcnt lgkmcnt(0)
	global_store_dwordx4 v[2:3], v[6:9], off
	s_cbranch_scc0 .LBB0_592

.LBB0_594:
	s_or_b64 exec, exec, s[4:5]
	s_waitcnt vmcnt(0)
	v_cvt_pk_bf16_f32 v132, v8, v20
	v_cvt_pk_bf16_f32 v133, v32, v40
	v_cvt_pk_bf16_f32 v134, v64, v72
	v_cvt_pk_bf16_f32 v135, v88, v100
	ds_write_b128 v165, v[132:135]
	v_cvt_pk_bf16_f32 v132, v9, v21
	v_cvt_pk_bf16_f32 v133, v33, v41
	v_cvt_pk_bf16_f32 v134, v65, v73
	v_cvt_pk_bf16_f32 v135, v89, v101
	ds_write_b128 v165, v[132:135] offset:4096
	v_cvt_pk_bf16_f32 v132, v10, v22
	v_cvt_pk_bf16_f32 v8, v11, v23
	v_cvt_pk_bf16_f32 v9, v35, v43
	v_cvt_pk_bf16_f32 v10, v67, v75
	v_cvt_pk_bf16_f32 v11, v91, v103
	ds_write_b128 v165, v[8:11] offset:12288
	v_cvt_pk_bf16_f32 v8, v4, v16
	v_cvt_pk_bf16_f32 v2, v5, v17
	v_cvt_pk_bf16_f32 v3, v29, v37
	v_cvt_pk_bf16_f32 v4, v61, v69
	v_cvt_pk_bf16_f32 v5, v85, v97
	ds_write_b128 v166, v[2:5] offset:4096
	v_cvt_pk_bf16_f32 v2, v6, v18
	v_cvt_pk_bf16_f32 v3, v30, v38
	v_cvt_pk_bf16_f32 v4, v62, v70
	v_cvt_pk_bf16_f32 v5, v86, v98
	ds_write_b128 v166, v[2:5] offset:8192
	v_cvt_pk_bf16_f32 v2, v7, v19
	v_cvt_pk_bf16_f32 v3, v31, v39
	v_cvt_pk_bf16_f32 v4, v63, v71
	v_cvt_pk_bf16_f32 v5, v87, v99
	ds_write_b128 v166, v[2:5] offset:12288
	v_cvt_pk_bf16_f32 v2, v12, v24
	v_cvt_pk_bf16_f32 v3, v44, v48
	v_cvt_pk_bf16_f32 v4, v76, v80
	v_cvt_pk_bf16_f32 v5, v108, v112
	ds_write_b128 v167, v[2:5]
	v_cvt_pk_bf16_f32 v2, v13, v25
	v_cvt_pk_bf16_f32 v3, v45, v49
	v_cvt_pk_bf16_f32 v4, v77, v81
	v_cvt_pk_bf16_f32 v5, v109, v113
	ds_write_b128 v167, v[2:5] offset:4096
	v_cvt_pk_bf16_f32 v2, v14, v26
	v_cvt_pk_bf16_f32 v3, v46, v50
	v_cvt_pk_bf16_f32 v4, v78, v82
	v_cvt_pk_bf16_f32 v5, v110, v114
	ds_write_b128 v167, v[2:5] offset:8192
	v_cvt_pk_bf16_f32 v2, v15, v27
	v_cvt_pk_bf16_f32 v3, v47, v51
	v_cvt_pk_bf16_f32 v4, v79, v83
	v_cvt_pk_bf16_f32 v5, v111, v115
	ds_write_b128 v167, v[2:5] offset:12288
	v_cvt_pk_bf16_f32 v2, v52, v56
	v_cvt_pk_bf16_f32 v3, v92, v104
	v_cvt_pk_bf16_f32 v4, v116, v120
	v_cvt_pk_bf16_f32 v5, v124, v128
	ds_write_b128 v168, v[2:5]
	v_cvt_pk_bf16_f32 v2, v53, v57
	v_cvt_pk_bf16_f32 v3, v93, v105
	v_cvt_pk_bf16_f32 v4, v117, v121
	v_cvt_pk_bf16_f32 v5, v125, v129
	ds_write_b128 v168, v[2:5] offset:4096
	v_cvt_pk_bf16_f32 v2, v54, v58
	v_cvt_pk_bf16_f32 v3, v94, v106
	v_cvt_pk_bf16_f32 v4, v118, v122
	v_cvt_pk_bf16_f32 v5, v126, v130
	v_cvt_pk_bf16_f32 v133, v34, v42
	v_cvt_pk_bf16_f32 v134, v66, v74
	v_cvt_pk_bf16_f32 v135, v90, v102
	v_cvt_pk_bf16_f32 v9, v28, v36
	v_cvt_pk_bf16_f32 v10, v60, v68
	v_cvt_pk_bf16_f32 v11, v84, v96
	ds_write_b128 v168, v[2:5] offset:8192
	v_cvt_pk_bf16_f32 v2, v55, v59
	v_cvt_pk_bf16_f32 v3, v95, v107
	v_cvt_pk_bf16_f32 v4, v119, v123
	v_cvt_pk_bf16_f32 v5, v127, v131
	s_sub_i32 s4, 0, s14
	ds_write_b128 v165, v[132:135] offset:8192
	ds_write_b128 v166, v[8:11]
	ds_write_b128 v168, v[2:5] offset:12288
	ds_read_b128 v[2:5], v169
	s_add_i32 s4, s4, s3
	v_add_u32_e32 v12, s4, v164
	s_ashr_i32 s1, s0, 31
	v_ashrrev_i32_e32 v13, 31, v12
	v_lshl_add_u64 v[10:11], s[0:1], 1, v[160:161]
	v_lshlrev_b64 v[6:7], 12, v[12:13]
	v_lshl_add_u64 v[14:15], v[10:11], 0, v[6:7]
	ds_read_b128 v[6:9], v170
	s_waitcnt lgkmcnt(0)
	global_store_dwordx4 v[14:15], v[2:5], off
	s_add_i32 s2, s2, s18
	s_add_i32 s3, s3, s13
	v_add_u32_e32 v2, 8, v12
	v_ashrrev_i32_e32 v3, 31, v2
	v_lshlrev_b64 v[2:3], 12, v[2:3]
	v_lshl_add_u64 v[2:3], v[10:11], 0, v[2:3]
	global_store_dwordx4 v[2:3], v[6:9], off
	ds_read_b128 v[2:5], v171
	s_cmpk_gt_i32 s2, 0x1ff
	v_add_u32_e32 v6, 16, v12
	v_ashrrev_i32_e32 v7, 31, v6
	v_lshlrev_b64 v[6:7], 12, v[6:7]
	v_lshl_add_u64 v[14:15], v[10:11], 0, v[6:7]
	ds_read_b128 v[6:9], v172
	s_waitcnt lgkmcnt(1)
	global_store_dwordx4 v[14:15], v[2:5], off
	s_nop 1
	v_add_u32_e32 v2, 24, v12
	v_ashrrev_i32_e32 v3, 31, v2
	v_lshlrev_b64 v[2:3], 12, v[2:3]
	v_lshl_add_u64 v[2:3], v[10:11], 0, v[2:3]
	s_waitcnt lgkmcnt(0)
	global_store_dwordx4 v[2:3], v[6:9], off
	ds_read_b128 v[2:5], v173
	s_nop 0
	v_add_u32_e32 v6, 32, v12
	v_ashrrev_i32_e32 v7, 31, v6
	v_lshlrev_b64 v[6:7], 12, v[6:7]
	v_lshl_add_u64 v[14:15], v[10:11], 0, v[6:7]
	ds_read_b128 v[6:9], v174
	s_waitcnt lgkmcnt(1)
	global_store_dwordx4 v[14:15], v[2:5], off
	s_nop 1
	v_add_u32_e32 v2, 40, v12
	v_ashrrev_i32_e32 v3, 31, v2
	v_lshlrev_b64 v[2:3], 12, v[2:3]
	v_lshl_add_u64 v[2:3], v[10:11], 0, v[2:3]
	s_waitcnt lgkmcnt(0)
	global_store_dwordx4 v[2:3], v[6:9], off
	ds_read_b128 v[2:5], v175
	s_nop 0
	v_add_u32_e32 v6, 48, v12
	v_ashrrev_i32_e32 v7, 31, v6
	v_lshlrev_b64 v[6:7], 12, v[6:7]
	v_lshl_add_u64 v[14:15], v[10:11], 0, v[6:7]
	ds_read_b128 v[6:9], v176
	s_waitcnt lgkmcnt(1)
	global_store_dwordx4 v[14:15], v[2:5], off
	s_nop 1
	v_add_u32_e32 v2, 56, v12
	v_ashrrev_i32_e32 v3, 31, v2
	v_lshlrev_b64 v[2:3], 12, v[2:3]
	v_lshl_add_u64 v[2:3], v[10:11], 0, v[2:3]
	s_waitcnt lgkmcnt(0)
	global_store_dwordx4 v[2:3], v[6:9], off
	ds_read_b128 v[2:5], v177
	s_nop 0
	v_add_u32_e32 v6, 64, v12
	v_ashrrev_i32_e32 v7, 31, v6
	v_lshlrev_b64 v[6:7], 12, v[6:7]
	v_lshl_add_u64 v[14:15], v[10:11], 0, v[6:7]
	ds_read_b128 v[6:9], v178
	s_waitcnt lgkmcnt(1)
	global_store_dwordx4 v[14:15], v[2:5], off
	s_nop 1
	v_add_u32_e32 v2, 0x48, v12
	v_ashrrev_i32_e32 v3, 31, v2
	v_lshlrev_b64 v[2:3], 12, v[2:3]
	v_lshl_add_u64 v[2:3], v[10:11], 0, v[2:3]
	s_waitcnt lgkmcnt(0)
	global_store_dwordx4 v[2:3], v[6:9], off
	ds_read_b128 v[2:5], v179
	s_nop 0
	v_add_u32_e32 v6, 0x50, v12
	v_ashrrev_i32_e32 v7, 31, v6
	v_lshlrev_b64 v[6:7], 12, v[6:7]
	v_lshl_add_u64 v[14:15], v[10:11], 0, v[6:7]
	ds_read_b128 v[6:9], v185
	s_waitcnt lgkmcnt(1)
	global_store_dwordx4 v[14:15], v[2:5], off
	s_nop 1
	v_add_u32_e32 v2, 0x58, v12
	v_ashrrev_i32_e32 v3, 31, v2
	v_lshlrev_b64 v[2:3], 12, v[2:3]
	v_lshl_add_u64 v[2:3], v[10:11], 0, v[2:3]
	s_waitcnt lgkmcnt(0)
	global_store_dwordx4 v[2:3], v[6:9], off
	ds_read_b128 v[2:5], v190
	s_nop 0
	v_add_u32_e32 v6, 0x60, v12
	v_ashrrev_i32_e32 v7, 31, v6
	v_lshlrev_b64 v[6:7], 12, v[6:7]
	v_lshl_add_u64 v[14:15], v[10:11], 0, v[6:7]
	ds_read_b128 v[6:9], v191
	s_waitcnt lgkmcnt(1)
	global_store_dwordx4 v[14:15], v[2:5], off
	s_nop 1
	v_add_u32_e32 v2, 0x68, v12
	v_ashrrev_i32_e32 v3, 31, v2
	v_lshlrev_b64 v[2:3], 12, v[2:3]
	v_lshl_add_u64 v[2:3], v[10:11], 0, v[2:3]
	s_waitcnt lgkmcnt(0)
	global_store_dwordx4 v[2:3], v[6:9], off
	ds_read_b128 v[2:5], v192
	s_nop 0
	v_add_u32_e32 v6, 0x70, v12
	v_ashrrev_i32_e32 v7, 31, v6
	v_lshlrev_b64 v[6:7], 12, v[6:7]
	v_lshl_add_u64 v[14:15], v[10:11], 0, v[6:7]
	ds_read_b128 v[6:9], v193
	s_waitcnt lgkmcnt(1)
	global_store_dwordx4 v[14:15], v[2:5], off
	s_nop 1
	v_add_u32_e32 v2, 0x78, v12
	v_ashrrev_i32_e32 v3, 31, v2
	v_lshlrev_b64 v[2:3], 12, v[2:3]
	v_lshl_add_u64 v[2:3], v[10:11], 0, v[2:3]
	s_waitcnt lgkmcnt(0)
	global_store_dwordx4 v[2:3], v[6:9], off
	s_cbranch_scc1 .LBB0_599

.LBB0_636:
	s_or_b64 exec, exec, s[4:5]
	s_waitcnt vmcnt(0)
	v_cvt_pk_bf16_f32 v130, v2, v6
	v_cvt_pk_bf16_f32 v131, v10, v14
	v_cvt_pk_bf16_f32 v132, v126, v122
	v_cvt_pk_bf16_f32 v133, v118, v114
	v_add_u32_e32 v1, v169, v168
	ds_write_b128 v1, v[130:133]
	v_cvt_pk_bf16_f32 v130, v3, v7
	v_cvt_pk_bf16_f32 v131, v11, v15
	v_cvt_pk_bf16_f32 v132, v127, v123
	v_cvt_pk_bf16_f32 v133, v119, v115
	ds_write_b128 v1, v[130:133] offset:4096
	v_cvt_pk_bf16_f32 v130, v4, v8
	v_cvt_pk_bf16_f32 v131, v12, v16
	v_cvt_pk_bf16_f32 v132, v128, v124
	v_cvt_pk_bf16_f32 v133, v120, v116
	v_cvt_pk_bf16_f32 v2, v5, v9
	v_cvt_pk_bf16_f32 v3, v13, v17
	v_cvt_pk_bf16_f32 v4, v129, v125
	v_cvt_pk_bf16_f32 v5, v121, v117
	ds_write_b128 v1, v[130:133] offset:8192
	ds_write_b128 v1, v[2:5] offset:12288
	v_cvt_pk_bf16_f32 v2, v110, v106
	v_cvt_pk_bf16_f32 v3, v102, v98
	v_cvt_pk_bf16_f32 v4, v94, v90
	v_cvt_pk_bf16_f32 v5, v86, v82
	v_add_u32_e32 v1, v169, v170
	ds_write_b128 v1, v[2:5]
	v_cvt_pk_bf16_f32 v2, v111, v107
	v_cvt_pk_bf16_f32 v3, v103, v99
	v_cvt_pk_bf16_f32 v4, v95, v91
	v_cvt_pk_bf16_f32 v5, v87, v83
	ds_write_b128 v1, v[2:5] offset:4096
	v_cvt_pk_bf16_f32 v2, v112, v108
	v_cvt_pk_bf16_f32 v3, v104, v100
	v_cvt_pk_bf16_f32 v4, v96, v92
	v_cvt_pk_bf16_f32 v5, v88, v84
	ds_write_b128 v1, v[2:5] offset:8192
	v_cvt_pk_bf16_f32 v2, v113, v109
	v_cvt_pk_bf16_f32 v3, v105, v101
	v_cvt_pk_bf16_f32 v4, v97, v93
	v_cvt_pk_bf16_f32 v5, v89, v85
	ds_write_b128 v1, v[2:5] offset:12288
	v_cvt_pk_bf16_f32 v2, v78, v74
	v_cvt_pk_bf16_f32 v3, v70, v66
	v_cvt_pk_bf16_f32 v4, v62, v58
	v_cvt_pk_bf16_f32 v5, v54, v50
	v_add_u32_e32 v1, v169, v171
	ds_write_b128 v1, v[2:5]
	v_cvt_pk_bf16_f32 v2, v79, v75
	v_cvt_pk_bf16_f32 v3, v71, v67
	v_cvt_pk_bf16_f32 v4, v63, v59
	v_cvt_pk_bf16_f32 v5, v55, v51
	ds_write_b128 v1, v[2:5] offset:4096
	v_cvt_pk_bf16_f32 v2, v80, v76
	v_cvt_pk_bf16_f32 v3, v72, v68
	v_cvt_pk_bf16_f32 v4, v64, v60
	v_cvt_pk_bf16_f32 v5, v56, v52
	ds_write_b128 v1, v[2:5] offset:8192
	v_cvt_pk_bf16_f32 v2, v81, v77
	v_cvt_pk_bf16_f32 v3, v73, v69
	v_cvt_pk_bf16_f32 v4, v65, v61
	v_cvt_pk_bf16_f32 v5, v57, v53
	ds_write_b128 v1, v[2:5] offset:12288
	v_cvt_pk_bf16_f32 v2, v46, v42
	v_cvt_pk_bf16_f32 v3, v38, v34
	v_cvt_pk_bf16_f32 v4, v30, v26
	v_cvt_pk_bf16_f32 v5, v22, v18
	v_add_u32_e32 v1, v169, v172
	ds_write_b128 v1, v[2:5]
	v_cvt_pk_bf16_f32 v2, v47, v43
	v_cvt_pk_bf16_f32 v3, v39, v35
	v_cvt_pk_bf16_f32 v4, v31, v27
	v_cvt_pk_bf16_f32 v5, v23, v19
	ds_write_b128 v1, v[2:5] offset:4096
	v_cvt_pk_bf16_f32 v2, v48, v44
	v_cvt_pk_bf16_f32 v3, v40, v36
	v_cvt_pk_bf16_f32 v4, v32, v28
	v_cvt_pk_bf16_f32 v5, v24, v20
	ds_write_b128 v1, v[2:5] offset:8192
	v_cvt_pk_bf16_f32 v2, v49, v45
	v_cvt_pk_bf16_f32 v3, v41, v37
	v_cvt_pk_bf16_f32 v4, v33, v29
	v_cvt_pk_bf16_f32 v5, v25, v21
	ds_write_b128 v1, v[2:5] offset:12288
	v_add_u32_e32 v1, v174, v173
	ds_read_b128 v[2:5], v1
	v_add_u32_e32 v12, s46, v165
	s_ashr_i32 s15, s14, 31
	v_ashrrev_i32_e32 v13, 31, v12
	v_lshl_add_u64 v[10:11], s[14:15], 1, v[158:159]
	v_lshlrev_b64 v[6:7], 12, v[12:13]
	v_add_u32_e32 v1, v176, v175
	v_lshl_add_u64 v[14:15], v[10:11], 0, v[6:7]
	ds_read_b128 v[6:9], v1
	s_waitcnt lgkmcnt(0)
	global_store_dwordx4 v[14:15], v[2:5], off
	v_add_u32_e32 v1, v178, v177
	s_add_i32 s2, s2, s44
	v_add_u32_e32 v2, 8, v12
	v_ashrrev_i32_e32 v3, 31, v2
	v_lshlrev_b64 v[2:3], 12, v[2:3]
	v_lshl_add_u64 v[2:3], v[10:11], 0, v[2:3]
	global_store_dwordx4 v[2:3], v[6:9], off
	ds_read_b128 v[2:5], v1
	v_add_u32_e32 v1, v185, v179
	v_add_u32_e32 v6, 16, v12
	v_ashrrev_i32_e32 v7, 31, v6
	v_lshlrev_b64 v[6:7], 12, v[6:7]
	v_lshl_add_u64 v[14:15], v[10:11], 0, v[6:7]
	ds_read_b128 v[6:9], v1
	s_waitcnt lgkmcnt(1)
	global_store_dwordx4 v[14:15], v[2:5], off
	v_add_u32_e32 v1, v190, v173
	v_add_u32_e32 v165, s30, v165
	v_add_u32_e32 v2, 24, v12
	v_ashrrev_i32_e32 v3, 31, v2
	v_lshlrev_b64 v[2:3], 12, v[2:3]
	v_lshl_add_u64 v[2:3], v[10:11], 0, v[2:3]
	s_waitcnt lgkmcnt(0)
	global_store_dwordx4 v[2:3], v[6:9], off
	ds_read_b128 v[2:5], v1
	v_add_u32_e32 v1, v192, v191
	v_add_u32_e32 v6, 32, v12
	v_ashrrev_i32_e32 v7, 31, v6
	v_lshlrev_b64 v[6:7], 12, v[6:7]
	v_lshl_add_u64 v[14:15], v[10:11], 0, v[6:7]
	ds_read_b128 v[6:9], v1
	s_waitcnt lgkmcnt(1)
	global_store_dwordx4 v[14:15], v[2:5], off
	v_add_u32_e32 v1, v194, v193
	s_cmpk_lt_i32 s2, 0x140
	v_add_u32_e32 v2, 40, v12
	v_ashrrev_i32_e32 v3, 31, v2
	v_lshlrev_b64 v[2:3], 12, v[2:3]
	v_lshl_add_u64 v[2:3], v[10:11], 0, v[2:3]
	s_waitcnt lgkmcnt(0)
	global_store_dwordx4 v[2:3], v[6:9], off
	ds_read_b128 v[2:5], v1
	v_add_u32_e32 v1, v196, v195
	v_add_u32_e32 v6, 48, v12
	v_ashrrev_i32_e32 v7, 31, v6
	v_lshlrev_b64 v[6:7], 12, v[6:7]
	v_lshl_add_u64 v[14:15], v[10:11], 0, v[6:7]
	ds_read_b128 v[6:9], v1
	s_waitcnt lgkmcnt(1)
	global_store_dwordx4 v[14:15], v[2:5], off
	v_add_u32_e32 v1, v197, v173
	v_add_u32_e32 v164, s30, v164
	v_add_u32_e32 v2, 56, v12
	v_ashrrev_i32_e32 v3, 31, v2
	v_lshlrev_b64 v[2:3], 12, v[2:3]
	v_lshl_add_u64 v[2:3], v[10:11], 0, v[2:3]
	s_waitcnt lgkmcnt(0)
	global_store_dwordx4 v[2:3], v[6:9], off
	ds_read_b128 v[2:5], v1
	v_add_u32_e32 v1, v199, v198
	v_add_u32_e32 v6, 64, v12
	v_ashrrev_i32_e32 v7, 31, v6
	v_lshlrev_b64 v[6:7], 12, v[6:7]
	v_lshl_add_u64 v[14:15], v[10:11], 0, v[6:7]
	ds_read_b128 v[6:9], v1
	s_waitcnt lgkmcnt(1)
	global_store_dwordx4 v[14:15], v[2:5], off
	v_add_u32_e32 v1, v201, v200
	s_nop 0
	v_add_u32_e32 v2, 0x48, v12
	v_ashrrev_i32_e32 v3, 31, v2
	v_lshlrev_b64 v[2:3], 12, v[2:3]
	v_lshl_add_u64 v[2:3], v[10:11], 0, v[2:3]
	s_waitcnt lgkmcnt(0)
	global_store_dwordx4 v[2:3], v[6:9], off
	ds_read_b128 v[2:5], v1
	v_add_u32_e32 v1, v203, v202
	v_add_u32_e32 v6, 0x50, v12
	v_ashrrev_i32_e32 v7, 31, v6
	v_lshlrev_b64 v[6:7], 12, v[6:7]
	v_lshl_add_u64 v[14:15], v[10:11], 0, v[6:7]
	ds_read_b128 v[6:9], v1
	s_waitcnt lgkmcnt(1)
	global_store_dwordx4 v[14:15], v[2:5], off
	v_add_u32_e32 v1, v204, v173
	s_nop 0
	v_add_u32_e32 v2, 0x58, v12
	v_ashrrev_i32_e32 v3, 31, v2
	v_lshlrev_b64 v[2:3], 12, v[2:3]
	v_lshl_add_u64 v[2:3], v[10:11], 0, v[2:3]
	s_waitcnt lgkmcnt(0)
	global_store_dwordx4 v[2:3], v[6:9], off
	ds_read_b128 v[2:5], v1
	v_add_u32_e32 v1, v206, v205
	v_add_u32_e32 v6, 0x60, v12
	v_ashrrev_i32_e32 v7, 31, v6
	v_lshlrev_b64 v[6:7], 12, v[6:7]
	v_lshl_add_u64 v[14:15], v[10:11], 0, v[6:7]
	ds_read_b128 v[6:9], v1
	s_waitcnt lgkmcnt(1)
	global_store_dwordx4 v[14:15], v[2:5], off
	v_add_u32_e32 v1, v208, v207
	s_nop 0
	v_add_u32_e32 v2, 0x68, v12
	v_ashrrev_i32_e32 v3, 31, v2
	v_lshlrev_b64 v[2:3], 12, v[2:3]
	v_lshl_add_u64 v[2:3], v[10:11], 0, v[2:3]
	s_waitcnt lgkmcnt(0)
	global_store_dwordx4 v[2:3], v[6:9], off
	ds_read_b128 v[2:5], v1
	v_add_u32_e32 v1, v210, v209
	v_add_u32_e32 v6, 0x70, v12
	v_ashrrev_i32_e32 v7, 31, v6
	v_lshlrev_b64 v[6:7], 12, v[6:7]
	v_lshl_add_u64 v[14:15], v[10:11], 0, v[6:7]
	ds_read_b128 v[6:9], v1
	s_waitcnt lgkmcnt(1)
	global_store_dwordx4 v[14:15], v[2:5], off
	s_nop 1
	v_add_u32_e32 v2, 0x78, v12
	v_ashrrev_i32_e32 v3, 31, v2
	v_lshlrev_b64 v[2:3], 12, v[2:3]
	v_lshl_add_u64 v[2:3], v[10:11], 0, v[2:3]
	s_waitcnt lgkmcnt(0)
	global_store_dwordx4 v[2:3], v[6:9], off
	s_cbranch_scc0 .LBB0_641

.LBB0_643:
	s_or_b64 exec, exec, s[4:5]
	s_waitcnt vmcnt(0)
	v_cvt_pk_bf16_f32 v130, v2, v6
	v_cvt_pk_bf16_f32 v131, v26, v30
	v_cvt_pk_bf16_f32 v132, v58, v62
	v_cvt_pk_bf16_f32 v133, v86, v94
	v_add_u32_e32 v1, v169, v168
	ds_write_b128 v1, v[130:133]
	v_cvt_pk_bf16_f32 v130, v3, v7
	v_cvt_pk_bf16_f32 v131, v27, v31
	v_cvt_pk_bf16_f32 v132, v59, v63
	v_cvt_pk_bf16_f32 v133, v87, v95
	ds_write_b128 v1, v[130:133] offset:4096
	v_cvt_pk_bf16_f32 v130, v4, v8
	v_cvt_pk_bf16_f32 v131, v28, v32
	v_cvt_pk_bf16_f32 v132, v60, v64
	v_cvt_pk_bf16_f32 v133, v88, v96
	v_cvt_pk_bf16_f32 v2, v5, v9
	v_cvt_pk_bf16_f32 v3, v29, v33
	v_cvt_pk_bf16_f32 v4, v61, v65
	v_cvt_pk_bf16_f32 v5, v89, v97
	ds_write_b128 v1, v[130:133] offset:8192
	ds_write_b128 v1, v[2:5] offset:12288
	v_cvt_pk_bf16_f32 v2, v10, v14
	v_cvt_pk_bf16_f32 v3, v34, v42
	v_cvt_pk_bf16_f32 v4, v66, v70
	v_cvt_pk_bf16_f32 v5, v98, v102
	v_add_u32_e32 v1, v169, v170
	ds_write_b128 v1, v[2:5]
	v_cvt_pk_bf16_f32 v2, v11, v15
	v_cvt_pk_bf16_f32 v3, v35, v43
	v_cvt_pk_bf16_f32 v4, v67, v71
	v_cvt_pk_bf16_f32 v5, v99, v103
	ds_write_b128 v1, v[2:5] offset:4096
	v_cvt_pk_bf16_f32 v2, v12, v16
	v_cvt_pk_bf16_f32 v3, v36, v44
	v_cvt_pk_bf16_f32 v4, v68, v72
	v_cvt_pk_bf16_f32 v5, v100, v104
	ds_write_b128 v1, v[2:5] offset:8192
	v_cvt_pk_bf16_f32 v2, v13, v17
	v_cvt_pk_bf16_f32 v3, v37, v45
	v_cvt_pk_bf16_f32 v4, v69, v73
	v_cvt_pk_bf16_f32 v5, v101, v105
	ds_write_b128 v1, v[2:5] offset:12288
	v_cvt_pk_bf16_f32 v2, v18, v22
	v_cvt_pk_bf16_f32 v3, v50, v54
	v_cvt_pk_bf16_f32 v4, v74, v82
	v_cvt_pk_bf16_f32 v5, v106, v110
	v_add_u32_e32 v1, v169, v171
	ds_write_b128 v1, v[2:5]
	v_cvt_pk_bf16_f32 v2, v19, v23
	v_cvt_pk_bf16_f32 v3, v51, v55
	v_cvt_pk_bf16_f32 v4, v75, v83
	v_cvt_pk_bf16_f32 v5, v107, v111
	ds_write_b128 v1, v[2:5] offset:4096
	v_cvt_pk_bf16_f32 v2, v20, v24
	v_cvt_pk_bf16_f32 v3, v52, v56
	v_cvt_pk_bf16_f32 v4, v76, v84
	v_cvt_pk_bf16_f32 v5, v108, v112
	ds_write_b128 v1, v[2:5] offset:8192
	v_cvt_pk_bf16_f32 v2, v21, v25
	v_cvt_pk_bf16_f32 v3, v53, v57
	v_cvt_pk_bf16_f32 v4, v77, v85
	v_cvt_pk_bf16_f32 v5, v109, v113
	ds_write_b128 v1, v[2:5] offset:12288
	v_cvt_pk_bf16_f32 v2, v38, v46
	v_cvt_pk_bf16_f32 v3, v78, v90
	v_cvt_pk_bf16_f32 v4, v114, v118
	v_cvt_pk_bf16_f32 v5, v122, v126
	v_add_u32_e32 v1, v169, v172
	ds_write_b128 v1, v[2:5]
	v_cvt_pk_bf16_f32 v2, v39, v47
	v_cvt_pk_bf16_f32 v3, v79, v91
	v_cvt_pk_bf16_f32 v4, v115, v119
	v_cvt_pk_bf16_f32 v5, v123, v127
	ds_write_b128 v1, v[2:5] offset:4096
	v_cvt_pk_bf16_f32 v2, v40, v48
	v_cvt_pk_bf16_f32 v3, v80, v92
	v_cvt_pk_bf16_f32 v4, v116, v120
	v_cvt_pk_bf16_f32 v5, v124, v128
	ds_write_b128 v1, v[2:5] offset:8192
	v_cvt_pk_bf16_f32 v2, v41, v49
	v_cvt_pk_bf16_f32 v3, v81, v93
	v_cvt_pk_bf16_f32 v4, v117, v121
	v_cvt_pk_bf16_f32 v5, v125, v129
	ds_write_b128 v1, v[2:5] offset:12288
	v_add_u32_e32 v1, v174, v173
	ds_read_b128 v[2:5], v1
	v_add_u32_e32 v12, s88, v165
	s_ashr_i32 s25, s24, 31
	v_ashrrev_i32_e32 v13, 31, v12
	v_lshl_add_u64 v[10:11], s[24:25], 1, v[158:159]
	v_lshlrev_b64 v[6:7], 10, v[12:13]
	v_add_u32_e32 v1, v176, v175
	v_lshl_add_u64 v[14:15], v[10:11], 0, v[6:7]
	ds_read_b128 v[6:9], v1
	s_waitcnt lgkmcnt(0)
	global_store_dwordx4 v[14:15], v[2:5], off
	v_add_u32_e32 v1, v178, v177
	s_add_i32 s2, s2, s44
	v_add_u32_e32 v2, 8, v12
	v_ashrrev_i32_e32 v3, 31, v2
	v_lshlrev_b64 v[2:3], 10, v[2:3]
	v_lshl_add_u64 v[2:3], v[10:11], 0, v[2:3]
	global_store_dwordx4 v[2:3], v[6:9], off
	ds_read_b128 v[2:5], v1
	v_add_u32_e32 v1, v185, v179
	v_add_u32_e32 v6, 16, v12
	v_ashrrev_i32_e32 v7, 31, v6
	v_lshlrev_b64 v[6:7], 10, v[6:7]
	v_lshl_add_u64 v[14:15], v[10:11], 0, v[6:7]
	ds_read_b128 v[6:9], v1
	s_waitcnt lgkmcnt(1)
	global_store_dwordx4 v[14:15], v[2:5], off
	v_add_u32_e32 v1, v190, v173
	v_add_u32_e32 v165, s47, v165
	v_add_u32_e32 v2, 24, v12
	v_ashrrev_i32_e32 v3, 31, v2
	v_lshlrev_b64 v[2:3], 10, v[2:3]
	v_lshl_add_u64 v[2:3], v[10:11], 0, v[2:3]
	s_waitcnt lgkmcnt(0)
	global_store_dwordx4 v[2:3], v[6:9], off
	ds_read_b128 v[2:5], v1
	v_add_u32_e32 v1, v192, v191
	v_add_u32_e32 v6, 32, v12
	v_ashrrev_i32_e32 v7, 31, v6
	v_lshlrev_b64 v[6:7], 10, v[6:7]
	v_lshl_add_u64 v[14:15], v[10:11], 0, v[6:7]
	ds_read_b128 v[6:9], v1
	s_waitcnt lgkmcnt(1)
	global_store_dwordx4 v[14:15], v[2:5], off
	v_add_u32_e32 v1, v194, v193
	s_cmpk_lt_i32 s2, 0xc0
	v_add_u32_e32 v2, 40, v12
	v_ashrrev_i32_e32 v3, 31, v2
	v_lshlrev_b64 v[2:3], 10, v[2:3]
	v_lshl_add_u64 v[2:3], v[10:11], 0, v[2:3]
	s_waitcnt lgkmcnt(0)
	global_store_dwordx4 v[2:3], v[6:9], off
	ds_read_b128 v[2:5], v1
	v_add_u32_e32 v1, v196, v195
	v_add_u32_e32 v6, 48, v12
	v_ashrrev_i32_e32 v7, 31, v6
	v_lshlrev_b64 v[6:7], 10, v[6:7]
	v_lshl_add_u64 v[14:15], v[10:11], 0, v[6:7]
	ds_read_b128 v[6:9], v1
	s_waitcnt lgkmcnt(1)
	global_store_dwordx4 v[14:15], v[2:5], off
	v_add_u32_e32 v1, v197, v173
	v_add_u32_e32 v164, s47, v164
	v_add_u32_e32 v2, 56, v12
	v_ashrrev_i32_e32 v3, 31, v2
	v_lshlrev_b64 v[2:3], 10, v[2:3]
	v_lshl_add_u64 v[2:3], v[10:11], 0, v[2:3]
	s_waitcnt lgkmcnt(0)
	global_store_dwordx4 v[2:3], v[6:9], off
	ds_read_b128 v[2:5], v1
	v_add_u32_e32 v1, v199, v198
	v_add_u32_e32 v6, 64, v12
	v_ashrrev_i32_e32 v7, 31, v6
	v_lshlrev_b64 v[6:7], 10, v[6:7]
	v_lshl_add_u64 v[14:15], v[10:11], 0, v[6:7]
	ds_read_b128 v[6:9], v1
	s_waitcnt lgkmcnt(1)
	global_store_dwordx4 v[14:15], v[2:5], off
	v_add_u32_e32 v1, v201, v200
	s_nop 0
	v_add_u32_e32 v2, 0x48, v12
	v_ashrrev_i32_e32 v3, 31, v2
	v_lshlrev_b64 v[2:3], 10, v[2:3]
	v_lshl_add_u64 v[2:3], v[10:11], 0, v[2:3]
	s_waitcnt lgkmcnt(0)
	global_store_dwordx4 v[2:3], v[6:9], off
	ds_read_b128 v[2:5], v1
	v_add_u32_e32 v1, v203, v202
	v_add_u32_e32 v6, 0x50, v12
	v_ashrrev_i32_e32 v7, 31, v6
	v_lshlrev_b64 v[6:7], 10, v[6:7]
	v_lshl_add_u64 v[14:15], v[10:11], 0, v[6:7]
	ds_read_b128 v[6:9], v1
	s_waitcnt lgkmcnt(1)
	global_store_dwordx4 v[14:15], v[2:5], off
	v_add_u32_e32 v1, v204, v173
	s_nop 0
	v_add_u32_e32 v2, 0x58, v12
	v_ashrrev_i32_e32 v3, 31, v2
	v_lshlrev_b64 v[2:3], 10, v[2:3]
	v_lshl_add_u64 v[2:3], v[10:11], 0, v[2:3]
	s_waitcnt lgkmcnt(0)
	global_store_dwordx4 v[2:3], v[6:9], off
	ds_read_b128 v[2:5], v1
	v_add_u32_e32 v1, v206, v205
	v_add_u32_e32 v6, 0x60, v12
	v_ashrrev_i32_e32 v7, 31, v6
	v_lshlrev_b64 v[6:7], 10, v[6:7]
	v_lshl_add_u64 v[14:15], v[10:11], 0, v[6:7]
	ds_read_b128 v[6:9], v1
	s_waitcnt lgkmcnt(1)
	global_store_dwordx4 v[14:15], v[2:5], off
	v_add_u32_e32 v1, v208, v207
	s_nop 0
	v_add_u32_e32 v2, 0x68, v12
	v_ashrrev_i32_e32 v3, 31, v2
	v_lshlrev_b64 v[2:3], 10, v[2:3]
	v_lshl_add_u64 v[2:3], v[10:11], 0, v[2:3]
	s_waitcnt lgkmcnt(0)
	global_store_dwordx4 v[2:3], v[6:9], off
	ds_read_b128 v[2:5], v1
	v_add_u32_e32 v1, v210, v209
	v_add_u32_e32 v6, 0x70, v12
	v_ashrrev_i32_e32 v7, 31, v6
	v_lshlrev_b64 v[6:7], 10, v[6:7]
	v_lshl_add_u64 v[14:15], v[10:11], 0, v[6:7]
	ds_read_b128 v[6:9], v1
	s_waitcnt lgkmcnt(1)
	global_store_dwordx4 v[14:15], v[2:5], off
	s_nop 1
	v_add_u32_e32 v2, 0x78, v12
	v_ashrrev_i32_e32 v3, 31, v2
	v_lshlrev_b64 v[2:3], 10, v[2:3]
	v_lshl_add_u64 v[2:3], v[10:11], 0, v[2:3]
	s_waitcnt lgkmcnt(0)
	global_store_dwordx4 v[2:3], v[6:9], off
	s_cbranch_scc0 .LBB0_648

.LBB0_651:
	s_or_b64 exec, exec, s[4:5]
	s_waitcnt vmcnt(0)
	v_cvt_pk_bf16_f32 v132, v12, v24
	v_cvt_pk_bf16_f32 v133, v32, v44
	v_cvt_pk_bf16_f32 v134, v64, v72
	v_cvt_pk_bf16_f32 v135, v92, v104
	v_add_u32_e32 v1, v169, v168
	ds_write_b128 v1, v[132:135]
	v_cvt_pk_bf16_f32 v132, v13, v25
	v_cvt_pk_bf16_f32 v133, v33, v45
	v_cvt_pk_bf16_f32 v134, v65, v73
	v_cvt_pk_bf16_f32 v135, v93, v105
	ds_write_b128 v1, v[132:135] offset:4096
	v_cvt_pk_bf16_f32 v132, v14, v26
	v_cvt_pk_bf16_f32 v133, v34, v46
	v_cvt_pk_bf16_f32 v134, v66, v74
	v_cvt_pk_bf16_f32 v135, v94, v106
	v_cvt_pk_bf16_f32 v12, v15, v27
	v_cvt_pk_bf16_f32 v13, v35, v47
	v_cvt_pk_bf16_f32 v14, v67, v75
	v_cvt_pk_bf16_f32 v15, v95, v107
	ds_write_b128 v1, v[132:135] offset:8192
	ds_write_b128 v1, v[12:15] offset:12288
	v_cvt_pk_bf16_f32 v12, v4, v16
	v_add_u32_e32 v1, v169, v170
	v_cvt_pk_bf16_f32 v2, v5, v17
	v_cvt_pk_bf16_f32 v3, v29, v41
	v_cvt_pk_bf16_f32 v4, v61, v69
	v_cvt_pk_bf16_f32 v5, v89, v101
	ds_write_b128 v1, v[2:5] offset:4096
	v_cvt_pk_bf16_f32 v2, v6, v18
	v_cvt_pk_bf16_f32 v3, v30, v42
	v_cvt_pk_bf16_f32 v4, v62, v70
	v_cvt_pk_bf16_f32 v5, v90, v102
	v_cvt_pk_bf16_f32 v13, v28, v40
	v_cvt_pk_bf16_f32 v14, v60, v68
	v_cvt_pk_bf16_f32 v15, v88, v100
	ds_write_b128 v1, v[2:5] offset:8192
	v_cvt_pk_bf16_f32 v2, v7, v19
	v_cvt_pk_bf16_f32 v3, v31, v43
	v_cvt_pk_bf16_f32 v4, v63, v71
	v_cvt_pk_bf16_f32 v5, v91, v103
	ds_write_b128 v1, v[12:15]
	ds_write_b128 v1, v[2:5] offset:12288
	v_cvt_pk_bf16_f32 v2, v8, v20
	v_cvt_pk_bf16_f32 v3, v36, v52
	v_cvt_pk_bf16_f32 v4, v76, v80
	v_cvt_pk_bf16_f32 v5, v108, v112
	v_add_u32_e32 v1, v169, v171
	ds_write_b128 v1, v[2:5]
	v_cvt_pk_bf16_f32 v2, v9, v21
	v_cvt_pk_bf16_f32 v3, v37, v53
	v_cvt_pk_bf16_f32 v4, v77, v81
	v_cvt_pk_bf16_f32 v5, v109, v113
	ds_write_b128 v1, v[2:5] offset:4096
	v_cvt_pk_bf16_f32 v2, v10, v22
	v_cvt_pk_bf16_f32 v3, v38, v54
	v_cvt_pk_bf16_f32 v4, v78, v82
	v_cvt_pk_bf16_f32 v5, v110, v114
	ds_write_b128 v1, v[2:5] offset:8192
	v_cvt_pk_bf16_f32 v2, v11, v23
	v_cvt_pk_bf16_f32 v3, v39, v55
	v_cvt_pk_bf16_f32 v4, v79, v83
	v_cvt_pk_bf16_f32 v5, v111, v115
	ds_write_b128 v1, v[2:5] offset:12288
	v_cvt_pk_bf16_f32 v2, v48, v56
	v_cvt_pk_bf16_f32 v3, v84, v96
	v_cvt_pk_bf16_f32 v4, v116, v120
	v_cvt_pk_bf16_f32 v5, v124, v128
	v_add_u32_e32 v1, v169, v172
	ds_write_b128 v1, v[2:5]
	v_cvt_pk_bf16_f32 v2, v49, v57
	v_cvt_pk_bf16_f32 v3, v85, v97
	v_cvt_pk_bf16_f32 v4, v117, v121
	v_cvt_pk_bf16_f32 v5, v125, v129
	ds_write_b128 v1, v[2:5] offset:4096
	v_cvt_pk_bf16_f32 v2, v50, v58
	v_cvt_pk_bf16_f32 v3, v86, v98
	v_cvt_pk_bf16_f32 v4, v118, v122
	v_cvt_pk_bf16_f32 v5, v126, v130
	ds_write_b128 v1, v[2:5] offset:8192
	v_cvt_pk_bf16_f32 v2, v51, v59
	v_cvt_pk_bf16_f32 v3, v87, v99
	v_cvt_pk_bf16_f32 v4, v119, v123
	v_cvt_pk_bf16_f32 v5, v127, v131
	s_sub_i32 s4, 0, s47
	ds_write_b128 v1, v[2:5] offset:12288
	v_add_u32_e32 v1, v174, v173
	ds_read_b128 v[2:5], v1
	s_add_i32 s4, s4, s3
	v_add_u32_e32 v12, s4, v214
	s_ashr_i32 s15, s14, 31
	v_ashrrev_i32_e32 v13, 31, v12
	v_lshl_add_u64 v[10:11], s[14:15], 1, v[164:165]
	v_lshlrev_b64 v[6:7], 10, v[12:13]
	v_add_u32_e32 v1, v176, v175
	v_lshl_add_u64 v[14:15], v[10:11], 0, v[6:7]
	ds_read_b128 v[6:9], v1
	s_waitcnt lgkmcnt(0)
	global_store_dwordx4 v[14:15], v[2:5], off
	v_add_u32_e32 v1, v178, v177
	s_add_i32 s2, s2, s44
	v_add_u32_e32 v2, 8, v12
	v_ashrrev_i32_e32 v3, 31, v2
	v_lshlrev_b64 v[2:3], 10, v[2:3]
	v_lshl_add_u64 v[2:3], v[10:11], 0, v[2:3]
	global_store_dwordx4 v[2:3], v[6:9], off
	ds_read_b128 v[2:5], v1
	v_add_u32_e32 v1, v185, v179
	v_add_u32_e32 v6, 16, v12
	v_ashrrev_i32_e32 v7, 31, v6
	v_lshlrev_b64 v[6:7], 10, v[6:7]
	v_lshl_add_u64 v[14:15], v[10:11], 0, v[6:7]
	ds_read_b128 v[6:9], v1
	s_waitcnt lgkmcnt(1)
	global_store_dwordx4 v[14:15], v[2:5], off
	v_add_u32_e32 v1, v190, v173
	v_add_u32_e32 v214, s30, v214
	v_add_u32_e32 v2, 24, v12
	v_ashrrev_i32_e32 v3, 31, v2
	v_lshlrev_b64 v[2:3], 10, v[2:3]
	v_lshl_add_u64 v[2:3], v[10:11], 0, v[2:3]
	s_waitcnt lgkmcnt(0)
	global_store_dwordx4 v[2:3], v[6:9], off
	ds_read_b128 v[2:5], v1
	v_add_u32_e32 v1, v192, v191
	v_add_u32_e32 v6, 32, v12
	v_ashrrev_i32_e32 v7, 31, v6
	v_lshlrev_b64 v[6:7], 10, v[6:7]
	v_lshl_add_u64 v[14:15], v[10:11], 0, v[6:7]
	ds_read_b128 v[6:9], v1
	s_waitcnt lgkmcnt(1)
	global_store_dwordx4 v[14:15], v[2:5], off
	v_add_u32_e32 v1, v194, v193
	v_add_u32_e32 v213, s30, v213
	v_add_u32_e32 v2, 40, v12
	v_ashrrev_i32_e32 v3, 31, v2
	v_lshlrev_b64 v[2:3], 10, v[2:3]
	v_lshl_add_u64 v[2:3], v[10:11], 0, v[2:3]
	s_waitcnt lgkmcnt(0)
	global_store_dwordx4 v[2:3], v[6:9], off
	ds_read_b128 v[2:5], v1
	v_add_u32_e32 v1, v196, v195
	v_add_u32_e32 v6, 48, v12
	v_ashrrev_i32_e32 v7, 31, v6
	v_lshlrev_b64 v[6:7], 10, v[6:7]
	v_lshl_add_u64 v[14:15], v[10:11], 0, v[6:7]
	ds_read_b128 v[6:9], v1
	s_waitcnt lgkmcnt(1)
	global_store_dwordx4 v[14:15], v[2:5], off
	v_add_u32_e32 v1, v197, v173
	s_cmpk_lt_i32 s2, 0x80
	v_add_u32_e32 v2, 56, v12
	v_ashrrev_i32_e32 v3, 31, v2
	v_lshlrev_b64 v[2:3], 10, v[2:3]
	v_lshl_add_u64 v[2:3], v[10:11], 0, v[2:3]
	s_waitcnt lgkmcnt(0)
	global_store_dwordx4 v[2:3], v[6:9], off
	ds_read_b128 v[2:5], v1
	v_add_u32_e32 v1, v199, v198
	v_add_u32_e32 v6, 64, v12
	v_ashrrev_i32_e32 v7, 31, v6
	v_lshlrev_b64 v[6:7], 10, v[6:7]
	v_lshl_add_u64 v[14:15], v[10:11], 0, v[6:7]
	ds_read_b128 v[6:9], v1
	s_waitcnt lgkmcnt(1)
	global_store_dwordx4 v[14:15], v[2:5], off
	v_add_u32_e32 v1, v201, v200
	v_add_u32_e32 v212, s46, v212
	v_add_u32_e32 v2, 0x48, v12
	v_ashrrev_i32_e32 v3, 31, v2
	v_lshlrev_b64 v[2:3], 10, v[2:3]
	v_lshl_add_u64 v[2:3], v[10:11], 0, v[2:3]
	s_waitcnt lgkmcnt(0)
	global_store_dwordx4 v[2:3], v[6:9], off
	ds_read_b128 v[2:5], v1
	v_add_u32_e32 v1, v203, v202
	v_add_u32_e32 v6, 0x50, v12
	v_ashrrev_i32_e32 v7, 31, v6
	v_lshlrev_b64 v[6:7], 10, v[6:7]
	v_lshl_add_u64 v[14:15], v[10:11], 0, v[6:7]
	ds_read_b128 v[6:9], v1
	s_waitcnt lgkmcnt(1)
	global_store_dwordx4 v[14:15], v[2:5], off
	v_add_u32_e32 v1, v204, v173
	s_nop 0
	v_add_u32_e32 v2, 0x58, v12
	v_ashrrev_i32_e32 v3, 31, v2
	v_lshlrev_b64 v[2:3], 10, v[2:3]
	v_lshl_add_u64 v[2:3], v[10:11], 0, v[2:3]
	s_waitcnt lgkmcnt(0)
	global_store_dwordx4 v[2:3], v[6:9], off
	ds_read_b128 v[2:5], v1
	v_add_u32_e32 v1, v206, v205
	v_add_u32_e32 v6, 0x60, v12
	v_ashrrev_i32_e32 v7, 31, v6
	v_lshlrev_b64 v[6:7], 10, v[6:7]
	v_lshl_add_u64 v[14:15], v[10:11], 0, v[6:7]
	ds_read_b128 v[6:9], v1
	s_waitcnt lgkmcnt(1)
	global_store_dwordx4 v[14:15], v[2:5], off
	v_add_u32_e32 v1, v208, v207
	s_nop 0
	v_add_u32_e32 v2, 0x68, v12
	v_ashrrev_i32_e32 v3, 31, v2
	v_lshlrev_b64 v[2:3], 10, v[2:3]
	v_lshl_add_u64 v[2:3], v[10:11], 0, v[2:3]
	s_waitcnt lgkmcnt(0)
	global_store_dwordx4 v[2:3], v[6:9], off
	ds_read_b128 v[2:5], v1
	v_add_u32_e32 v1, v210, v209
	v_add_u32_e32 v6, 0x70, v12
	v_ashrrev_i32_e32 v7, 31, v6
	v_lshlrev_b64 v[6:7], 10, v[6:7]
	v_lshl_add_u64 v[14:15], v[10:11], 0, v[6:7]
	ds_read_b128 v[6:9], v1
	s_waitcnt lgkmcnt(1)
	global_store_dwordx4 v[14:15], v[2:5], off
	s_nop 1
	v_add_u32_e32 v2, 0x78, v12
	v_ashrrev_i32_e32 v3, 31, v2
	v_lshlrev_b64 v[2:3], 10, v[2:3]
	v_lshl_add_u64 v[2:3], v[10:11], 0, v[2:3]
	s_waitcnt lgkmcnt(0)
	global_store_dwordx4 v[2:3], v[6:9], off
	s_cbranch_scc0 .LBB0_656

.LBB0_665:
	s_or_b64 exec, exec, s[4:5]
	s_waitcnt vmcnt(0)
	v_cvt_pk_bf16_f32 v134, v102, v98
	v_cvt_pk_bf16_f32 v135, v110, v106
	v_cvt_pk_bf16_f32 v136, v118, v114
	v_cvt_pk_bf16_f32 v137, v126, v122
	v_add_u32_e32 v102, v169, v168
	ds_write_b128 v102, v[134:137]
	v_cvt_pk_bf16_f32 v134, v103, v99
	v_cvt_pk_bf16_f32 v135, v111, v107
	v_cvt_pk_bf16_f32 v136, v119, v115
	v_cvt_pk_bf16_f32 v137, v127, v123
	ds_write_b128 v102, v[134:137] offset:4096
	v_cvt_pk_bf16_f32 v134, v104, v100
	v_cvt_pk_bf16_f32 v98, v105, v101
	v_cvt_pk_bf16_f32 v99, v113, v109
	v_cvt_pk_bf16_f32 v100, v121, v117
	v_cvt_pk_bf16_f32 v101, v129, v125
	ds_write_b128 v102, v[98:101] offset:12288
	v_cvt_pk_bf16_f32 v98, v70, v66
	v_cvt_pk_bf16_f32 v99, v78, v74
	v_cvt_pk_bf16_f32 v100, v86, v82
	v_cvt_pk_bf16_f32 v101, v94, v90
	v_add_u32_e32 v70, v169, v170
	ds_write_b128 v70, v[98:101]
	v_cvt_pk_bf16_f32 v98, v71, v67
	v_cvt_pk_bf16_f32 v99, v79, v75
	v_cvt_pk_bf16_f32 v100, v87, v83
	v_cvt_pk_bf16_f32 v101, v95, v91
	ds_write_b128 v70, v[98:101] offset:4096
	v_cvt_pk_bf16_f32 v98, v72, v68
	v_cvt_pk_bf16_f32 v66, v73, v69
	v_cvt_pk_bf16_f32 v67, v81, v77
	v_cvt_pk_bf16_f32 v68, v89, v85
	v_cvt_pk_bf16_f32 v69, v97, v93
	ds_write_b128 v70, v[66:69] offset:12288
	v_cvt_pk_bf16_f32 v66, v38, v34
	v_cvt_pk_bf16_f32 v67, v46, v42
	v_cvt_pk_bf16_f32 v68, v54, v50
	v_cvt_pk_bf16_f32 v69, v62, v58
	v_add_u32_e32 v38, v169, v171
	ds_write_b128 v38, v[66:69]
	v_cvt_pk_bf16_f32 v66, v39, v35
	v_cvt_pk_bf16_f32 v67, v47, v43
	v_cvt_pk_bf16_f32 v68, v55, v51
	v_cvt_pk_bf16_f32 v69, v63, v59
	ds_write_b128 v38, v[66:69] offset:4096
	v_cvt_pk_bf16_f32 v66, v40, v36
	v_cvt_pk_bf16_f32 v34, v41, v37
	v_cvt_pk_bf16_f32 v35, v49, v45
	v_cvt_pk_bf16_f32 v36, v57, v53
	v_cvt_pk_bf16_f32 v37, v65, v61
	ds_write_b128 v38, v[34:37] offset:12288
	v_cvt_pk_bf16_f32 v34, v6, v2
	v_cvt_pk_bf16_f32 v35, v14, v10
	v_cvt_pk_bf16_f32 v36, v22, v18
	v_cvt_pk_bf16_f32 v37, v30, v26
	v_add_u32_e32 v6, v169, v172
	ds_write_b128 v6, v[34:37]
	v_cvt_pk_bf16_f32 v34, v7, v3
	v_cvt_pk_bf16_f32 v35, v15, v11
	v_cvt_pk_bf16_f32 v36, v23, v19
	v_cvt_pk_bf16_f32 v37, v31, v27
	s_sub_i32 s4, 0, s13
	v_cvt_pk_bf16_f32 v135, v112, v108
	v_cvt_pk_bf16_f32 v136, v120, v116
	v_cvt_pk_bf16_f32 v137, v128, v124
	v_cvt_pk_bf16_f32 v99, v80, v76
	v_cvt_pk_bf16_f32 v100, v88, v84
	v_cvt_pk_bf16_f32 v101, v96, v92
	v_cvt_pk_bf16_f32 v67, v48, v44
	v_cvt_pk_bf16_f32 v68, v56, v52
	v_cvt_pk_bf16_f32 v69, v64, v60
	ds_write_b128 v6, v[34:37] offset:4096
	v_cvt_pk_bf16_f32 v34, v8, v4
	v_cvt_pk_bf16_f32 v35, v16, v12
	v_cvt_pk_bf16_f32 v36, v24, v20
	v_cvt_pk_bf16_f32 v37, v32, v28
	v_cvt_pk_bf16_f32 v2, v9, v5
	v_cvt_pk_bf16_f32 v3, v17, v13
	v_cvt_pk_bf16_f32 v4, v25, v21
	v_cvt_pk_bf16_f32 v5, v33, v29
	ds_write_b128 v102, v[134:137] offset:8192
	ds_write_b128 v70, v[98:101] offset:8192
	ds_write_b128 v38, v[66:69] offset:8192
	ds_write_b128 v6, v[34:37] offset:8192
	ds_write_b128 v6, v[2:5] offset:12288
	v_add_u32_e32 v2, v174, v173
	s_add_i32 s4, s4, s3
	ds_read_b128 v[2:5], v2
	v_add_u32_e32 v12, s4, v132
	s_ashr_i32 s13, s12, 31
	v_ashrrev_i32_e32 v13, 31, v12
	v_lshl_add_u64 v[10:11], s[12:13], 1, v[130:131]
	v_lshlrev_b64 v[6:7], 12, v[12:13]
	v_lshl_add_u64 v[14:15], v[10:11], 0, v[6:7]
	v_add_u32_e32 v6, v176, v175
	ds_read_b128 v[6:9], v6
	s_waitcnt lgkmcnt(0)
	global_store_dwordx4 v[14:15], v[2:5], off
	s_add_i32 s2, s2, s44
	v_add_u32_e32 v132, s14, v132
	v_add_u32_e32 v2, 8, v12
	v_ashrrev_i32_e32 v3, 31, v2
	v_lshlrev_b64 v[2:3], 12, v[2:3]
	v_lshl_add_u64 v[2:3], v[10:11], 0, v[2:3]
	global_store_dwordx4 v[2:3], v[6:9], off
	v_add_u32_e32 v2, v178, v177
	ds_read_b128 v[2:5], v2
	v_add_u32_e32 v6, 16, v12
	v_ashrrev_i32_e32 v7, 31, v6
	v_lshlrev_b64 v[6:7], 12, v[6:7]
	v_lshl_add_u64 v[14:15], v[10:11], 0, v[6:7]
	v_add_u32_e32 v6, v185, v179
	ds_read_b128 v[6:9], v6
	s_waitcnt lgkmcnt(1)
	global_store_dwordx4 v[14:15], v[2:5], off
	s_cmpk_lt_i32 s2, 0x200
	v_add_u32_e32 v1, s14, v1
	v_add_u32_e32 v2, 24, v12
	v_ashrrev_i32_e32 v3, 31, v2
	v_lshlrev_b64 v[2:3], 12, v[2:3]
	v_lshl_add_u64 v[2:3], v[10:11], 0, v[2:3]
	s_waitcnt lgkmcnt(0)
	global_store_dwordx4 v[2:3], v[6:9], off
	v_add_u32_e32 v2, v190, v173
	ds_read_b128 v[2:5], v2
	v_add_u32_e32 v6, 32, v12
	v_ashrrev_i32_e32 v7, 31, v6
	v_lshlrev_b64 v[6:7], 12, v[6:7]
	v_lshl_add_u64 v[14:15], v[10:11], 0, v[6:7]
	v_add_u32_e32 v6, v192, v191
	ds_read_b128 v[6:9], v6
	s_waitcnt lgkmcnt(1)
	global_store_dwordx4 v[14:15], v[2:5], off
	s_nop 1
	v_add_u32_e32 v2, 40, v12
	v_ashrrev_i32_e32 v3, 31, v2
	v_lshlrev_b64 v[2:3], 12, v[2:3]
	v_lshl_add_u64 v[2:3], v[10:11], 0, v[2:3]
	s_waitcnt lgkmcnt(0)
	global_store_dwordx4 v[2:3], v[6:9], off
	v_add_u32_e32 v2, v194, v193
	ds_read_b128 v[2:5], v2
	v_add_u32_e32 v6, 48, v12
	v_ashrrev_i32_e32 v7, 31, v6
	v_lshlrev_b64 v[6:7], 12, v[6:7]
	v_lshl_add_u64 v[14:15], v[10:11], 0, v[6:7]
	v_add_u32_e32 v6, v196, v195
	ds_read_b128 v[6:9], v6
	s_waitcnt lgkmcnt(1)
	global_store_dwordx4 v[14:15], v[2:5], off
	s_nop 1
	v_add_u32_e32 v2, 56, v12
	v_ashrrev_i32_e32 v3, 31, v2
	v_lshlrev_b64 v[2:3], 12, v[2:3]
	v_lshl_add_u64 v[2:3], v[10:11], 0, v[2:3]
	s_waitcnt lgkmcnt(0)
	global_store_dwordx4 v[2:3], v[6:9], off
	v_add_u32_e32 v2, v197, v173
	ds_read_b128 v[2:5], v2
	v_add_u32_e32 v6, 64, v12
	v_ashrrev_i32_e32 v7, 31, v6
	v_lshlrev_b64 v[6:7], 12, v[6:7]
	v_lshl_add_u64 v[14:15], v[10:11], 0, v[6:7]
	v_add_u32_e32 v6, v199, v198
	ds_read_b128 v[6:9], v6
	s_waitcnt lgkmcnt(1)
	global_store_dwordx4 v[14:15], v[2:5], off
	s_nop 1
	v_add_u32_e32 v2, 0x48, v12
	v_ashrrev_i32_e32 v3, 31, v2
	v_lshlrev_b64 v[2:3], 12, v[2:3]
	v_lshl_add_u64 v[2:3], v[10:11], 0, v[2:3]
	s_waitcnt lgkmcnt(0)
	global_store_dwordx4 v[2:3], v[6:9], off
	v_add_u32_e32 v2, v201, v200
	ds_read_b128 v[2:5], v2
	v_add_u32_e32 v6, 0x50, v12
	v_ashrrev_i32_e32 v7, 31, v6
	v_lshlrev_b64 v[6:7], 12, v[6:7]
	v_lshl_add_u64 v[14:15], v[10:11], 0, v[6:7]
	v_add_u32_e32 v6, v203, v202
	ds_read_b128 v[6:9], v6
	s_waitcnt lgkmcnt(1)
	global_store_dwordx4 v[14:15], v[2:5], off
	s_nop 1
	v_add_u32_e32 v2, 0x58, v12
	v_ashrrev_i32_e32 v3, 31, v2
	v_lshlrev_b64 v[2:3], 12, v[2:3]
	v_lshl_add_u64 v[2:3], v[10:11], 0, v[2:3]
	s_waitcnt lgkmcnt(0)
	global_store_dwordx4 v[2:3], v[6:9], off
	v_add_u32_e32 v2, v204, v173
	ds_read_b128 v[2:5], v2
	v_add_u32_e32 v6, 0x60, v12
	v_ashrrev_i32_e32 v7, 31, v6
	v_lshlrev_b64 v[6:7], 12, v[6:7]
	v_lshl_add_u64 v[14:15], v[10:11], 0, v[6:7]
	v_add_u32_e32 v6, v206, v205
	ds_read_b128 v[6:9], v6
	s_waitcnt lgkmcnt(1)
	global_store_dwordx4 v[14:15], v[2:5], off
	s_nop 1
	v_add_u32_e32 v2, 0x68, v12
	v_ashrrev_i32_e32 v3, 31, v2
	v_lshlrev_b64 v[2:3], 12, v[2:3]
	v_lshl_add_u64 v[2:3], v[10:11], 0, v[2:3]
	s_waitcnt lgkmcnt(0)
	global_store_dwordx4 v[2:3], v[6:9], off
	v_add_u32_e32 v2, v208, v207
	ds_read_b128 v[2:5], v2
	v_add_u32_e32 v6, 0x70, v12
	v_ashrrev_i32_e32 v7, 31, v6
	v_lshlrev_b64 v[6:7], 12, v[6:7]
	v_lshl_add_u64 v[14:15], v[10:11], 0, v[6:7]
	v_add_u32_e32 v6, v210, v209
	ds_read_b128 v[6:9], v6
	s_waitcnt lgkmcnt(1)
	global_store_dwordx4 v[14:15], v[2:5], off
	s_nop 1
	v_add_u32_e32 v2, 0x78, v12
	v_ashrrev_i32_e32 v3, 31, v2
	v_lshlrev_b64 v[2:3], 12, v[2:3]
	v_lshl_add_u64 v[2:3], v[10:11], 0, v[2:3]
	s_waitcnt lgkmcnt(0)
	global_store_dwordx4 v[2:3], v[6:9], off
	s_cbranch_scc0 .LBB0_633

.LBB0_672:
	s_or_b64 exec, exec, s[4:5]
	s_waitcnt vmcnt(0)
	v_cvt_pk_bf16_f32 v134, v102, v98
	v_cvt_pk_bf16_f32 v135, v110, v106
	v_cvt_pk_bf16_f32 v136, v118, v114
	v_cvt_pk_bf16_f32 v137, v126, v122
	v_add_u32_e32 v102, v169, v168
	ds_write_b128 v102, v[134:137]
	v_cvt_pk_bf16_f32 v134, v103, v99
	v_cvt_pk_bf16_f32 v135, v111, v107
	v_cvt_pk_bf16_f32 v136, v119, v115
	v_cvt_pk_bf16_f32 v137, v127, v123
	ds_write_b128 v102, v[134:137] offset:4096
	v_cvt_pk_bf16_f32 v134, v104, v100
	v_cvt_pk_bf16_f32 v98, v105, v101
	v_cvt_pk_bf16_f32 v99, v113, v109
	v_cvt_pk_bf16_f32 v100, v121, v117
	v_cvt_pk_bf16_f32 v101, v129, v125
	ds_write_b128 v102, v[98:101] offset:12288
	v_cvt_pk_bf16_f32 v98, v70, v66
	v_cvt_pk_bf16_f32 v99, v78, v74
	v_cvt_pk_bf16_f32 v100, v86, v82
	v_cvt_pk_bf16_f32 v101, v94, v90
	v_add_u32_e32 v70, v169, v170
	ds_write_b128 v70, v[98:101]
	v_cvt_pk_bf16_f32 v98, v71, v67
	v_cvt_pk_bf16_f32 v99, v79, v75
	v_cvt_pk_bf16_f32 v100, v87, v83
	v_cvt_pk_bf16_f32 v101, v95, v91
	ds_write_b128 v70, v[98:101] offset:4096
	v_cvt_pk_bf16_f32 v98, v72, v68
	v_cvt_pk_bf16_f32 v66, v73, v69
	v_cvt_pk_bf16_f32 v67, v81, v77
	v_cvt_pk_bf16_f32 v68, v89, v85
	v_cvt_pk_bf16_f32 v69, v97, v93
	ds_write_b128 v70, v[66:69] offset:12288
	v_cvt_pk_bf16_f32 v66, v38, v34
	v_cvt_pk_bf16_f32 v67, v46, v42
	v_cvt_pk_bf16_f32 v68, v54, v50
	v_cvt_pk_bf16_f32 v69, v62, v58
	v_add_u32_e32 v38, v169, v171
	ds_write_b128 v38, v[66:69]
	v_cvt_pk_bf16_f32 v66, v39, v35
	v_cvt_pk_bf16_f32 v67, v47, v43
	v_cvt_pk_bf16_f32 v68, v55, v51
	v_cvt_pk_bf16_f32 v69, v63, v59
	ds_write_b128 v38, v[66:69] offset:4096
	v_cvt_pk_bf16_f32 v66, v40, v36
	v_cvt_pk_bf16_f32 v34, v41, v37
	v_cvt_pk_bf16_f32 v35, v49, v45
	v_cvt_pk_bf16_f32 v36, v57, v53
	v_cvt_pk_bf16_f32 v37, v65, v61
	ds_write_b128 v38, v[34:37] offset:12288
	v_cvt_pk_bf16_f32 v34, v6, v2
	v_cvt_pk_bf16_f32 v35, v14, v10
	v_cvt_pk_bf16_f32 v36, v22, v18
	v_cvt_pk_bf16_f32 v37, v30, v26
	v_add_u32_e32 v6, v169, v172
	ds_write_b128 v6, v[34:37]
	v_cvt_pk_bf16_f32 v34, v7, v3
	v_cvt_pk_bf16_f32 v35, v15, v11
	v_cvt_pk_bf16_f32 v36, v23, v19
	v_cvt_pk_bf16_f32 v37, v31, v27
	s_sub_i32 s4, 0, s1
	v_cvt_pk_bf16_f32 v135, v112, v108
	v_cvt_pk_bf16_f32 v136, v120, v116
	v_cvt_pk_bf16_f32 v137, v128, v124
	v_cvt_pk_bf16_f32 v99, v80, v76
	v_cvt_pk_bf16_f32 v100, v88, v84
	v_cvt_pk_bf16_f32 v101, v96, v92
	v_cvt_pk_bf16_f32 v67, v48, v44
	v_cvt_pk_bf16_f32 v68, v56, v52
	v_cvt_pk_bf16_f32 v69, v64, v60
	ds_write_b128 v6, v[34:37] offset:4096
	v_cvt_pk_bf16_f32 v34, v8, v4
	v_cvt_pk_bf16_f32 v35, v16, v12
	v_cvt_pk_bf16_f32 v36, v24, v20
	v_cvt_pk_bf16_f32 v37, v32, v28
	v_cvt_pk_bf16_f32 v2, v9, v5
	v_cvt_pk_bf16_f32 v3, v17, v13
	v_cvt_pk_bf16_f32 v4, v25, v21
	v_cvt_pk_bf16_f32 v5, v33, v29
	ds_write_b128 v102, v[134:137] offset:8192
	ds_write_b128 v70, v[98:101] offset:8192
	ds_write_b128 v38, v[66:69] offset:8192
	ds_write_b128 v6, v[34:37] offset:8192
	ds_write_b128 v6, v[2:5] offset:12288
	v_add_u32_e32 v2, v174, v173
	s_add_i32 s4, s4, s2
	ds_read_b128 v[2:5], v2
	v_add_u32_e32 v12, s4, v132
	s_ashr_i32 s1, s0, 31
	v_ashrrev_i32_e32 v13, 31, v12
	v_lshl_add_u64 v[10:11], s[0:1], 1, v[130:131]
	v_lshlrev_b64 v[6:7], 14, v[12:13]
	v_lshl_add_u64 v[14:15], v[10:11], 0, v[6:7]
	v_add_u32_e32 v6, v176, v175
	ds_read_b128 v[6:9], v6
	s_waitcnt lgkmcnt(0)
	global_store_dwordx4 v[14:15], v[2:5], off
	s_add_i32 s3, s3, s44
	v_add_u32_e32 v132, s12, v132
	v_add_u32_e32 v2, 8, v12
	v_ashrrev_i32_e32 v3, 31, v2
	v_lshlrev_b64 v[2:3], 14, v[2:3]
	v_lshl_add_u64 v[2:3], v[10:11], 0, v[2:3]
	global_store_dwordx4 v[2:3], v[6:9], off
	v_add_u32_e32 v2, v178, v177
	ds_read_b128 v[2:5], v2
	v_add_u32_e32 v6, 16, v12
	v_ashrrev_i32_e32 v7, 31, v6
	v_lshlrev_b64 v[6:7], 14, v[6:7]
	v_lshl_add_u64 v[14:15], v[10:11], 0, v[6:7]
	v_add_u32_e32 v6, v185, v179
	ds_read_b128 v[6:9], v6
	s_waitcnt lgkmcnt(1)
	global_store_dwordx4 v[14:15], v[2:5], off
	s_cmpk_lt_i32 s3, 0x800
	v_add_u32_e32 v1, s12, v1
	v_add_u32_e32 v2, 24, v12
	v_ashrrev_i32_e32 v3, 31, v2
	v_lshlrev_b64 v[2:3], 14, v[2:3]
	v_lshl_add_u64 v[2:3], v[10:11], 0, v[2:3]
	s_waitcnt lgkmcnt(0)
	global_store_dwordx4 v[2:3], v[6:9], off
	v_add_u32_e32 v2, v190, v173
	ds_read_b128 v[2:5], v2
	v_add_u32_e32 v6, 32, v12
	v_ashrrev_i32_e32 v7, 31, v6
	v_lshlrev_b64 v[6:7], 14, v[6:7]
	v_lshl_add_u64 v[14:15], v[10:11], 0, v[6:7]
	v_add_u32_e32 v6, v192, v191
	ds_read_b128 v[6:9], v6
	s_waitcnt lgkmcnt(1)
	global_store_dwordx4 v[14:15], v[2:5], off
	s_nop 1
	v_add_u32_e32 v2, 40, v12
	v_ashrrev_i32_e32 v3, 31, v2
	v_lshlrev_b64 v[2:3], 14, v[2:3]
	v_lshl_add_u64 v[2:3], v[10:11], 0, v[2:3]
	s_waitcnt lgkmcnt(0)
	global_store_dwordx4 v[2:3], v[6:9], off
	v_add_u32_e32 v2, v194, v193
	ds_read_b128 v[2:5], v2
	v_add_u32_e32 v6, 48, v12
	v_ashrrev_i32_e32 v7, 31, v6
	v_lshlrev_b64 v[6:7], 14, v[6:7]
	v_lshl_add_u64 v[14:15], v[10:11], 0, v[6:7]
	v_add_u32_e32 v6, v196, v195
	ds_read_b128 v[6:9], v6
	s_waitcnt lgkmcnt(1)
	global_store_dwordx4 v[14:15], v[2:5], off
	s_nop 1
	v_add_u32_e32 v2, 56, v12
	v_ashrrev_i32_e32 v3, 31, v2
	v_lshlrev_b64 v[2:3], 14, v[2:3]
	v_lshl_add_u64 v[2:3], v[10:11], 0, v[2:3]
	s_waitcnt lgkmcnt(0)
	global_store_dwordx4 v[2:3], v[6:9], off
	v_add_u32_e32 v2, v197, v173
	ds_read_b128 v[2:5], v2
	v_add_u32_e32 v6, 64, v12
	v_ashrrev_i32_e32 v7, 31, v6
	v_lshlrev_b64 v[6:7], 14, v[6:7]
	v_lshl_add_u64 v[14:15], v[10:11], 0, v[6:7]
	v_add_u32_e32 v6, v199, v198
	ds_read_b128 v[6:9], v6
	s_waitcnt lgkmcnt(1)
	global_store_dwordx4 v[14:15], v[2:5], off
	s_nop 1
	v_add_u32_e32 v2, 0x48, v12
	v_ashrrev_i32_e32 v3, 31, v2
	v_lshlrev_b64 v[2:3], 14, v[2:3]
	v_lshl_add_u64 v[2:3], v[10:11], 0, v[2:3]
	s_waitcnt lgkmcnt(0)
	global_store_dwordx4 v[2:3], v[6:9], off
	v_add_u32_e32 v2, v201, v200
	ds_read_b128 v[2:5], v2
	v_add_u32_e32 v6, 0x50, v12
	v_ashrrev_i32_e32 v7, 31, v6
	v_lshlrev_b64 v[6:7], 14, v[6:7]
	v_lshl_add_u64 v[14:15], v[10:11], 0, v[6:7]
	v_add_u32_e32 v6, v203, v202
	ds_read_b128 v[6:9], v6
	s_waitcnt lgkmcnt(1)
	global_store_dwordx4 v[14:15], v[2:5], off
	s_nop 1
	v_add_u32_e32 v2, 0x58, v12
	v_ashrrev_i32_e32 v3, 31, v2
	v_lshlrev_b64 v[2:3], 14, v[2:3]
	v_lshl_add_u64 v[2:3], v[10:11], 0, v[2:3]
	s_waitcnt lgkmcnt(0)
	global_store_dwordx4 v[2:3], v[6:9], off
	v_add_u32_e32 v2, v204, v173
	ds_read_b128 v[2:5], v2
	v_add_u32_e32 v6, 0x60, v12
	v_ashrrev_i32_e32 v7, 31, v6
	v_lshlrev_b64 v[6:7], 14, v[6:7]
	v_lshl_add_u64 v[14:15], v[10:11], 0, v[6:7]
	v_add_u32_e32 v6, v206, v205
	ds_read_b128 v[6:9], v6
	s_waitcnt lgkmcnt(1)
	global_store_dwordx4 v[14:15], v[2:5], off
	s_nop 1
	v_add_u32_e32 v2, 0x68, v12
	v_ashrrev_i32_e32 v3, 31, v2
	v_lshlrev_b64 v[2:3], 14, v[2:3]
	v_lshl_add_u64 v[2:3], v[10:11], 0, v[2:3]
	s_waitcnt lgkmcnt(0)
	global_store_dwordx4 v[2:3], v[6:9], off
	v_add_u32_e32 v2, v208, v207
	ds_read_b128 v[2:5], v2
	v_add_u32_e32 v6, 0x70, v12
	v_ashrrev_i32_e32 v7, 31, v6
	v_lshlrev_b64 v[6:7], 14, v[6:7]
	v_lshl_add_u64 v[14:15], v[10:11], 0, v[6:7]
	v_add_u32_e32 v6, v210, v209
	ds_read_b128 v[6:9], v6
	s_waitcnt lgkmcnt(1)
	global_store_dwordx4 v[14:15], v[2:5], off
	s_nop 1
	v_add_u32_e32 v2, 0x78, v12
	v_ashrrev_i32_e32 v3, 31, v2
	v_lshlrev_b64 v[2:3], 14, v[2:3]
	v_lshl_add_u64 v[2:3], v[10:11], 0, v[2:3]
	s_waitcnt lgkmcnt(0)
	global_store_dwordx4 v[2:3], v[6:9], off
	s_cbranch_scc0 .LBB0_669

.LBB0_677:
	s_or_b64 exec, exec, s[4:5]
	s_waitcnt vmcnt(0)
	v_cvt_pk_bf16_f32 v132, v8, v20
	v_cvt_pk_bf16_f32 v133, v32, v44
	v_cvt_pk_bf16_f32 v134, v64, v72
	v_cvt_pk_bf16_f32 v135, v88, v100
	v_add_u32_e32 v1, v169, v168
	ds_write_b128 v1, v[132:135]
	v_cvt_pk_bf16_f32 v132, v9, v21
	v_cvt_pk_bf16_f32 v133, v33, v45
	v_cvt_pk_bf16_f32 v134, v65, v73
	v_cvt_pk_bf16_f32 v135, v89, v101
	ds_write_b128 v1, v[132:135] offset:4096
	v_cvt_pk_bf16_f32 v132, v10, v22
	v_cvt_pk_bf16_f32 v133, v34, v46
	v_cvt_pk_bf16_f32 v134, v66, v74
	v_cvt_pk_bf16_f32 v135, v90, v102
	v_cvt_pk_bf16_f32 v8, v11, v23
	v_cvt_pk_bf16_f32 v9, v35, v47
	v_cvt_pk_bf16_f32 v10, v67, v75
	v_cvt_pk_bf16_f32 v11, v91, v103
	ds_write_b128 v1, v[132:135] offset:8192
	ds_write_b128 v1, v[8:11] offset:12288
	v_cvt_pk_bf16_f32 v8, v4, v16
	v_add_u32_e32 v1, v169, v170
	v_cvt_pk_bf16_f32 v2, v5, v17
	v_cvt_pk_bf16_f32 v3, v29, v41
	v_cvt_pk_bf16_f32 v4, v61, v69
	v_cvt_pk_bf16_f32 v5, v97, v105
	ds_write_b128 v1, v[2:5] offset:4096
	v_cvt_pk_bf16_f32 v2, v6, v18
	v_cvt_pk_bf16_f32 v3, v30, v42
	v_cvt_pk_bf16_f32 v4, v62, v70
	v_cvt_pk_bf16_f32 v5, v98, v106
	v_cvt_pk_bf16_f32 v9, v28, v40
	v_cvt_pk_bf16_f32 v10, v60, v68
	v_cvt_pk_bf16_f32 v11, v96, v104
	ds_write_b128 v1, v[2:5] offset:8192
	v_cvt_pk_bf16_f32 v2, v7, v19
	v_cvt_pk_bf16_f32 v3, v31, v43
	v_cvt_pk_bf16_f32 v4, v63, v71
	v_cvt_pk_bf16_f32 v5, v99, v107
	ds_write_b128 v1, v[8:11]
	ds_write_b128 v1, v[2:5] offset:12288
	v_cvt_pk_bf16_f32 v2, v12, v24
	v_cvt_pk_bf16_f32 v3, v52, v56
	v_cvt_pk_bf16_f32 v4, v76, v84
	v_cvt_pk_bf16_f32 v5, v108, v112
	v_add_u32_e32 v1, v169, v171
	ds_write_b128 v1, v[2:5]
	v_cvt_pk_bf16_f32 v2, v13, v25
	v_cvt_pk_bf16_f32 v3, v53, v57
	v_cvt_pk_bf16_f32 v4, v77, v85
	v_cvt_pk_bf16_f32 v5, v109, v113
	ds_write_b128 v1, v[2:5] offset:4096
	v_cvt_pk_bf16_f32 v2, v14, v26
	v_cvt_pk_bf16_f32 v3, v54, v58
	v_cvt_pk_bf16_f32 v4, v78, v86
	v_cvt_pk_bf16_f32 v5, v110, v114
	ds_write_b128 v1, v[2:5] offset:8192
	v_cvt_pk_bf16_f32 v2, v15, v27
	v_cvt_pk_bf16_f32 v3, v55, v59
	v_cvt_pk_bf16_f32 v4, v79, v87
	v_cvt_pk_bf16_f32 v5, v111, v115
	ds_write_b128 v1, v[2:5] offset:12288
	v_cvt_pk_bf16_f32 v2, v36, v48
	v_cvt_pk_bf16_f32 v3, v80, v92
	v_cvt_pk_bf16_f32 v4, v116, v120
	v_cvt_pk_bf16_f32 v5, v124, v128
	v_add_u32_e32 v1, v169, v172
	ds_write_b128 v1, v[2:5]
	v_cvt_pk_bf16_f32 v2, v37, v49
	v_cvt_pk_bf16_f32 v3, v81, v93
	v_cvt_pk_bf16_f32 v4, v117, v121
	v_cvt_pk_bf16_f32 v5, v125, v129
	ds_write_b128 v1, v[2:5] offset:4096
	v_cvt_pk_bf16_f32 v2, v38, v50
	v_cvt_pk_bf16_f32 v3, v82, v94
	v_cvt_pk_bf16_f32 v4, v118, v122
	v_cvt_pk_bf16_f32 v5, v126, v130
	ds_write_b128 v1, v[2:5] offset:8192
	v_cvt_pk_bf16_f32 v2, v39, v51
	v_cvt_pk_bf16_f32 v3, v83, v95
	v_cvt_pk_bf16_f32 v4, v119, v123
	v_cvt_pk_bf16_f32 v5, v127, v131
	s_sub_i32 s4, 0, s46
	ds_write_b128 v1, v[2:5] offset:12288
	v_add_u32_e32 v1, v174, v173
	ds_read_b128 v[2:5], v1
	s_add_i32 s4, s4, s30
	v_add_u32_e32 v12, s4, v212
	s_ashr_i32 s13, s12, 31
	v_ashrrev_i32_e32 v13, 31, v12
	v_lshl_add_u64 v[10:11], s[12:13], 1, v[164:165]
	v_lshlrev_b64 v[6:7], 12, v[12:13]
	v_add_u32_e32 v1, v176, v175
	v_lshl_add_u64 v[14:15], v[10:11], 0, v[6:7]
	ds_read_b128 v[6:9], v1
	s_waitcnt lgkmcnt(0)
	global_store_dwordx4 v[14:15], v[2:5], off
	v_add_u32_e32 v1, v178, v177
	s_add_i32 s3, s3, s44
	v_add_u32_e32 v2, 8, v12
	v_ashrrev_i32_e32 v3, 31, v2
	v_lshlrev_b64 v[2:3], 12, v[2:3]
	v_lshl_add_u64 v[2:3], v[10:11], 0, v[2:3]
	global_store_dwordx4 v[2:3], v[6:9], off
	ds_read_b128 v[2:5], v1
	v_add_u32_e32 v1, v185, v179
	v_add_u32_e32 v6, 16, v12
	v_ashrrev_i32_e32 v7, 31, v6
	v_lshlrev_b64 v[6:7], 12, v[6:7]
	v_lshl_add_u64 v[14:15], v[10:11], 0, v[6:7]
	ds_read_b128 v[6:9], v1
	s_waitcnt lgkmcnt(1)
	global_store_dwordx4 v[14:15], v[2:5], off
	v_add_u32_e32 v1, v190, v173
	v_add_u32_e32 v212, s45, v212
	v_add_u32_e32 v2, 24, v12
	v_ashrrev_i32_e32 v3, 31, v2
	v_lshlrev_b64 v[2:3], 12, v[2:3]
	v_lshl_add_u64 v[2:3], v[10:11], 0, v[2:3]
	s_waitcnt lgkmcnt(0)
	global_store_dwordx4 v[2:3], v[6:9], off
	ds_read_b128 v[2:5], v1
	v_add_u32_e32 v1, v192, v191
	v_add_u32_e32 v6, 32, v12
	v_ashrrev_i32_e32 v7, 31, v6
	v_lshlrev_b64 v[6:7], 12, v[6:7]
	v_lshl_add_u64 v[14:15], v[10:11], 0, v[6:7]
	ds_read_b128 v[6:9], v1
	s_waitcnt lgkmcnt(1)
	global_store_dwordx4 v[14:15], v[2:5], off
	v_add_u32_e32 v1, v194, v193
	s_cmpk_lt_i32 s3, 0x800
	v_add_u32_e32 v2, 40, v12
	v_ashrrev_i32_e32 v3, 31, v2
	v_lshlrev_b64 v[2:3], 12, v[2:3]
	v_lshl_add_u64 v[2:3], v[10:11], 0, v[2:3]
	s_waitcnt lgkmcnt(0)
	global_store_dwordx4 v[2:3], v[6:9], off
	ds_read_b128 v[2:5], v1
	v_add_u32_e32 v1, v196, v195
	v_add_u32_e32 v6, 48, v12
	v_ashrrev_i32_e32 v7, 31, v6
	v_lshlrev_b64 v[6:7], 12, v[6:7]
	v_lshl_add_u64 v[14:15], v[10:11], 0, v[6:7]
	ds_read_b128 v[6:9], v1
	s_waitcnt lgkmcnt(1)
	global_store_dwordx4 v[14:15], v[2:5], off
	v_add_u32_e32 v1, v197, v173
	v_add_u32_e32 v211, s45, v211
	v_add_u32_e32 v2, 56, v12
	v_ashrrev_i32_e32 v3, 31, v2
	v_lshlrev_b64 v[2:3], 12, v[2:3]
	v_lshl_add_u64 v[2:3], v[10:11], 0, v[2:3]
	s_waitcnt lgkmcnt(0)
	global_store_dwordx4 v[2:3], v[6:9], off
	ds_read_b128 v[2:5], v1
	v_add_u32_e32 v1, v199, v198
	v_add_u32_e32 v6, 64, v12
	v_ashrrev_i32_e32 v7, 31, v6
	v_lshlrev_b64 v[6:7], 12, v[6:7]
	v_lshl_add_u64 v[14:15], v[10:11], 0, v[6:7]
	ds_read_b128 v[6:9], v1
	s_waitcnt lgkmcnt(1)
	global_store_dwordx4 v[14:15], v[2:5], off
	v_add_u32_e32 v1, v201, v200
	s_nop 0
	v_add_u32_e32 v2, 0x48, v12
	v_ashrrev_i32_e32 v3, 31, v2
	v_lshlrev_b64 v[2:3], 12, v[2:3]
	v_lshl_add_u64 v[2:3], v[10:11], 0, v[2:3]
	s_waitcnt lgkmcnt(0)
	global_store_dwordx4 v[2:3], v[6:9], off
	ds_read_b128 v[2:5], v1
	v_add_u32_e32 v1, v203, v202
	v_add_u32_e32 v6, 0x50, v12
	v_ashrrev_i32_e32 v7, 31, v6
	v_lshlrev_b64 v[6:7], 12, v[6:7]
	v_lshl_add_u64 v[14:15], v[10:11], 0, v[6:7]
	ds_read_b128 v[6:9], v1
	s_waitcnt lgkmcnt(1)
	global_store_dwordx4 v[14:15], v[2:5], off
	v_add_u32_e32 v1, v204, v173
	s_nop 0
	v_add_u32_e32 v2, 0x58, v12
	v_ashrrev_i32_e32 v3, 31, v2
	v_lshlrev_b64 v[2:3], 12, v[2:3]
	v_lshl_add_u64 v[2:3], v[10:11], 0, v[2:3]
	s_waitcnt lgkmcnt(0)
	global_store_dwordx4 v[2:3], v[6:9], off
	ds_read_b128 v[2:5], v1
	v_add_u32_e32 v1, v206, v205
	v_add_u32_e32 v6, 0x60, v12
	v_ashrrev_i32_e32 v7, 31, v6
	v_lshlrev_b64 v[6:7], 12, v[6:7]
	v_lshl_add_u64 v[14:15], v[10:11], 0, v[6:7]
	ds_read_b128 v[6:9], v1
	s_waitcnt lgkmcnt(1)
	global_store_dwordx4 v[14:15], v[2:5], off
	v_add_u32_e32 v1, v208, v207
	s_nop 0
	v_add_u32_e32 v2, 0x68, v12
	v_ashrrev_i32_e32 v3, 31, v2
	v_lshlrev_b64 v[2:3], 12, v[2:3]
	v_lshl_add_u64 v[2:3], v[10:11], 0, v[2:3]
	s_waitcnt lgkmcnt(0)
	global_store_dwordx4 v[2:3], v[6:9], off
	ds_read_b128 v[2:5], v1
	v_add_u32_e32 v1, v210, v209
	v_add_u32_e32 v6, 0x70, v12
	v_ashrrev_i32_e32 v7, 31, v6
	v_lshlrev_b64 v[6:7], 12, v[6:7]
	v_lshl_add_u64 v[14:15], v[10:11], 0, v[6:7]
	ds_read_b128 v[6:9], v1
	s_waitcnt lgkmcnt(1)
	global_store_dwordx4 v[14:15], v[2:5], off
	s_nop 1
	v_add_u32_e32 v2, 0x78, v12
	v_ashrrev_i32_e32 v3, 31, v2
	v_lshlrev_b64 v[2:3], 12, v[2:3]
	v_lshl_add_u64 v[2:3], v[10:11], 0, v[2:3]
	s_waitcnt lgkmcnt(0)
	global_store_dwordx4 v[2:3], v[6:9], off
	s_cbranch_scc0 .LBB0_682
